# v63 + priority stays raised across both MFMA groups of a k-step in every GEMM k-loop (12 redundant setprio 0/1 pairs removed)
# speedup vs baseline: 1.0048x; 1.0011x over previous
.LBB0_86:
	s_add_i32 s35, s11, 1
	s_bitcmp1_b32 s35, 0
	s_cselect_b32 s37, 0x9000, 0
	v_add_u32_e32 v110, s37, v81
	v_lshl_add_u64 v[106:107], v[94:95], 0, s[12:13]
	s_mov_b64 s[38:39], 0x6181080
	v_readfirstlane_b32 s37, v110
	v_add_u32_e32 v111, 0x1000, v110
	v_lshl_add_u64 v[108:109], v[106:107], 0, s[38:39]
	s_mov_b32 m0, s37
	s_mov_b64 s[38:39], 0x61e5080
	v_readfirstlane_b32 s37, v111
	v_add_u32_e32 v111, 0x2000, v110
	global_load_lds_dwordx4 v[108:109], off
	v_lshl_add_u64 v[108:109], v[106:107], 0, s[38:39]
	s_mov_b32 m0, s37
	s_mov_b64 s[38:39], 0x6249080
	v_readfirstlane_b32 s37, v111
	v_add_u32_e32 v111, 0x3000, v110
	global_load_lds_dwordx4 v[108:109], off
	v_lshl_add_u64 v[108:109], v[106:107], 0, s[38:39]
	s_mov_b32 m0, s37
	s_mov_b64 s[38:39], 0x62ad080
	v_readfirstlane_b32 s37, v111
	global_load_lds_dwordx4 v[108:109], off
	v_lshl_add_u64 v[108:109], v[106:107], 0, s[38:39]
	s_mov_b32 m0, s37
	s_mov_b64 s[38:39], 0x6311080
	global_load_lds_dwordx4 v[108:109], off
	v_add_u32_e32 v108, 0x4000, v110
	v_lshl_add_u64 v[106:107], v[106:107], 0, s[38:39]
	v_readfirstlane_b32 s37, v108
	s_mov_b32 m0, s37
	v_add_u32_e32 v111, 0x5000, v110
	global_load_lds_dwordx4 v[106:107], off
	v_lshl_add_u64 v[106:107], v[100:101], 0, s[12:13]
	s_mov_b64 s[38:39], 0x14531080
	v_readfirstlane_b32 s37, v111
	v_add_u32_e32 v111, 0x6000, v110
	v_lshl_add_u64 v[108:109], v[106:107], 0, s[38:39]
	s_mov_b32 m0, s37
	s_mov_b64 s[38:39], 0x14541080
	v_readfirstlane_b32 s37, v111
	v_add_u32_e32 v111, 0x7000, v110
	global_load_lds_dwordx4 v[108:109], off
	v_lshl_add_u64 v[108:109], v[106:107], 0, s[38:39]
	s_mov_b32 m0, s37
	s_mov_b64 s[38:39], 0x14551080
	v_readfirstlane_b32 s37, v111
	global_load_lds_dwordx4 v[108:109], off
	v_lshl_add_u64 v[108:109], v[106:107], 0, s[38:39]
	s_mov_b32 m0, s37
	s_mov_b64 s[38:39], 0x14561080
	global_load_lds_dwordx4 v[108:109], off
	v_add_u32_e32 v108, 0x8000, v110
	v_lshl_add_u64 v[106:107], v[106:107], 0, s[38:39]
	v_readfirstlane_b32 s37, v108
	s_mov_b32 m0, s37
	s_bitcmp1_b32 s11, 0
	global_load_lds_dwordx4 v[106:107], off
	s_cselect_b32 s11, 0x9000, 0
	s_add_i32 s11, s11, 0
	v_add_u32_e32 v114, s11, v116
	v_add_u32_e32 v115, v114, v117
	ds_read_b128 v[106:109], v115
	ds_read_b128 v[110:113], v115 offset:2048
	ds_read_b128 v[122:125], v115 offset:4096
	ds_read_b128 v[156:159], v115 offset:6144
	v_add_u32_e32 v114, v114, v118
	ds_read_b128 v[166:169], v115 offset:8192
	ds_read_b128 v[178:181], v114 offset:20480
	ds_read_b128 v[182:185], v114 offset:22528
	ds_read_b128 v[186:189], v114 offset:24576
	ds_read_b128 v[190:193], v114 offset:26624
	v_add_u32_e32 v210, s11, v119
	v_add_u32_e32 v211, v210, v117
	ds_read_b128 v[212:215], v211
	ds_read_b128 v[216:219], v211 offset:2048
	ds_read_b128 v[220:223], v211 offset:4096
	ds_read_b128 v[224:227], v211 offset:6144
	v_add_u32_e32 v228, v210, v118
	ds_read_b128 v[230:233], v211 offset:8192
	ds_read_b128 v[234:237], v228 offset:20480
	ds_read_b128 v[238:241], v228 offset:22528
	ds_read_b128 v[242:245], v228 offset:24576
	ds_read_b128 v[246:249], v228 offset:26624
	s_setprio 1
	s_waitcnt lgkmcnt(9)
	v_mfma_f32_16x16x32_bf16 v[76:79], v[178:181], v[106:109], v[76:79]
	v_mfma_f32_16x16x32_bf16 v[72:75], v[182:185], v[106:109], v[72:75]
	v_mfma_f32_16x16x32_bf16 v[68:71], v[186:189], v[106:109], v[68:71]
	v_mfma_f32_16x16x32_bf16 v[64:67], v[190:193], v[106:109], v[64:67]
	v_mfma_f32_16x16x32_bf16 v[60:63], v[178:181], v[110:113], v[60:63]
	v_mfma_f32_16x16x32_bf16 v[56:59], v[182:185], v[110:113], v[56:59]
	v_mfma_f32_16x16x32_bf16 v[52:55], v[186:189], v[110:113], v[52:55]
	v_mfma_f32_16x16x32_bf16 v[48:51], v[190:193], v[110:113], v[48:51]
	v_mfma_f32_16x16x32_bf16 v[44:47], v[178:181], v[122:125], v[44:47]
	v_mfma_f32_16x16x32_bf16 v[40:43], v[182:185], v[122:125], v[40:43]
	v_mfma_f32_16x16x32_bf16 v[36:39], v[186:189], v[122:125], v[36:39]
	v_mfma_f32_16x16x32_bf16 v[32:35], v[190:193], v[122:125], v[32:35]
	v_mfma_f32_16x16x32_bf16 v[28:31], v[178:181], v[156:159], v[28:31]
	v_mfma_f32_16x16x32_bf16 v[24:27], v[182:185], v[156:159], v[24:27]
	v_mfma_f32_16x16x32_bf16 v[20:23], v[186:189], v[156:159], v[20:23]
	v_mfma_f32_16x16x32_bf16 v[16:19], v[190:193], v[156:159], v[16:19]
	v_mfma_f32_16x16x32_bf16 v[12:15], v[178:181], v[166:169], v[12:15]
	v_mfma_f32_16x16x32_bf16 v[8:11], v[182:185], v[166:169], v[8:11]
	v_mfma_f32_16x16x32_bf16 v[4:7], v[186:189], v[166:169], v[4:7]
	v_mfma_f32_16x16x32_bf16 v[0:3], v[190:193], v[166:169], v[0:3]
	s_waitcnt lgkmcnt(0)
	v_mfma_f32_16x16x32_bf16 v[76:79], v[234:237], v[212:215], v[76:79]
	v_mfma_f32_16x16x32_bf16 v[72:75], v[238:241], v[212:215], v[72:75]
	v_mfma_f32_16x16x32_bf16 v[68:71], v[242:245], v[212:215], v[68:71]
	v_mfma_f32_16x16x32_bf16 v[64:67], v[246:249], v[212:215], v[64:67]
	v_mfma_f32_16x16x32_bf16 v[60:63], v[234:237], v[216:219], v[60:63]
	v_mfma_f32_16x16x32_bf16 v[56:59], v[238:241], v[216:219], v[56:59]
	v_mfma_f32_16x16x32_bf16 v[52:55], v[242:245], v[216:219], v[52:55]
	v_mfma_f32_16x16x32_bf16 v[48:51], v[246:249], v[216:219], v[48:51]
	v_mfma_f32_16x16x32_bf16 v[44:47], v[234:237], v[220:223], v[44:47]
	v_mfma_f32_16x16x32_bf16 v[40:43], v[238:241], v[220:223], v[40:43]
	v_mfma_f32_16x16x32_bf16 v[36:39], v[242:245], v[220:223], v[36:39]
	v_mfma_f32_16x16x32_bf16 v[32:35], v[246:249], v[220:223], v[32:35]
	v_mfma_f32_16x16x32_bf16 v[28:31], v[234:237], v[224:227], v[28:31]
	v_mfma_f32_16x16x32_bf16 v[24:27], v[238:241], v[224:227], v[24:27]
	v_mfma_f32_16x16x32_bf16 v[20:23], v[242:245], v[224:227], v[20:23]
	v_mfma_f32_16x16x32_bf16 v[16:19], v[246:249], v[224:227], v[16:19]
	v_mfma_f32_16x16x32_bf16 v[12:15], v[234:237], v[230:233], v[12:15]
	v_mfma_f32_16x16x32_bf16 v[8:11], v[238:241], v[230:233], v[8:11]
	v_mfma_f32_16x16x32_bf16 v[4:7], v[242:245], v[230:233], v[4:7]
	v_mfma_f32_16x16x32_bf16 v[0:3], v[246:249], v[230:233], v[0:3]
	s_setprio 0
	s_waitcnt vmcnt(0)
	s_add_u32 s12, s12, 0x80
	s_addc_u32 s13, s13, 0
	s_cmpk_lg_i32 s12, 0x780
	s_mov_b32 s11, s35
	s_waitcnt vmcnt(0)
	s_barrier
	s_cbranch_scc1 .LBB0_86
	s_mul_i32 s12, s36, 0xa0
	s_lshl_b32 s13, s10, 7
	v_ashrrev_i32_e32 v242, 7, v176
	v_mov_b32_e32 v243, 0x50
	v_and_or_b32 v248, v176, 15, s12
	v_mad_u32_u24 v248, v242, v243, v248
	v_and_b32_e32 v242, 64, v176
	v_lshrrev_b32_e32 v243, 2, v176
	v_and_b32_e32 v243, 12, v243
	v_or3_b32 v249, v242, v243, s13
	v_mul_u32_u24_e32 v244, 0x3200, v248
	v_lshl_add_u32 v244, v249, 1, v244
	v_add_u32_e32 v244, 0x1800, v244
	v_mov_b32_e32 v247, 0
	v_mov_b32_e32 v246, v244
	v_lshl_add_u64 v[248:249], v[246:247], 0, s[0:1]
	global_load_dwordx2 v[212:213], v[248:249], off
	global_load_dwordx2 v[214:215], v[248:249], off offset:32
	global_load_dwordx2 v[216:217], v[248:249], off offset:64
	global_load_dwordx2 v[218:219], v[248:249], off offset:96
	v_add_u32_e32 v246, 0x32000, v244
	v_lshl_add_u64 v[248:249], v[246:247], 0, s[0:1]
	global_load_dwordx2 v[220:221], v[248:249], off
	global_load_dwordx2 v[222:223], v[248:249], off offset:32
	global_load_dwordx2 v[224:225], v[248:249], off offset:64
	global_load_dwordx2 v[226:227], v[248:249], off offset:96
	v_add_u32_e32 v246, 0x64000, v244
	v_lshl_add_u64 v[248:249], v[246:247], 0, s[0:1]
	global_load_dwordx2 v[202:203], v[248:249], off
	global_load_dwordx2 v[210:211], v[248:249], off offset:32
	global_load_dwordx2 v[230:231], v[248:249], off offset:64
	global_load_dwordx2 v[232:233], v[248:249], off offset:96
	v_add_u32_e32 v246, 0x96000, v244
	v_lshl_add_u64 v[248:249], v[246:247], 0, s[0:1]
	global_load_dwordx2 v[234:235], v[248:249], off
	global_load_dwordx2 v[236:237], v[248:249], off offset:32
	global_load_dwordx2 v[238:239], v[248:249], off offset:64
	global_load_dwordx2 v[240:241], v[248:249], off offset:96
	v_add_u32_e32 v246, 0xc8000, v244
	v_lshl_add_u64 v[248:249], v[246:247], 0, s[0:1]
	global_load_dwordx2 v[242:243], v[248:249], off
	global_load_dwordx2 v[244:245], v[248:249], off offset:32
	global_load_dwordx2 v[246:247], v[248:249], off offset:64
	global_load_dwordx2 v[248:249], v[248:249], off offset:96
	v_add_u32_e32 v122, v120, v118
	v_add_u32_e32 v123, v120, v117
	ds_read_b128 v[106:109], v122 offset:63488
	ds_read_b128 v[110:113], v122 offset:61440
	ds_read_b128 v[156:159], v122 offset:59392
	ds_read_b128 v[166:169], v122 offset:57344
	ds_read_b128 v[178:181], v123 offset:45056
	ds_read_b128 v[182:185], v123 offset:43008
	ds_read_b128 v[186:189], v123 offset:40960
	ds_read_b128 v[190:193], v123 offset:38912
	ds_read_b128 v[194:197], v123 offset:36864
	s_setprio 1
	s_waitcnt lgkmcnt(0)
	v_mfma_f32_16x16x32_bf16 v[76:79], v[166:169], v[194:197], v[76:79]
	v_mfma_f32_16x16x32_bf16 v[72:75], v[156:159], v[194:197], v[72:75]
	v_mfma_f32_16x16x32_bf16 v[68:71], v[110:113], v[194:197], v[68:71]
	v_mfma_f32_16x16x32_bf16 v[64:67], v[106:109], v[194:197], v[64:67]
	v_mfma_f32_16x16x32_bf16 v[60:63], v[166:169], v[190:193], v[60:63]
	v_mfma_f32_16x16x32_bf16 v[56:59], v[156:159], v[190:193], v[56:59]
	v_mfma_f32_16x16x32_bf16 v[52:55], v[110:113], v[190:193], v[52:55]
	v_mfma_f32_16x16x32_bf16 v[48:51], v[106:109], v[190:193], v[48:51]
	v_mfma_f32_16x16x32_bf16 v[44:47], v[166:169], v[186:189], v[44:47]
	v_mfma_f32_16x16x32_bf16 v[40:43], v[156:159], v[186:189], v[40:43]
	v_mfma_f32_16x16x32_bf16 v[36:39], v[110:113], v[186:189], v[36:39]
	v_mfma_f32_16x16x32_bf16 v[32:35], v[106:109], v[186:189], v[32:35]
	v_mfma_f32_16x16x32_bf16 v[28:31], v[166:169], v[182:185], v[28:31]
	v_mfma_f32_16x16x32_bf16 v[24:27], v[156:159], v[182:185], v[24:27]
	v_mfma_f32_16x16x32_bf16 v[20:23], v[110:113], v[182:185], v[20:23]
	v_mfma_f32_16x16x32_bf16 v[16:19], v[106:109], v[182:185], v[16:19]
	v_mfma_f32_16x16x32_bf16 v[12:15], v[166:169], v[178:181], v[12:15]
	v_mfma_f32_16x16x32_bf16 v[8:11], v[156:159], v[178:181], v[8:11]
	v_mfma_f32_16x16x32_bf16 v[4:7], v[110:113], v[178:181], v[4:7]
	v_mfma_f32_16x16x32_bf16 v[0:3], v[106:109], v[178:181], v[0:3]
	s_setprio 0
	v_add_u32_e32 v124, v121, v117
	ds_read_b128 v[106:109], v124 offset:36864
	ds_read_b128 v[110:113], v124 offset:38912
	ds_read_b128 v[156:159], v124 offset:40960
	ds_read_b128 v[166:169], v124 offset:43008
	v_add_u32_e32 v125, v121, v118
	ds_read_b128 v[178:181], v124 offset:45056
	ds_read_b128 v[182:185], v125 offset:57344
	ds_read_b128 v[186:189], v125 offset:59392
	ds_read_b128 v[190:193], v125 offset:61440
	ds_read_b128 v[194:197], v125 offset:63488
	s_setprio 1
	s_waitcnt lgkmcnt(1)
	v_mfma_f32_16x16x32_bf16 v[68:71], v[190:193], v[106:109], v[68:71]
	s_waitcnt lgkmcnt(0)
	v_mfma_f32_16x16x32_bf16 v[64:67], v[194:197], v[106:109], v[64:67]
	v_mfma_f32_16x16x32_bf16 v[60:63], v[182:185], v[110:113], v[60:63]
	v_mfma_f32_16x16x32_bf16 v[56:59], v[186:189], v[110:113], v[56:59]
	v_mfma_f32_16x16x32_bf16 v[52:55], v[190:193], v[110:113], v[52:55]
	v_mfma_f32_16x16x32_bf16 v[48:51], v[194:197], v[110:113], v[48:51]
	v_mfma_f32_16x16x32_bf16 v[44:47], v[182:185], v[156:159], v[44:47]
	v_mfma_f32_16x16x32_bf16 v[40:43], v[186:189], v[156:159], v[40:43]
	v_mfma_f32_16x16x32_bf16 v[36:39], v[190:193], v[156:159], v[36:39]
	v_mfma_f32_16x16x32_bf16 v[32:35], v[194:197], v[156:159], v[32:35]
	v_mfma_f32_16x16x32_bf16 v[28:31], v[182:185], v[166:169], v[28:31]
	v_mfma_f32_16x16x32_bf16 v[24:27], v[186:189], v[166:169], v[24:27]
	v_mfma_f32_16x16x32_bf16 v[20:23], v[190:193], v[166:169], v[20:23]
	v_mfma_f32_16x16x32_bf16 v[16:19], v[194:197], v[166:169], v[16:19]
	v_mfma_f32_16x16x32_bf16 v[12:15], v[182:185], v[178:181], v[12:15]
	v_mfma_f32_16x16x32_bf16 v[8:11], v[186:189], v[178:181], v[8:11]
	v_mfma_f32_16x16x32_bf16 v[4:7], v[190:193], v[178:181], v[4:7]
	v_mfma_f32_16x16x32_bf16 v[0:3], v[194:197], v[178:181], v[0:3]
	v_mfma_f32_16x16x32_bf16 v[198:201], v[182:185], v[106:109], v[76:79]
	v_mfma_f32_16x16x32_bf16 v[206:209], v[186:189], v[106:109], v[72:75]
	s_setprio 0
	s_nop 1
	v_mov_b32_e32 v72, v97
	s_waitcnt vmcnt(0)
	s_barrier
	s_mul_i32 s12, s36, 0xa0
	s_movk_i32 s11, 0x50
	s_mov_b32 s35, 0
	s_lshl_b32 s13, s10, 7
	s_movk_i32 s36, 0x3200
	s_mov_b64 s[38:39], 0x1800
	s_mov_b64 s[10:11], 0x800
	v_ashrrev_i32_e32 v190, 7, v176
	v_mov_b32_e32 v191, 0x50
	v_and_or_b32 v194, v176, 15, s12
	v_mad_u32_u24 v194, v190, v191, v194
	v_and_b32_e32 v190, 64, v176
	v_lshrrev_b32_e32 v191, 2, v176
	v_and_b32_e32 v191, 12, v191
	v_or3_b32 v195, v190, v191, s13
	v_lshlrev_b32_e32 v192, 12, v194
	v_lshl_add_u32 v192, v195, 2, v192
	v_mov_b32_e32 v115, 0
	v_mov_b32_e32 v114, v192
	v_lshl_add_u64 v[196:197], v[114:115], 0, s[4:5]
	v_lshlrev_b32_e32 v190, 16, v212
	v_and_b32_e32 v191, 0xffff0000, v212
	v_pk_mul_f32 v[198:199], v[198:199], v[190:191]
	v_lshlrev_b32_e32 v212, 16, v213
	v_and_b32_e32 v213, 0xffff0000, v213
	v_pk_mul_f32 v[200:201], v[200:201], v[212:213]
	s_nop 0
	global_store_dwordx4 v[196:197], v[198:201], off
	v_lshlrev_b32_e32 v190, 16, v214
	v_and_b32_e32 v191, 0xffff0000, v214
	v_pk_mul_f32 v[206:207], v[206:207], v[190:191]
	v_lshlrev_b32_e32 v214, 16, v215
	v_and_b32_e32 v215, 0xffff0000, v215
	v_pk_mul_f32 v[208:209], v[208:209], v[214:215]
	s_nop 0
	global_store_dwordx4 v[196:197], v[206:209], off offset:64
	v_lshlrev_b32_e32 v190, 16, v216
	v_and_b32_e32 v191, 0xffff0000, v216
	v_pk_mul_f32 v[68:69], v[68:69], v[190:191]
	v_lshlrev_b32_e32 v216, 16, v217
	v_and_b32_e32 v217, 0xffff0000, v217
	v_pk_mul_f32 v[70:71], v[70:71], v[216:217]
	s_nop 0
	global_store_dwordx4 v[196:197], v[68:71], off offset:128
	v_lshlrev_b32_e32 v190, 16, v218
	v_and_b32_e32 v191, 0xffff0000, v218
	v_pk_mul_f32 v[64:65], v[64:65], v[190:191]
	v_lshlrev_b32_e32 v218, 16, v219
	v_and_b32_e32 v219, 0xffff0000, v219
	v_pk_mul_f32 v[66:67], v[66:67], v[218:219]
	s_nop 0
	global_store_dwordx4 v[196:197], v[64:67], off offset:192
	v_add_u32_e32 v114, 0x10000, v192
	v_lshl_add_u64 v[196:197], v[114:115], 0, s[4:5]
	v_lshlrev_b32_e32 v190, 16, v220
	v_and_b32_e32 v191, 0xffff0000, v220
	v_pk_mul_f32 v[60:61], v[60:61], v[190:191]
	v_lshlrev_b32_e32 v220, 16, v221
	v_and_b32_e32 v221, 0xffff0000, v221
	v_pk_mul_f32 v[62:63], v[62:63], v[220:221]
	s_nop 0
	global_store_dwordx4 v[196:197], v[60:63], off
	v_lshlrev_b32_e32 v190, 16, v222
	v_and_b32_e32 v191, 0xffff0000, v222
	v_pk_mul_f32 v[56:57], v[56:57], v[190:191]
	v_lshlrev_b32_e32 v222, 16, v223
	v_and_b32_e32 v223, 0xffff0000, v223
	v_pk_mul_f32 v[58:59], v[58:59], v[222:223]
	s_nop 0
	global_store_dwordx4 v[196:197], v[56:59], off offset:64
	v_lshlrev_b32_e32 v190, 16, v224
	v_and_b32_e32 v191, 0xffff0000, v224
	v_pk_mul_f32 v[52:53], v[52:53], v[190:191]
	v_lshlrev_b32_e32 v224, 16, v225
	v_and_b32_e32 v225, 0xffff0000, v225
	v_pk_mul_f32 v[54:55], v[54:55], v[224:225]
	s_nop 0
	global_store_dwordx4 v[196:197], v[52:55], off offset:128
	v_lshlrev_b32_e32 v190, 16, v226
	v_and_b32_e32 v191, 0xffff0000, v226
	v_pk_mul_f32 v[48:49], v[48:49], v[190:191]
	v_lshlrev_b32_e32 v226, 16, v227
	v_and_b32_e32 v227, 0xffff0000, v227
	v_pk_mul_f32 v[50:51], v[50:51], v[226:227]
	s_nop 0
	global_store_dwordx4 v[196:197], v[48:51], off offset:192
	v_add_u32_e32 v114, 0x20000, v192
	v_lshl_add_u64 v[196:197], v[114:115], 0, s[4:5]
	v_lshlrev_b32_e32 v190, 16, v202
	v_and_b32_e32 v191, 0xffff0000, v202
	v_pk_mul_f32 v[44:45], v[44:45], v[190:191]
	v_lshlrev_b32_e32 v202, 16, v203
	v_and_b32_e32 v203, 0xffff0000, v203
	v_pk_mul_f32 v[46:47], v[46:47], v[202:203]
	s_nop 0
	global_store_dwordx4 v[196:197], v[44:47], off
	v_lshlrev_b32_e32 v190, 16, v210
	v_and_b32_e32 v191, 0xffff0000, v210
	v_pk_mul_f32 v[40:41], v[40:41], v[190:191]
	v_lshlrev_b32_e32 v210, 16, v211
	v_and_b32_e32 v211, 0xffff0000, v211
	v_pk_mul_f32 v[42:43], v[42:43], v[210:211]
	s_nop 0
	global_store_dwordx4 v[196:197], v[40:43], off offset:64
	v_lshlrev_b32_e32 v190, 16, v230
	v_and_b32_e32 v191, 0xffff0000, v230
	v_pk_mul_f32 v[36:37], v[36:37], v[190:191]
	v_lshlrev_b32_e32 v230, 16, v231
	v_and_b32_e32 v231, 0xffff0000, v231
	v_pk_mul_f32 v[38:39], v[38:39], v[230:231]
	s_nop 0
	global_store_dwordx4 v[196:197], v[36:39], off offset:128
	v_lshlrev_b32_e32 v190, 16, v232
	v_and_b32_e32 v191, 0xffff0000, v232
	v_pk_mul_f32 v[32:33], v[32:33], v[190:191]
	v_lshlrev_b32_e32 v232, 16, v233
	v_and_b32_e32 v233, 0xffff0000, v233
	v_pk_mul_f32 v[34:35], v[34:35], v[232:233]
	s_nop 0
	global_store_dwordx4 v[196:197], v[32:35], off offset:192
	v_add_u32_e32 v114, 0x30000, v192
	v_lshl_add_u64 v[196:197], v[114:115], 0, s[4:5]
	v_lshlrev_b32_e32 v190, 16, v234
	v_and_b32_e32 v191, 0xffff0000, v234
	v_pk_mul_f32 v[28:29], v[28:29], v[190:191]
	v_lshlrev_b32_e32 v234, 16, v235
	v_and_b32_e32 v235, 0xffff0000, v235
	v_pk_mul_f32 v[30:31], v[30:31], v[234:235]
	s_nop 0
	global_store_dwordx4 v[196:197], v[28:31], off
	v_lshlrev_b32_e32 v190, 16, v236
	v_and_b32_e32 v191, 0xffff0000, v236
	v_pk_mul_f32 v[24:25], v[24:25], v[190:191]
	v_lshlrev_b32_e32 v236, 16, v237
	v_and_b32_e32 v237, 0xffff0000, v237
	v_pk_mul_f32 v[26:27], v[26:27], v[236:237]
	s_nop 0
	global_store_dwordx4 v[196:197], v[24:27], off offset:64
	v_lshlrev_b32_e32 v190, 16, v238
	v_and_b32_e32 v191, 0xffff0000, v238
	v_pk_mul_f32 v[20:21], v[20:21], v[190:191]
	v_lshlrev_b32_e32 v238, 16, v239
	v_and_b32_e32 v239, 0xffff0000, v239
	v_pk_mul_f32 v[22:23], v[22:23], v[238:239]
	s_nop 0
	global_store_dwordx4 v[196:197], v[20:23], off offset:128
	v_lshlrev_b32_e32 v190, 16, v240
	v_and_b32_e32 v191, 0xffff0000, v240
	v_pk_mul_f32 v[16:17], v[16:17], v[190:191]
	v_lshlrev_b32_e32 v240, 16, v241
	v_and_b32_e32 v241, 0xffff0000, v241
	v_pk_mul_f32 v[18:19], v[18:19], v[240:241]
	s_nop 0
	global_store_dwordx4 v[196:197], v[16:19], off offset:192
	v_add_u32_e32 v114, 0x40000, v192
	v_lshl_add_u64 v[196:197], v[114:115], 0, s[4:5]
	v_lshlrev_b32_e32 v190, 16, v242
	v_and_b32_e32 v191, 0xffff0000, v242
	v_pk_mul_f32 v[12:13], v[12:13], v[190:191]
	v_lshlrev_b32_e32 v242, 16, v243
	v_and_b32_e32 v243, 0xffff0000, v243
	v_pk_mul_f32 v[14:15], v[14:15], v[242:243]
	s_nop 0
	global_store_dwordx4 v[196:197], v[12:15], off
	v_lshlrev_b32_e32 v190, 16, v244
	v_and_b32_e32 v191, 0xffff0000, v244
	v_pk_mul_f32 v[8:9], v[8:9], v[190:191]
	v_lshlrev_b32_e32 v244, 16, v245
	v_and_b32_e32 v245, 0xffff0000, v245
	v_pk_mul_f32 v[10:11], v[10:11], v[244:245]
	s_nop 0
	global_store_dwordx4 v[196:197], v[8:11], off offset:64
	v_lshlrev_b32_e32 v190, 16, v246
	v_and_b32_e32 v191, 0xffff0000, v246
	v_pk_mul_f32 v[4:5], v[4:5], v[190:191]
	v_lshlrev_b32_e32 v246, 16, v247
	v_and_b32_e32 v247, 0xffff0000, v247
	v_pk_mul_f32 v[6:7], v[6:7], v[246:247]
	s_nop 0
	global_store_dwordx4 v[196:197], v[4:7], off offset:128
	v_lshlrev_b32_e32 v190, 16, v248
	v_and_b32_e32 v191, 0xffff0000, v248
	v_pk_mul_f32 v[0:1], v[0:1], v[190:191]
	v_lshlrev_b32_e32 v248, 16, v249
	v_and_b32_e32 v249, 0xffff0000, v249
	v_pk_mul_f32 v[2:3], v[2:3], v[248:249]
	s_nop 0
	global_store_dwordx4 v[196:197], v[0:3], off offset:192
	s_nop 1
	v_lshl_add_u64 v[0:1], v[104:105], 0, s[10:11]
	v_readfirstlane_b32 s10, v81
	s_mov_b32 m0, s10
	s_mov_b64 s[10:11], 0x64800
	global_load_lds_dwordx4 v[0:1], off
	v_lshl_add_u64 v[0:1], v[104:105], 0, s[10:11]
	v_readfirstlane_b32 s10, v133
	s_mov_b32 m0, s10
	s_mov_b64 s[10:11], 0xc8800
	global_load_lds_dwordx4 v[0:1], off
	v_lshl_add_u64 v[0:1], v[104:105], 0, s[10:11]
	v_readfirstlane_b32 s10, v132
	s_mov_b32 m0, s10
	s_mov_b64 s[10:11], 0x12c800
	global_load_lds_dwordx4 v[0:1], off
	v_lshl_add_u64 v[0:1], v[104:105], 0, s[10:11]
	v_readfirstlane_b32 s10, v131
	s_mov_b32 m0, s10
	s_mov_b64 s[10:11], 0x190800
	global_load_lds_dwordx4 v[0:1], off
	v_lshl_add_u64 v[0:1], v[104:105], 0, s[10:11]
	v_readfirstlane_b32 s10, v130
	s_mov_b32 m0, s10
	v_readfirstlane_b32 s10, v129
	global_load_lds_dwordx4 v[0:1], off
	v_lshl_add_u64 v[0:1], v[86:87], 0, s[8:9]
	s_mov_b32 m0, s10
	v_readfirstlane_b32 s10, v128
	global_load_lds_dwordx4 v[0:1], off
	v_lshl_add_u64 v[2:3], v[0:1], 0, s[40:41]
	s_mov_b32 m0, s10
	s_mov_b64 s[10:11], 0x20000
	global_load_lds_dwordx4 v[2:3], off
	v_lshl_add_u64 v[2:3], v[0:1], 0, s[10:11]
	v_readfirstlane_b32 s10, v127
	s_mov_b32 m0, s10
	s_mov_b64 s[10:11], 0x30000
	v_lshl_add_u64 v[0:1], v[0:1], 0, s[10:11]
	v_readfirstlane_b32 s10, v126
	global_load_lds_dwordx4 v[2:3], off
	s_mov_b32 m0, s10
	s_mov_b64 s[10:11], 0
	global_load_lds_dwordx4 v[0:1], off
	s_waitcnt vmcnt(0)
	v_mov_b32_e32 v0, 0
	v_mov_b32_e32 v1, v0
	v_mov_b32_e32 v2, v0
	v_mov_b32_e32 v3, v0
	v_mov_b32_e32 v4, v0
	v_mov_b32_e32 v5, v0
	v_mov_b32_e32 v6, v0
	v_mov_b32_e32 v7, v0
	v_mov_b32_e32 v8, v0
	v_mov_b32_e32 v9, v0
	v_mov_b32_e32 v10, v0
	v_mov_b32_e32 v11, v0
	v_mov_b32_e32 v12, v0
	v_mov_b32_e32 v13, v0
	v_mov_b32_e32 v14, v0
	v_mov_b32_e32 v15, v0
	v_mov_b32_e32 v16, v0
	v_mov_b32_e32 v17, v0
	v_mov_b32_e32 v18, v0
	v_mov_b32_e32 v19, v0
	v_mov_b32_e32 v20, v0
	v_mov_b32_e32 v21, v0
	v_mov_b32_e32 v22, v0
	v_mov_b32_e32 v23, v0
	v_mov_b32_e32 v24, v0
	v_mov_b32_e32 v25, v0
	v_mov_b32_e32 v26, v0
	v_mov_b32_e32 v27, v0
	v_mov_b32_e32 v28, v0
	v_mov_b32_e32 v29, v0
	v_mov_b32_e32 v30, v0
	v_mov_b32_e32 v31, v0
	v_mov_b32_e32 v32, v0
	v_mov_b32_e32 v33, v0
	v_mov_b32_e32 v34, v0
	v_mov_b32_e32 v35, v0
	v_mov_b32_e32 v36, v0
	v_mov_b32_e32 v37, v0
	v_mov_b32_e32 v38, v0
	v_mov_b32_e32 v39, v0
	v_mov_b32_e32 v40, v0
	v_mov_b32_e32 v41, v0
	v_mov_b32_e32 v42, v0
	v_mov_b32_e32 v43, v0
	v_mov_b32_e32 v44, v0
	v_mov_b32_e32 v45, v0
	v_mov_b32_e32 v46, v0
	v_mov_b32_e32 v47, v0
	v_mov_b32_e32 v48, v0
	v_mov_b32_e32 v49, v0
	v_mov_b32_e32 v50, v0
	v_mov_b32_e32 v51, v0
	v_mov_b32_e32 v52, v0
	v_mov_b32_e32 v53, v0
	v_mov_b32_e32 v54, v0
	v_mov_b32_e32 v55, v0
	v_mov_b32_e32 v56, v0
	v_mov_b32_e32 v57, v0
	v_mov_b32_e32 v58, v0
	v_mov_b32_e32 v59, v0
	v_mov_b32_e32 v60, v0
	v_mov_b32_e32 v61, v0
	v_mov_b32_e32 v62, v0
	v_mov_b32_e32 v63, v0
	v_mov_b32_e32 v64, v0
	v_mov_b32_e32 v65, v0
	v_mov_b32_e32 v66, v0
	v_mov_b32_e32 v67, v0
	v_mov_b32_e32 v68, v0
	v_mov_b32_e32 v69, v0
	v_mov_b32_e32 v70, v0
	v_mov_b32_e32 v71, v0
	v_mov_b32_e32 v72, v0
	v_mov_b32_e32 v73, v0
	v_mov_b32_e32 v74, v0
	v_mov_b32_e32 v75, v0
	v_mov_b32_e32 v76, v0
	v_mov_b32_e32 v77, v0
	v_mov_b32_e32 v78, v0
	v_mov_b32_e32 v79, v0
	s_waitcnt vmcnt(0) lgkmcnt(0)
	s_barrier
.LBB0_88:
	s_add_i32 s36, s35, 1
	s_bitcmp1_b32 s36, 0
	s_cselect_b32 s37, 0x9000, 0
	v_add_u32_e32 v108, s37, v81
	v_lshl_add_u64 v[104:105], v[94:95], 0, s[10:11]
	s_mov_b64 s[38:39], 0x6181880
	v_readfirstlane_b32 s37, v108
	v_add_u32_e32 v109, 0x1000, v108
	v_lshl_add_u64 v[106:107], v[104:105], 0, s[38:39]
	s_mov_b32 m0, s37
	s_mov_b64 s[38:39], 0x61e5880
	v_readfirstlane_b32 s37, v109
	v_add_u32_e32 v109, 0x2000, v108
	global_load_lds_dwordx4 v[106:107], off
	v_lshl_add_u64 v[106:107], v[104:105], 0, s[38:39]
	s_mov_b32 m0, s37
	s_mov_b64 s[38:39], 0x6249880
	v_readfirstlane_b32 s37, v109
	v_add_u32_e32 v109, 0x3000, v108
	global_load_lds_dwordx4 v[106:107], off
	v_lshl_add_u64 v[106:107], v[104:105], 0, s[38:39]
	s_mov_b32 m0, s37
	s_mov_b64 s[38:39], 0x62ad880
	v_readfirstlane_b32 s37, v109
	global_load_lds_dwordx4 v[106:107], off
	v_lshl_add_u64 v[106:107], v[104:105], 0, s[38:39]
	s_mov_b32 m0, s37
	s_mov_b64 s[38:39], 0x6311880
	global_load_lds_dwordx4 v[106:107], off
	v_add_u32_e32 v106, 0x4000, v108
	v_lshl_add_u64 v[104:105], v[104:105], 0, s[38:39]
	v_readfirstlane_b32 s37, v106
	s_mov_b32 m0, s37
	v_add_u32_e32 v109, 0x5000, v108
	global_load_lds_dwordx4 v[104:105], off
	v_lshl_add_u64 v[104:105], v[100:101], 0, s[10:11]
	s_mov_b64 s[38:39], 0x14731080
	v_readfirstlane_b32 s37, v109
	v_add_u32_e32 v109, 0x6000, v108
	v_lshl_add_u64 v[106:107], v[104:105], 0, s[38:39]
	s_mov_b32 m0, s37
	s_mov_b64 s[38:39], 0x14741080
	v_readfirstlane_b32 s37, v109
	v_add_u32_e32 v109, 0x7000, v108
	global_load_lds_dwordx4 v[106:107], off
	v_lshl_add_u64 v[106:107], v[104:105], 0, s[38:39]
	s_mov_b32 m0, s37
	s_mov_b64 s[38:39], 0x14751080
	v_readfirstlane_b32 s37, v109
	global_load_lds_dwordx4 v[106:107], off
	v_lshl_add_u64 v[106:107], v[104:105], 0, s[38:39]
	s_mov_b32 m0, s37
	s_mov_b64 s[38:39], 0x14761080
	global_load_lds_dwordx4 v[106:107], off
	v_add_u32_e32 v106, 0x8000, v108
	v_lshl_add_u64 v[104:105], v[104:105], 0, s[38:39]
	v_readfirstlane_b32 s37, v106
	s_mov_b32 m0, s37
	s_bitcmp1_b32 s35, 0
	global_load_lds_dwordx4 v[104:105], off
	s_cselect_b32 s35, 0x9000, 0
	s_add_i32 s35, s35, 0
	v_add_u32_e32 v166, s35, v116
	v_add_u32_e32 v167, v166, v117
	ds_read_b128 v[104:107], v167
	ds_read_b128 v[108:111], v167 offset:2048
	ds_read_b128 v[112:115], v167 offset:4096
	ds_read_b128 v[156:159], v167 offset:6144
	v_add_u32_e32 v177, v166, v118
	ds_read_b128 v[166:169], v167 offset:8192
	ds_read_b128 v[178:181], v177 offset:20480
	ds_read_b128 v[182:185], v177 offset:22528
	ds_read_b128 v[186:189], v177 offset:24576
	ds_read_b128 v[190:193], v177 offset:26624
	v_add_u32_e32 v210, s35, v119
	v_add_u32_e32 v211, v210, v117
	ds_read_b128 v[212:215], v211
	ds_read_b128 v[216:219], v211 offset:2048
	ds_read_b128 v[220:223], v211 offset:4096
	ds_read_b128 v[224:227], v211 offset:6144
	v_add_u32_e32 v228, v210, v118
	ds_read_b128 v[230:233], v211 offset:8192
	ds_read_b128 v[234:237], v228 offset:20480
	ds_read_b128 v[238:241], v228 offset:22528
	ds_read_b128 v[242:245], v228 offset:24576
	ds_read_b128 v[246:249], v228 offset:26624
	s_setprio 1
	s_waitcnt lgkmcnt(9)
	v_mfma_f32_16x16x32_bf16 v[76:79], v[178:181], v[104:107], v[76:79]
	v_mfma_f32_16x16x32_bf16 v[72:75], v[182:185], v[104:107], v[72:75]
	v_mfma_f32_16x16x32_bf16 v[68:71], v[186:189], v[104:107], v[68:71]
	v_mfma_f32_16x16x32_bf16 v[64:67], v[190:193], v[104:107], v[64:67]
	v_mfma_f32_16x16x32_bf16 v[60:63], v[178:181], v[108:111], v[60:63]
	v_mfma_f32_16x16x32_bf16 v[56:59], v[182:185], v[108:111], v[56:59]
	v_mfma_f32_16x16x32_bf16 v[52:55], v[186:189], v[108:111], v[52:55]
	v_mfma_f32_16x16x32_bf16 v[48:51], v[190:193], v[108:111], v[48:51]
	v_mfma_f32_16x16x32_bf16 v[44:47], v[178:181], v[112:115], v[44:47]
	v_mfma_f32_16x16x32_bf16 v[40:43], v[182:185], v[112:115], v[40:43]
	v_mfma_f32_16x16x32_bf16 v[36:39], v[186:189], v[112:115], v[36:39]
	v_mfma_f32_16x16x32_bf16 v[32:35], v[190:193], v[112:115], v[32:35]
	v_mfma_f32_16x16x32_bf16 v[28:31], v[178:181], v[156:159], v[28:31]
	v_mfma_f32_16x16x32_bf16 v[24:27], v[182:185], v[156:159], v[24:27]
	v_mfma_f32_16x16x32_bf16 v[20:23], v[186:189], v[156:159], v[20:23]
	v_mfma_f32_16x16x32_bf16 v[16:19], v[190:193], v[156:159], v[16:19]
	v_mfma_f32_16x16x32_bf16 v[12:15], v[178:181], v[166:169], v[12:15]
	v_mfma_f32_16x16x32_bf16 v[8:11], v[182:185], v[166:169], v[8:11]
	v_mfma_f32_16x16x32_bf16 v[4:7], v[186:189], v[166:169], v[4:7]
	v_mfma_f32_16x16x32_bf16 v[0:3], v[190:193], v[166:169], v[0:3]
	s_waitcnt lgkmcnt(0)
	v_mfma_f32_16x16x32_bf16 v[76:79], v[234:237], v[212:215], v[76:79]
	v_mfma_f32_16x16x32_bf16 v[72:75], v[238:241], v[212:215], v[72:75]
	v_mfma_f32_16x16x32_bf16 v[68:71], v[242:245], v[212:215], v[68:71]
	v_mfma_f32_16x16x32_bf16 v[64:67], v[246:249], v[212:215], v[64:67]
	v_mfma_f32_16x16x32_bf16 v[60:63], v[234:237], v[216:219], v[60:63]
	v_mfma_f32_16x16x32_bf16 v[56:59], v[238:241], v[216:219], v[56:59]
	v_mfma_f32_16x16x32_bf16 v[52:55], v[242:245], v[216:219], v[52:55]
	v_mfma_f32_16x16x32_bf16 v[48:51], v[246:249], v[216:219], v[48:51]
	v_mfma_f32_16x16x32_bf16 v[44:47], v[234:237], v[220:223], v[44:47]
	v_mfma_f32_16x16x32_bf16 v[40:43], v[238:241], v[220:223], v[40:43]
	v_mfma_f32_16x16x32_bf16 v[36:39], v[242:245], v[220:223], v[36:39]
	v_mfma_f32_16x16x32_bf16 v[32:35], v[246:249], v[220:223], v[32:35]
	v_mfma_f32_16x16x32_bf16 v[28:31], v[234:237], v[224:227], v[28:31]
	v_mfma_f32_16x16x32_bf16 v[24:27], v[238:241], v[224:227], v[24:27]
	v_mfma_f32_16x16x32_bf16 v[20:23], v[242:245], v[224:227], v[20:23]
	v_mfma_f32_16x16x32_bf16 v[16:19], v[246:249], v[224:227], v[16:19]
	v_mfma_f32_16x16x32_bf16 v[12:15], v[234:237], v[230:233], v[12:15]
	v_mfma_f32_16x16x32_bf16 v[8:11], v[238:241], v[230:233], v[8:11]
	v_mfma_f32_16x16x32_bf16 v[4:7], v[242:245], v[230:233], v[4:7]
	v_mfma_f32_16x16x32_bf16 v[0:3], v[246:249], v[230:233], v[0:3]
	s_setprio 0
	s_waitcnt vmcnt(0)
	s_add_u32 s10, s10, 0x80
	s_addc_u32 s11, s11, 0
	s_cmpk_lg_i32 s10, 0x780
	s_mov_b32 s35, s36
	s_waitcnt vmcnt(0)
	s_barrier
	s_cbranch_scc1 .LBB0_88
	v_ashrrev_i32_e32 v242, 7, v176
	v_mov_b32_e32 v243, 0x50
	v_and_or_b32 v248, v176, 15, s12
	v_mad_u32_u24 v248, v242, v243, v248
	v_and_b32_e32 v242, 64, v176
	v_lshrrev_b32_e32 v243, 2, v176
	v_and_b32_e32 v243, 12, v243
	v_or3_b32 v249, v242, v243, s13
	v_mul_u32_u24_e32 v244, 0x3200, v248
	v_lshl_add_u32 v244, v249, 1, v244
	v_add_u32_e32 v244, 0x2000, v244
	v_mov_b32_e32 v247, 0
	v_mov_b32_e32 v246, v244
	v_lshl_add_u64 v[248:249], v[246:247], 0, s[0:1]
	global_load_dwordx2 v[212:213], v[248:249], off
	global_load_dwordx2 v[214:215], v[248:249], off offset:32
	global_load_dwordx2 v[216:217], v[248:249], off offset:64
	global_load_dwordx2 v[218:219], v[248:249], off offset:96
	v_add_u32_e32 v246, 0x32000, v244
	v_lshl_add_u64 v[248:249], v[246:247], 0, s[0:1]
	global_load_dwordx2 v[220:221], v[248:249], off
	global_load_dwordx2 v[222:223], v[248:249], off offset:32
	global_load_dwordx2 v[224:225], v[248:249], off offset:64
	global_load_dwordx2 v[226:227], v[248:249], off offset:96
	v_add_u32_e32 v246, 0x64000, v244
	v_lshl_add_u64 v[248:249], v[246:247], 0, s[0:1]
	global_load_dwordx2 v[202:203], v[248:249], off
	global_load_dwordx2 v[210:211], v[248:249], off offset:32
	global_load_dwordx2 v[230:231], v[248:249], off offset:64
	global_load_dwordx2 v[232:233], v[248:249], off offset:96
	v_add_u32_e32 v246, 0x96000, v244
	v_lshl_add_u64 v[248:249], v[246:247], 0, s[0:1]
	global_load_dwordx2 v[234:235], v[248:249], off
	global_load_dwordx2 v[236:237], v[248:249], off offset:32
	global_load_dwordx2 v[238:239], v[248:249], off offset:64
	global_load_dwordx2 v[240:241], v[248:249], off offset:96
	v_add_u32_e32 v246, 0xc8000, v244
	v_lshl_add_u64 v[248:249], v[246:247], 0, s[0:1]
	global_load_dwordx2 v[242:243], v[248:249], off
	global_load_dwordx2 v[244:245], v[248:249], off offset:32
	global_load_dwordx2 v[246:247], v[248:249], off offset:64
	global_load_dwordx2 v[248:249], v[248:249], off offset:96
	ds_read_b128 v[104:107], v122 offset:63488
	ds_read_b128 v[108:111], v122 offset:61440
	ds_read_b128 v[112:115], v122 offset:59392
	ds_read_b128 v[156:159], v122 offset:57344
	ds_read_b128 v[166:169], v123 offset:45056
	ds_read_b128 v[178:181], v123 offset:43008
	ds_read_b128 v[182:185], v123 offset:40960
	ds_read_b128 v[186:189], v123 offset:38912
	ds_read_b128 v[190:193], v123 offset:36864
	s_setprio 1
	s_waitcnt lgkmcnt(0)
	v_mfma_f32_16x16x32_bf16 v[76:79], v[156:159], v[190:193], v[76:79]
	v_mfma_f32_16x16x32_bf16 v[72:75], v[112:115], v[190:193], v[72:75]
	v_mfma_f32_16x16x32_bf16 v[68:71], v[108:111], v[190:193], v[68:71]
	v_mfma_f32_16x16x32_bf16 v[64:67], v[104:107], v[190:193], v[64:67]
	v_mfma_f32_16x16x32_bf16 v[60:63], v[156:159], v[186:189], v[60:63]
	v_mfma_f32_16x16x32_bf16 v[56:59], v[112:115], v[186:189], v[56:59]
	v_mfma_f32_16x16x32_bf16 v[52:55], v[108:111], v[186:189], v[52:55]
	v_mfma_f32_16x16x32_bf16 v[48:51], v[104:107], v[186:189], v[48:51]
	v_mfma_f32_16x16x32_bf16 v[44:47], v[156:159], v[182:185], v[44:47]
	v_mfma_f32_16x16x32_bf16 v[40:43], v[112:115], v[182:185], v[40:43]
	v_mfma_f32_16x16x32_bf16 v[36:39], v[108:111], v[182:185], v[36:39]
	v_mfma_f32_16x16x32_bf16 v[32:35], v[104:107], v[182:185], v[32:35]
	v_mfma_f32_16x16x32_bf16 v[28:31], v[156:159], v[178:181], v[28:31]
	v_mfma_f32_16x16x32_bf16 v[24:27], v[112:115], v[178:181], v[24:27]
	v_mfma_f32_16x16x32_bf16 v[20:23], v[108:111], v[178:181], v[20:23]
	v_mfma_f32_16x16x32_bf16 v[16:19], v[104:107], v[178:181], v[16:19]
	v_mfma_f32_16x16x32_bf16 v[12:15], v[156:159], v[166:169], v[12:15]
	v_mfma_f32_16x16x32_bf16 v[8:11], v[112:115], v[166:169], v[8:11]
	v_mfma_f32_16x16x32_bf16 v[4:7], v[108:111], v[166:169], v[4:7]
	v_mfma_f32_16x16x32_bf16 v[0:3], v[104:107], v[166:169], v[0:3]
	s_setprio 0
	ds_read_b128 v[104:107], v124 offset:36864
	ds_read_b128 v[108:111], v124 offset:38912
	ds_read_b128 v[112:115], v124 offset:40960
	ds_read_b128 v[156:159], v124 offset:43008
	ds_read_b128 v[166:169], v124 offset:45056
	ds_read_b128 v[178:181], v125 offset:57344
	ds_read_b128 v[182:185], v125 offset:59392
	ds_read_b128 v[186:189], v125 offset:61440
	ds_read_b128 v[190:193], v125 offset:63488
	s_setprio 1
	s_waitcnt lgkmcnt(3)
	v_mfma_f32_16x16x32_bf16 v[76:79], v[178:181], v[104:107], v[76:79]
	s_waitcnt lgkmcnt(0)
	v_mfma_f32_16x16x32_bf16 v[64:67], v[190:193], v[104:107], v[64:67]
	v_mfma_f32_16x16x32_bf16 v[60:63], v[178:181], v[108:111], v[60:63]
	v_mfma_f32_16x16x32_bf16 v[56:59], v[182:185], v[108:111], v[56:59]
	v_mfma_f32_16x16x32_bf16 v[52:55], v[186:189], v[108:111], v[52:55]
	v_mfma_f32_16x16x32_bf16 v[48:51], v[190:193], v[108:111], v[48:51]
	v_mfma_f32_16x16x32_bf16 v[44:47], v[178:181], v[112:115], v[44:47]
	v_mfma_f32_16x16x32_bf16 v[40:43], v[182:185], v[112:115], v[40:43]
	v_mfma_f32_16x16x32_bf16 v[36:39], v[186:189], v[112:115], v[36:39]
	v_mfma_f32_16x16x32_bf16 v[32:35], v[190:193], v[112:115], v[32:35]
	v_mfma_f32_16x16x32_bf16 v[28:31], v[178:181], v[156:159], v[28:31]
	v_mfma_f32_16x16x32_bf16 v[24:27], v[182:185], v[156:159], v[24:27]
	v_mfma_f32_16x16x32_bf16 v[20:23], v[186:189], v[156:159], v[20:23]
	v_mfma_f32_16x16x32_bf16 v[16:19], v[190:193], v[156:159], v[16:19]
	v_mfma_f32_16x16x32_bf16 v[12:15], v[178:181], v[166:169], v[12:15]
	v_mfma_f32_16x16x32_bf16 v[8:11], v[182:185], v[166:169], v[8:11]
	v_mfma_f32_16x16x32_bf16 v[4:7], v[186:189], v[166:169], v[4:7]
	v_mfma_f32_16x16x32_bf16 v[0:3], v[190:193], v[166:169], v[0:3]
	v_mfma_f32_16x16x32_bf16 v[194:197], v[182:185], v[104:107], v[72:75]
	v_mfma_f32_16x16x32_bf16 v[198:201], v[186:189], v[104:107], v[68:71]
	s_setprio 0
	s_nop 1
	v_mov_b32_e32 v68, v97
	s_waitcnt vmcnt(0)
	s_barrier
	s_movk_i32 s11, 0x50
	s_mov_b32 s10, 0
	s_movk_i32 s11, 0x3200
	s_mov_b64 s[38:39], 0x2000
	s_mov_b64 s[36:37], 0x1000
	v_readfirstlane_b32 s11, v81
	s_mov_b32 m0, s11
	v_readfirstlane_b32 s11, v133
	v_ashrrev_i32_e32 v186, 7, v176
	v_mov_b32_e32 v187, 0x50
	v_and_or_b32 v190, v176, 15, s12
	v_mad_u32_u24 v190, v186, v187, v190
	v_and_b32_e32 v186, 64, v176
	v_lshrrev_b32_e32 v187, 2, v176
	v_and_b32_e32 v187, 12, v187
	v_or3_b32 v191, v186, v187, s13
	v_lshlrev_b32_e32 v204, 12, v190
	v_lshl_add_u32 v204, v191, 2, v204
	v_mov_b32_e32 v115, 0
	v_mov_b32_e32 v114, v204
	v_lshl_add_u64 v[190:191], v[114:115], 0, s[4:5]
	global_load_dwordx4 v[68:71], v[190:191], off
	global_load_dwordx4 v[72:75], v[190:191], off offset:64
	global_load_dwordx4 v[106:109], v[190:191], off offset:128
	global_load_dwordx4 v[110:113], v[190:191], off offset:192
	v_add_u32_e32 v114, 0x10000, v204
	v_lshl_add_u64 v[190:191], v[114:115], 0, s[4:5]
	global_load_dwordx4 v[156:159], v[190:191], off
	global_load_dwordx4 v[166:169], v[190:191], off offset:64
	global_load_dwordx4 v[178:181], v[190:191], off offset:128
	global_load_dwordx4 v[182:185], v[190:191], off offset:192
	v_mov_b32_e32 v114, v204
	v_lshl_add_u64 v[192:193], v[114:115], 0, s[4:5]
	s_waitcnt vmcnt(7)
	v_lshlrev_b32_e32 v186, 16, v212
	v_and_b32_e32 v187, 0xffff0000, v212
	v_pk_fma_f32 v[76:77], v[76:77], v[186:187], v[68:69]
	v_lshlrev_b32_e32 v212, 16, v213
	v_and_b32_e32 v213, 0xffff0000, v213
	v_pk_fma_f32 v[78:79], v[78:79], v[212:213], v[70:71]
	s_nop 0
	global_store_dwordx4 v[192:193], v[76:79], off
	s_waitcnt vmcnt(7)
	v_lshlrev_b32_e32 v186, 16, v214
	v_and_b32_e32 v187, 0xffff0000, v214
	v_pk_fma_f32 v[194:195], v[194:195], v[186:187], v[72:73]
	v_lshlrev_b32_e32 v214, 16, v215
	v_and_b32_e32 v215, 0xffff0000, v215
	v_pk_fma_f32 v[196:197], v[196:197], v[214:215], v[74:75]
	s_nop 0
	global_store_dwordx4 v[192:193], v[194:197], off offset:64
	s_waitcnt vmcnt(7)
	v_lshlrev_b32_e32 v186, 16, v216
	v_and_b32_e32 v187, 0xffff0000, v216
	v_pk_fma_f32 v[198:199], v[198:199], v[186:187], v[106:107]
	v_lshlrev_b32_e32 v216, 16, v217
	v_and_b32_e32 v217, 0xffff0000, v217
	v_pk_fma_f32 v[200:201], v[200:201], v[216:217], v[108:109]
	s_nop 0
	global_store_dwordx4 v[192:193], v[198:201], off offset:128
	s_waitcnt vmcnt(7)
	v_lshlrev_b32_e32 v186, 16, v218
	v_and_b32_e32 v187, 0xffff0000, v218
	v_pk_fma_f32 v[64:65], v[64:65], v[186:187], v[110:111]
	v_lshlrev_b32_e32 v218, 16, v219
	v_and_b32_e32 v219, 0xffff0000, v219
	v_pk_fma_f32 v[66:67], v[66:67], v[218:219], v[112:113]
	s_nop 0
	global_store_dwordx4 v[192:193], v[64:67], off offset:192
	v_add_u32_e32 v114, 0x20000, v204
	v_lshl_add_u64 v[190:191], v[114:115], 0, s[4:5]
	global_load_dwordx4 v[68:71], v[190:191], off
	global_load_dwordx4 v[72:75], v[190:191], off offset:64
	global_load_dwordx4 v[106:109], v[190:191], off offset:128
	global_load_dwordx4 v[110:113], v[190:191], off offset:192
	v_add_u32_e32 v114, 0x10000, v204
	v_lshl_add_u64 v[192:193], v[114:115], 0, s[4:5]
	s_waitcnt vmcnt(11)
	v_lshlrev_b32_e32 v186, 16, v220
	v_and_b32_e32 v187, 0xffff0000, v220
	v_pk_fma_f32 v[60:61], v[60:61], v[186:187], v[156:157]
	v_lshlrev_b32_e32 v220, 16, v221
	v_and_b32_e32 v221, 0xffff0000, v221
	v_pk_fma_f32 v[62:63], v[62:63], v[220:221], v[158:159]
	s_nop 0
	global_store_dwordx4 v[192:193], v[60:63], off
	s_waitcnt vmcnt(11)
	v_lshlrev_b32_e32 v186, 16, v222
	v_and_b32_e32 v187, 0xffff0000, v222
	v_pk_fma_f32 v[56:57], v[56:57], v[186:187], v[166:167]
	v_lshlrev_b32_e32 v222, 16, v223
	v_and_b32_e32 v223, 0xffff0000, v223
	v_pk_fma_f32 v[58:59], v[58:59], v[222:223], v[168:169]
	s_nop 0
	global_store_dwordx4 v[192:193], v[56:59], off offset:64
	s_waitcnt vmcnt(11)
	v_lshlrev_b32_e32 v186, 16, v224
	v_and_b32_e32 v187, 0xffff0000, v224
	v_pk_fma_f32 v[52:53], v[52:53], v[186:187], v[178:179]
	v_lshlrev_b32_e32 v224, 16, v225
	v_and_b32_e32 v225, 0xffff0000, v225
	v_pk_fma_f32 v[54:55], v[54:55], v[224:225], v[180:181]
	s_nop 0
	global_store_dwordx4 v[192:193], v[52:55], off offset:128
	s_waitcnt vmcnt(11)
	v_lshlrev_b32_e32 v186, 16, v226
	v_and_b32_e32 v187, 0xffff0000, v226
	v_pk_fma_f32 v[48:49], v[48:49], v[186:187], v[182:183]
	v_lshlrev_b32_e32 v226, 16, v227
	v_and_b32_e32 v227, 0xffff0000, v227
	v_pk_fma_f32 v[50:51], v[50:51], v[226:227], v[184:185]
	s_nop 0
	global_store_dwordx4 v[192:193], v[48:51], off offset:192
	v_add_u32_e32 v114, 0x30000, v204
	v_lshl_add_u64 v[190:191], v[114:115], 0, s[4:5]
	global_load_dwordx4 v[156:159], v[190:191], off
	global_load_dwordx4 v[166:169], v[190:191], off offset:64
	global_load_dwordx4 v[178:181], v[190:191], off offset:128
	global_load_dwordx4 v[182:185], v[190:191], off offset:192
	v_add_u32_e32 v114, 0x40000, v204
	v_lshl_add_u64 v[190:191], v[114:115], 0, s[4:5]
	global_load_dwordx4 v[212:215], v[190:191], off
	global_load_dwordx4 v[216:219], v[190:191], off offset:64
	global_load_dwordx4 v[220:223], v[190:191], off offset:128
	global_load_dwordx4 v[224:227], v[190:191], off offset:192
	v_add_u32_e32 v114, 0x20000, v204
	v_lshl_add_u64 v[192:193], v[114:115], 0, s[4:5]
	s_waitcnt vmcnt(15)
	v_lshlrev_b32_e32 v186, 16, v202
	v_and_b32_e32 v187, 0xffff0000, v202
	v_pk_fma_f32 v[44:45], v[44:45], v[186:187], v[68:69]
	v_lshlrev_b32_e32 v202, 16, v203
	v_and_b32_e32 v203, 0xffff0000, v203
	v_pk_fma_f32 v[46:47], v[46:47], v[202:203], v[70:71]
	s_nop 0
	global_store_dwordx4 v[192:193], v[44:47], off
	s_waitcnt vmcnt(15)
	v_lshlrev_b32_e32 v186, 16, v210
	v_and_b32_e32 v187, 0xffff0000, v210
	v_pk_fma_f32 v[40:41], v[40:41], v[186:187], v[72:73]
	v_lshlrev_b32_e32 v210, 16, v211
	v_and_b32_e32 v211, 0xffff0000, v211
	v_pk_fma_f32 v[42:43], v[42:43], v[210:211], v[74:75]
	s_nop 0
	global_store_dwordx4 v[192:193], v[40:43], off offset:64
	s_waitcnt vmcnt(15)
	v_lshlrev_b32_e32 v186, 16, v230
	v_and_b32_e32 v187, 0xffff0000, v230
	v_pk_fma_f32 v[36:37], v[36:37], v[186:187], v[106:107]
	v_lshlrev_b32_e32 v230, 16, v231
	v_and_b32_e32 v231, 0xffff0000, v231
	v_pk_fma_f32 v[38:39], v[38:39], v[230:231], v[108:109]
	s_nop 0
	global_store_dwordx4 v[192:193], v[36:39], off offset:128
	s_waitcnt vmcnt(15)
	v_lshlrev_b32_e32 v186, 16, v232
	v_and_b32_e32 v187, 0xffff0000, v232
	v_pk_fma_f32 v[32:33], v[32:33], v[186:187], v[110:111]
	v_lshlrev_b32_e32 v232, 16, v233
	v_and_b32_e32 v233, 0xffff0000, v233
	v_pk_fma_f32 v[34:35], v[34:35], v[232:233], v[112:113]
	s_nop 0
	global_store_dwordx4 v[192:193], v[32:35], off offset:192
	v_add_u32_e32 v114, 0x30000, v204
	v_lshl_add_u64 v[192:193], v[114:115], 0, s[4:5]
	s_waitcnt vmcnt(11)
	v_lshlrev_b32_e32 v186, 16, v234
	v_and_b32_e32 v187, 0xffff0000, v234
	v_pk_fma_f32 v[28:29], v[28:29], v[186:187], v[156:157]
	v_lshlrev_b32_e32 v234, 16, v235
	v_and_b32_e32 v235, 0xffff0000, v235
	v_pk_fma_f32 v[30:31], v[30:31], v[234:235], v[158:159]
	s_nop 0
	global_store_dwordx4 v[192:193], v[28:31], off
	s_waitcnt vmcnt(11)
	v_lshlrev_b32_e32 v186, 16, v236
	v_and_b32_e32 v187, 0xffff0000, v236
	v_pk_fma_f32 v[24:25], v[24:25], v[186:187], v[166:167]
	v_lshlrev_b32_e32 v236, 16, v237
	v_and_b32_e32 v237, 0xffff0000, v237
	v_pk_fma_f32 v[26:27], v[26:27], v[236:237], v[168:169]
	s_nop 0
	global_store_dwordx4 v[192:193], v[24:27], off offset:64
	s_waitcnt vmcnt(11)
	v_lshlrev_b32_e32 v186, 16, v238
	v_and_b32_e32 v187, 0xffff0000, v238
	v_pk_fma_f32 v[20:21], v[20:21], v[186:187], v[178:179]
	v_lshlrev_b32_e32 v238, 16, v239
	v_and_b32_e32 v239, 0xffff0000, v239
	v_pk_fma_f32 v[22:23], v[22:23], v[238:239], v[180:181]
	s_nop 0
	global_store_dwordx4 v[192:193], v[20:23], off offset:128
	s_waitcnt vmcnt(11)
	v_lshlrev_b32_e32 v186, 16, v240
	v_and_b32_e32 v187, 0xffff0000, v240
	v_pk_fma_f32 v[16:17], v[16:17], v[186:187], v[182:183]
	v_lshlrev_b32_e32 v240, 16, v241
	v_and_b32_e32 v241, 0xffff0000, v241
	v_pk_fma_f32 v[18:19], v[18:19], v[240:241], v[184:185]
	s_nop 0
	global_store_dwordx4 v[192:193], v[16:19], off offset:192
	v_add_u32_e32 v114, 0x40000, v204
	v_lshl_add_u64 v[192:193], v[114:115], 0, s[4:5]
	s_waitcnt vmcnt(11)
	v_lshlrev_b32_e32 v186, 16, v242
	v_and_b32_e32 v187, 0xffff0000, v242
	v_pk_fma_f32 v[12:13], v[12:13], v[186:187], v[212:213]
	v_lshlrev_b32_e32 v242, 16, v243
	v_and_b32_e32 v243, 0xffff0000, v243
	v_pk_fma_f32 v[14:15], v[14:15], v[242:243], v[214:215]
	s_nop 0
	global_store_dwordx4 v[192:193], v[12:15], off
	s_waitcnt vmcnt(11)
	v_lshlrev_b32_e32 v186, 16, v244
	v_and_b32_e32 v187, 0xffff0000, v244
	v_pk_fma_f32 v[8:9], v[8:9], v[186:187], v[216:217]
	v_lshlrev_b32_e32 v244, 16, v245
	v_and_b32_e32 v245, 0xffff0000, v245
	v_pk_fma_f32 v[10:11], v[10:11], v[244:245], v[218:219]
	s_nop 0
	global_store_dwordx4 v[192:193], v[8:11], off offset:64
	s_waitcnt vmcnt(11)
	v_lshlrev_b32_e32 v186, 16, v246
	v_and_b32_e32 v187, 0xffff0000, v246
	v_pk_fma_f32 v[4:5], v[4:5], v[186:187], v[220:221]
	v_lshlrev_b32_e32 v246, 16, v247
	v_and_b32_e32 v247, 0xffff0000, v247
	v_pk_fma_f32 v[6:7], v[6:7], v[246:247], v[222:223]
	s_nop 0
	global_store_dwordx4 v[192:193], v[4:7], off offset:128
	s_waitcnt vmcnt(11)
	v_lshlrev_b32_e32 v186, 16, v248
	v_and_b32_e32 v187, 0xffff0000, v248
	v_pk_fma_f32 v[0:1], v[0:1], v[186:187], v[224:225]
	v_lshlrev_b32_e32 v248, 16, v249
	v_and_b32_e32 v249, 0xffff0000, v249
	v_pk_fma_f32 v[2:3], v[2:3], v[248:249], v[226:227]
	s_nop 0
	global_store_dwordx4 v[192:193], v[0:3], off offset:192
	s_nop 1
	v_lshl_add_u64 v[0:1], v[102:103], 0, v[96:97]
	v_lshl_add_u64 v[2:3], v[0:1], 0, s[36:37]
	s_mov_b64 s[36:37], 0x65000
	global_load_lds_dwordx4 v[2:3], off
	v_lshl_add_u64 v[2:3], v[0:1], 0, s[36:37]
	s_mov_b32 m0, s11
	s_mov_b64 s[36:37], 0xc9000
	v_readfirstlane_b32 s11, v132
	global_load_lds_dwordx4 v[2:3], off
	v_lshl_add_u64 v[2:3], v[0:1], 0, s[36:37]
	s_mov_b32 m0, s11
	s_mov_b64 s[36:37], 0x12d000
	v_readfirstlane_b32 s11, v131
	global_load_lds_dwordx4 v[2:3], off
	v_lshl_add_u64 v[2:3], v[0:1], 0, s[36:37]
	s_mov_b32 m0, s11
	s_mov_b64 s[36:37], 0x191000
	v_readfirstlane_b32 s11, v130
	global_load_lds_dwordx4 v[2:3], off
	v_lshl_add_u64 v[0:1], v[0:1], 0, s[36:37]
	s_mov_b32 m0, s11
	s_nop 0
	global_load_lds_dwordx4 v[0:1], off
	v_lshl_add_u64 v[0:1], v[88:89], 0, s[8:9]
	v_readfirstlane_b32 s8, v129
	s_mov_b32 m0, s8
	v_readfirstlane_b32 s8, v128
	global_load_lds_dwordx4 v[0:1], off
	v_lshl_add_u64 v[2:3], v[0:1], 0, s[40:41]
	s_mov_b32 m0, s8
	s_mov_b64 s[8:9], 0x20000
	global_load_lds_dwordx4 v[2:3], off
	v_lshl_add_u64 v[2:3], v[0:1], 0, s[8:9]
	v_readfirstlane_b32 s8, v127
	s_mov_b32 m0, s8
	s_mov_b64 s[8:9], 0x30000
	v_lshl_add_u64 v[0:1], v[0:1], 0, s[8:9]
	v_readfirstlane_b32 s8, v126
	global_load_lds_dwordx4 v[2:3], off
	s_mov_b32 m0, s8
	s_mov_b64 s[8:9], 0
	global_load_lds_dwordx4 v[0:1], off
	s_waitcnt vmcnt(0)
	v_mov_b32_e32 v0, 0
	v_mov_b32_e32 v1, v0
	v_mov_b32_e32 v2, v0
	v_mov_b32_e32 v3, v0
	v_mov_b32_e32 v4, v0
	v_mov_b32_e32 v5, v0
	v_mov_b32_e32 v6, v0
	v_mov_b32_e32 v7, v0
	v_mov_b32_e32 v8, v0
	v_mov_b32_e32 v9, v0
	v_mov_b32_e32 v10, v0
	v_mov_b32_e32 v11, v0
	v_mov_b32_e32 v12, v0
	v_mov_b32_e32 v13, v0
	v_mov_b32_e32 v14, v0
	v_mov_b32_e32 v15, v0
	v_mov_b32_e32 v16, v0
	v_mov_b32_e32 v17, v0
	v_mov_b32_e32 v18, v0
	v_mov_b32_e32 v19, v0
	v_mov_b32_e32 v20, v0
	v_mov_b32_e32 v21, v0
	v_mov_b32_e32 v22, v0
	v_mov_b32_e32 v23, v0
	v_mov_b32_e32 v24, v0
	v_mov_b32_e32 v25, v0
	v_mov_b32_e32 v26, v0
	v_mov_b32_e32 v27, v0
	v_mov_b32_e32 v28, v0
	v_mov_b32_e32 v29, v0
	v_mov_b32_e32 v30, v0
	v_mov_b32_e32 v31, v0
	v_mov_b32_e32 v32, v0
	v_mov_b32_e32 v33, v0
	v_mov_b32_e32 v34, v0
	v_mov_b32_e32 v35, v0
	v_mov_b32_e32 v36, v0
	v_mov_b32_e32 v37, v0
	v_mov_b32_e32 v38, v0
	v_mov_b32_e32 v39, v0
	v_mov_b32_e32 v40, v0
	v_mov_b32_e32 v41, v0
	v_mov_b32_e32 v42, v0
	v_mov_b32_e32 v43, v0
	v_mov_b32_e32 v44, v0
	v_mov_b32_e32 v45, v0
	v_mov_b32_e32 v46, v0
	v_mov_b32_e32 v47, v0
	v_mov_b32_e32 v48, v0
	v_mov_b32_e32 v49, v0
	v_mov_b32_e32 v50, v0
	v_mov_b32_e32 v51, v0
	v_mov_b32_e32 v52, v0
	v_mov_b32_e32 v53, v0
	v_mov_b32_e32 v54, v0
	v_mov_b32_e32 v55, v0
	v_mov_b32_e32 v56, v0
	v_mov_b32_e32 v57, v0
	v_mov_b32_e32 v58, v0
	v_mov_b32_e32 v59, v0
	v_mov_b32_e32 v60, v0
	v_mov_b32_e32 v61, v0
	v_mov_b32_e32 v62, v0
	v_mov_b32_e32 v63, v0
	v_mov_b32_e32 v64, v0
	v_mov_b32_e32 v65, v0
	v_mov_b32_e32 v66, v0
	v_mov_b32_e32 v67, v0
	v_mov_b32_e32 v68, v0
	v_mov_b32_e32 v69, v0
	v_mov_b32_e32 v70, v0
	v_mov_b32_e32 v71, v0
	v_mov_b32_e32 v72, v0
	v_mov_b32_e32 v73, v0
	v_mov_b32_e32 v74, v0
	v_mov_b32_e32 v75, v0
	v_mov_b32_e32 v76, v0
	v_mov_b32_e32 v77, v0
	v_mov_b32_e32 v78, v0
	v_mov_b32_e32 v79, v0
	s_waitcnt vmcnt(0) lgkmcnt(0)
	s_barrier
.LBB0_90:
	s_add_i32 s11, s10, 1
	s_bitcmp1_b32 s11, 0
	s_cselect_b32 s35, 0x9000, 0
	v_add_u32_e32 v96, s35, v81
	v_lshl_add_u64 v[102:103], v[94:95], 0, s[8:9]
	s_mov_b64 s[36:37], 0x6182080
	v_readfirstlane_b32 s35, v96
	v_add_u32_e32 v106, 0x1000, v96
	v_lshl_add_u64 v[104:105], v[102:103], 0, s[36:37]
	s_mov_b32 m0, s35
	s_mov_b64 s[36:37], 0x61e6080
	v_readfirstlane_b32 s35, v106
	v_add_u32_e32 v106, 0x2000, v96
	global_load_lds_dwordx4 v[104:105], off
	v_lshl_add_u64 v[104:105], v[102:103], 0, s[36:37]
	s_mov_b32 m0, s35
	s_mov_b64 s[36:37], 0x624a080
	v_readfirstlane_b32 s35, v106
	v_add_u32_e32 v106, 0x3000, v96
	global_load_lds_dwordx4 v[104:105], off
	v_lshl_add_u64 v[104:105], v[102:103], 0, s[36:37]
	s_mov_b32 m0, s35
	s_mov_b64 s[36:37], 0x62ae080
	v_readfirstlane_b32 s35, v106
	global_load_lds_dwordx4 v[104:105], off
	v_lshl_add_u64 v[104:105], v[102:103], 0, s[36:37]
	s_mov_b32 m0, s35
	s_mov_b64 s[36:37], 0x6312080
	global_load_lds_dwordx4 v[104:105], off
	v_add_u32_e32 v104, 0x4000, v96
	v_lshl_add_u64 v[102:103], v[102:103], 0, s[36:37]
	v_readfirstlane_b32 s35, v104
	s_mov_b32 m0, s35
	v_add_u32_e32 v106, 0x5000, v96
	global_load_lds_dwordx4 v[102:103], off
	v_lshl_add_u64 v[102:103], v[100:101], 0, s[8:9]
	s_mov_b64 s[36:37], 0x14931080
	v_readfirstlane_b32 s35, v106
	v_add_u32_e32 v106, 0x6000, v96
	v_lshl_add_u64 v[104:105], v[102:103], 0, s[36:37]
	s_mov_b32 m0, s35
	s_mov_b64 s[36:37], 0x14941080
	v_readfirstlane_b32 s35, v106
	v_add_u32_e32 v106, 0x7000, v96
	global_load_lds_dwordx4 v[104:105], off
	v_lshl_add_u64 v[104:105], v[102:103], 0, s[36:37]
	s_mov_b32 m0, s35
	s_mov_b64 s[36:37], 0x14951080
	v_readfirstlane_b32 s35, v106
	v_add_u32_e32 v96, 0x8000, v96
	global_load_lds_dwordx4 v[104:105], off
	v_lshl_add_u64 v[104:105], v[102:103], 0, s[36:37]
	s_mov_b32 m0, s35
	s_mov_b64 s[36:37], 0x14961080
	v_readfirstlane_b32 s35, v96
	global_load_lds_dwordx4 v[104:105], off
	v_lshl_add_u64 v[102:103], v[102:103], 0, s[36:37]
	s_mov_b32 m0, s35
	s_bitcmp1_b32 s10, 0
	global_load_lds_dwordx4 v[102:103], off
	s_cselect_b32 s10, 0x9000, 0
	s_add_i32 s10, s10, 0
	v_add_u32_e32 v96, s10, v116
	v_add_u32_e32 v114, v96, v117
	ds_read_b128 v[102:105], v114
	ds_read_b128 v[106:109], v114 offset:2048
	ds_read_b128 v[110:113], v114 offset:4096
	ds_read_b128 v[126:129], v114 offset:6144
	v_add_u32_e32 v96, v96, v118
	ds_read_b128 v[130:133], v114 offset:8192
	ds_read_b128 v[156:159], v96 offset:20480
	ds_read_b128 v[166:169], v96 offset:22528
	ds_read_b128 v[178:181], v96 offset:24576
	ds_read_b128 v[182:185], v96 offset:26624
	v_add_u32_e32 v210, s10, v119
	v_add_u32_e32 v211, v210, v117
	ds_read_b128 v[212:215], v211
	ds_read_b128 v[216:219], v211 offset:2048
	ds_read_b128 v[220:223], v211 offset:4096
	ds_read_b128 v[224:227], v211 offset:6144
	v_add_u32_e32 v228, v210, v118
	ds_read_b128 v[230:233], v211 offset:8192
	ds_read_b128 v[234:237], v228 offset:20480
	ds_read_b128 v[238:241], v228 offset:22528
	ds_read_b128 v[242:245], v228 offset:24576
	ds_read_b128 v[246:249], v228 offset:26624
	s_setprio 1
	s_waitcnt lgkmcnt(9)
	v_mfma_f32_16x16x32_bf16 v[76:79], v[156:159], v[102:105], v[76:79]
	v_mfma_f32_16x16x32_bf16 v[72:75], v[166:169], v[102:105], v[72:75]
	v_mfma_f32_16x16x32_bf16 v[68:71], v[178:181], v[102:105], v[68:71]
	v_mfma_f32_16x16x32_bf16 v[64:67], v[182:185], v[102:105], v[64:67]
	v_mfma_f32_16x16x32_bf16 v[60:63], v[156:159], v[106:109], v[60:63]
	v_mfma_f32_16x16x32_bf16 v[56:59], v[166:169], v[106:109], v[56:59]
	v_mfma_f32_16x16x32_bf16 v[52:55], v[178:181], v[106:109], v[52:55]
	v_mfma_f32_16x16x32_bf16 v[48:51], v[182:185], v[106:109], v[48:51]
	v_mfma_f32_16x16x32_bf16 v[44:47], v[156:159], v[110:113], v[44:47]
	v_mfma_f32_16x16x32_bf16 v[40:43], v[166:169], v[110:113], v[40:43]
	v_mfma_f32_16x16x32_bf16 v[36:39], v[178:181], v[110:113], v[36:39]
	v_mfma_f32_16x16x32_bf16 v[32:35], v[182:185], v[110:113], v[32:35]
	v_mfma_f32_16x16x32_bf16 v[28:31], v[156:159], v[126:129], v[28:31]
	v_mfma_f32_16x16x32_bf16 v[24:27], v[166:169], v[126:129], v[24:27]
	v_mfma_f32_16x16x32_bf16 v[20:23], v[178:181], v[126:129], v[20:23]
	v_mfma_f32_16x16x32_bf16 v[16:19], v[182:185], v[126:129], v[16:19]
	v_mfma_f32_16x16x32_bf16 v[12:15], v[156:159], v[130:133], v[12:15]
	v_mfma_f32_16x16x32_bf16 v[8:11], v[166:169], v[130:133], v[8:11]
	v_mfma_f32_16x16x32_bf16 v[4:7], v[178:181], v[130:133], v[4:7]
	v_mfma_f32_16x16x32_bf16 v[0:3], v[182:185], v[130:133], v[0:3]
	s_waitcnt lgkmcnt(0)
	v_mfma_f32_16x16x32_bf16 v[76:79], v[234:237], v[212:215], v[76:79]
	v_mfma_f32_16x16x32_bf16 v[72:75], v[238:241], v[212:215], v[72:75]
	v_mfma_f32_16x16x32_bf16 v[68:71], v[242:245], v[212:215], v[68:71]
	v_mfma_f32_16x16x32_bf16 v[64:67], v[246:249], v[212:215], v[64:67]
	v_mfma_f32_16x16x32_bf16 v[60:63], v[234:237], v[216:219], v[60:63]
	v_mfma_f32_16x16x32_bf16 v[56:59], v[238:241], v[216:219], v[56:59]
	v_mfma_f32_16x16x32_bf16 v[52:55], v[242:245], v[216:219], v[52:55]
	v_mfma_f32_16x16x32_bf16 v[48:51], v[246:249], v[216:219], v[48:51]
	v_mfma_f32_16x16x32_bf16 v[44:47], v[234:237], v[220:223], v[44:47]
	v_mfma_f32_16x16x32_bf16 v[40:43], v[238:241], v[220:223], v[40:43]
	v_mfma_f32_16x16x32_bf16 v[36:39], v[242:245], v[220:223], v[36:39]
	v_mfma_f32_16x16x32_bf16 v[32:35], v[246:249], v[220:223], v[32:35]
	v_mfma_f32_16x16x32_bf16 v[28:31], v[234:237], v[224:227], v[28:31]
	v_mfma_f32_16x16x32_bf16 v[24:27], v[238:241], v[224:227], v[24:27]
	v_mfma_f32_16x16x32_bf16 v[20:23], v[242:245], v[224:227], v[20:23]
	v_mfma_f32_16x16x32_bf16 v[16:19], v[246:249], v[224:227], v[16:19]
	v_mfma_f32_16x16x32_bf16 v[12:15], v[234:237], v[230:233], v[12:15]
	v_mfma_f32_16x16x32_bf16 v[8:11], v[238:241], v[230:233], v[8:11]
	v_mfma_f32_16x16x32_bf16 v[4:7], v[242:245], v[230:233], v[4:7]
	v_mfma_f32_16x16x32_bf16 v[0:3], v[246:249], v[230:233], v[0:3]
	s_setprio 0
	s_waitcnt vmcnt(0)
	s_add_u32 s8, s8, 0x80
	s_addc_u32 s9, s9, 0
	s_cmpk_lg_i32 s8, 0x780
	s_mov_b32 s10, s11
	s_waitcnt vmcnt(0)
	s_barrier
	s_cbranch_scc1 .LBB0_90
	v_ashrrev_i32_e32 v242, 7, v176
	v_mov_b32_e32 v243, 0x50
	v_and_or_b32 v248, v176, 15, s12
	v_mad_u32_u24 v248, v242, v243, v248
	v_and_b32_e32 v242, 64, v176
	v_lshrrev_b32_e32 v243, 2, v176
	v_and_b32_e32 v243, 12, v243
	v_or3_b32 v249, v242, v243, s13
	v_mul_u32_u24_e32 v244, 0x3200, v248
	v_lshl_add_u32 v244, v249, 1, v244
	v_add_u32_e32 v244, 0x2800, v244
	v_mov_b32_e32 v247, 0
	v_mov_b32_e32 v246, v244
	v_lshl_add_u64 v[248:249], v[246:247], 0, s[0:1]
	global_load_dwordx2 v[212:213], v[248:249], off
	global_load_dwordx2 v[214:215], v[248:249], off offset:32
	global_load_dwordx2 v[216:217], v[248:249], off offset:64
	global_load_dwordx2 v[218:219], v[248:249], off offset:96
	v_add_u32_e32 v246, 0x32000, v244
	v_lshl_add_u64 v[248:249], v[246:247], 0, s[0:1]
	global_load_dwordx2 v[220:221], v[248:249], off
	global_load_dwordx2 v[222:223], v[248:249], off offset:32
	global_load_dwordx2 v[224:225], v[248:249], off offset:64
	global_load_dwordx2 v[226:227], v[248:249], off offset:96
	v_add_u32_e32 v246, 0x64000, v244
	v_lshl_add_u64 v[248:249], v[246:247], 0, s[0:1]
	global_load_dwordx2 v[202:203], v[248:249], off
	global_load_dwordx2 v[210:211], v[248:249], off offset:32
	global_load_dwordx2 v[230:231], v[248:249], off offset:64
	global_load_dwordx2 v[232:233], v[248:249], off offset:96
	v_add_u32_e32 v246, 0x96000, v244
	v_lshl_add_u64 v[248:249], v[246:247], 0, s[0:1]
	global_load_dwordx2 v[234:235], v[248:249], off
	global_load_dwordx2 v[236:237], v[248:249], off offset:32
	global_load_dwordx2 v[238:239], v[248:249], off offset:64
	global_load_dwordx2 v[240:241], v[248:249], off offset:96
	v_add_u32_e32 v246, 0xc8000, v244
	v_lshl_add_u64 v[248:249], v[246:247], 0, s[0:1]
	global_load_dwordx2 v[242:243], v[248:249], off
	global_load_dwordx2 v[244:245], v[248:249], off offset:32
	global_load_dwordx2 v[246:247], v[248:249], off offset:64
	global_load_dwordx2 v[248:249], v[248:249], off offset:96
	ds_read_b128 v[100:103], v122 offset:63488
	ds_read_b128 v[104:107], v122 offset:61440
	ds_read_b128 v[108:111], v122 offset:59392
	ds_read_b128 v[112:115], v122 offset:57344
	ds_read_b128 v[126:129], v123 offset:45056
	ds_read_b128 v[130:133], v123 offset:43008
	ds_read_b128 v[156:159], v123 offset:40960
	ds_read_b128 v[166:169], v123 offset:38912
	ds_read_b128 v[178:181], v123 offset:36864
	s_setprio 1
	s_waitcnt lgkmcnt(0)
	v_mfma_f32_16x16x32_bf16 v[76:79], v[112:115], v[178:181], v[76:79]
	v_mfma_f32_16x16x32_bf16 v[72:75], v[108:111], v[178:181], v[72:75]
	v_mfma_f32_16x16x32_bf16 v[68:71], v[104:107], v[178:181], v[68:71]
	v_mfma_f32_16x16x32_bf16 v[64:67], v[100:103], v[178:181], v[64:67]
	v_mfma_f32_16x16x32_bf16 v[60:63], v[112:115], v[166:169], v[60:63]
	v_mfma_f32_16x16x32_bf16 v[56:59], v[108:111], v[166:169], v[56:59]
	v_mfma_f32_16x16x32_bf16 v[52:55], v[104:107], v[166:169], v[52:55]
	v_mfma_f32_16x16x32_bf16 v[48:51], v[100:103], v[166:169], v[48:51]
	v_mfma_f32_16x16x32_bf16 v[44:47], v[112:115], v[156:159], v[44:47]
	v_mfma_f32_16x16x32_bf16 v[40:43], v[108:111], v[156:159], v[40:43]
	v_mfma_f32_16x16x32_bf16 v[36:39], v[104:107], v[156:159], v[36:39]
	v_mfma_f32_16x16x32_bf16 v[32:35], v[100:103], v[156:159], v[32:35]
	v_mfma_f32_16x16x32_bf16 v[28:31], v[112:115], v[130:133], v[28:31]
	v_mfma_f32_16x16x32_bf16 v[24:27], v[108:111], v[130:133], v[24:27]
	v_mfma_f32_16x16x32_bf16 v[20:23], v[104:107], v[130:133], v[20:23]
	v_mfma_f32_16x16x32_bf16 v[16:19], v[100:103], v[130:133], v[16:19]
	v_mfma_f32_16x16x32_bf16 v[12:15], v[112:115], v[126:129], v[12:15]
	v_mfma_f32_16x16x32_bf16 v[8:11], v[108:111], v[126:129], v[8:11]
	v_mfma_f32_16x16x32_bf16 v[4:7], v[104:107], v[126:129], v[4:7]
	v_mfma_f32_16x16x32_bf16 v[0:3], v[100:103], v[126:129], v[0:3]
	s_setprio 0
	ds_read_b128 v[100:103], v124 offset:36864
	ds_read_b128 v[104:107], v124 offset:38912
	ds_read_b128 v[108:111], v124 offset:40960
	ds_read_b128 v[112:115], v124 offset:43008
	ds_read_b128 v[126:129], v124 offset:45056
	ds_read_b128 v[130:133], v125 offset:57344
	ds_read_b128 v[156:159], v125 offset:59392
	ds_read_b128 v[166:169], v125 offset:61440
	ds_read_b128 v[122:125], v125 offset:63488
	s_setprio 1
	s_waitcnt lgkmcnt(3)
	v_mfma_f32_16x16x32_bf16 v[178:181], v[130:133], v[100:103], v[76:79]
	s_waitcnt lgkmcnt(2)
	v_mfma_f32_16x16x32_bf16 v[72:75], v[156:159], v[100:103], v[72:75]
	s_waitcnt lgkmcnt(1)
	v_mfma_f32_16x16x32_bf16 v[68:71], v[166:169], v[100:103], v[68:71]
	s_waitcnt lgkmcnt(0)
	v_mfma_f32_16x16x32_bf16 v[64:67], v[122:125], v[100:103], v[64:67]
	v_mfma_f32_16x16x32_bf16 v[60:63], v[130:133], v[104:107], v[60:63]
	v_mfma_f32_16x16x32_bf16 v[56:59], v[156:159], v[104:107], v[56:59]
	v_mfma_f32_16x16x32_bf16 v[52:55], v[166:169], v[104:107], v[52:55]
	v_mfma_f32_16x16x32_bf16 v[48:51], v[122:125], v[104:107], v[48:51]
	v_mfma_f32_16x16x32_bf16 v[44:47], v[130:133], v[108:111], v[44:47]
	v_mfma_f32_16x16x32_bf16 v[40:43], v[156:159], v[108:111], v[40:43]
	v_mfma_f32_16x16x32_bf16 v[36:39], v[166:169], v[108:111], v[36:39]
	v_mfma_f32_16x16x32_bf16 v[32:35], v[122:125], v[108:111], v[32:35]
	v_mfma_f32_16x16x32_bf16 v[28:31], v[130:133], v[112:115], v[28:31]
	v_mfma_f32_16x16x32_bf16 v[24:27], v[156:159], v[112:115], v[24:27]
	v_mfma_f32_16x16x32_bf16 v[20:23], v[166:169], v[112:115], v[20:23]
	v_mfma_f32_16x16x32_bf16 v[16:19], v[122:125], v[112:115], v[16:19]
	v_mfma_f32_16x16x32_bf16 v[12:15], v[130:133], v[126:129], v[12:15]
	v_mfma_f32_16x16x32_bf16 v[8:11], v[156:159], v[126:129], v[8:11]
	v_mfma_f32_16x16x32_bf16 v[4:7], v[166:169], v[126:129], v[4:7]
	v_mfma_f32_16x16x32_bf16 v[0:3], v[122:125], v[126:129], v[0:3]
	s_setprio 0
	v_mov_b32_e32 v76, v97
	s_waitcnt vmcnt(0)
	s_barrier
	v_ashrrev_i32_e32 v198, 7, v176
	v_mov_b32_e32 v199, 0x50
	v_and_or_b32 v206, v176, 15, s12
	v_mad_u32_u24 v206, v198, v199, v206
	v_and_b32_e32 v198, 64, v176
	v_lshrrev_b32_e32 v199, 2, v176
	v_and_b32_e32 v199, 12, v199
	v_or3_b32 v207, v198, v199, s13
	v_lshlrev_b32_e32 v194, 12, v206
	v_lshl_add_u32 v194, v207, 2, v194
	v_lshlrev_b32_e32 v195, 11, v206
	v_lshl_add_u32 v195, v207, 1, v195
	v_mov_b32_e32 v115, 0
	v_mov_b32_e32 v114, v194
	v_lshl_add_u64 v[206:207], v[114:115], 0, s[4:5]
	global_load_dwordx4 v[76:79], v[206:207], off
	global_load_dwordx4 v[106:109], v[206:207], off offset:64
	global_load_dwordx4 v[110:113], v[206:207], off offset:128
	global_load_dwordx4 v[122:125], v[206:207], off offset:192
	v_add_u32_e32 v114, 0x10000, v194
	v_lshl_add_u64 v[206:207], v[114:115], 0, s[4:5]
	global_load_dwordx4 v[126:129], v[206:207], off
	global_load_dwordx4 v[130:133], v[206:207], off offset:64
	global_load_dwordx4 v[156:159], v[206:207], off offset:128
	global_load_dwordx4 v[166:169], v[206:207], off offset:192
	v_mov_b32_e32 v114, v195
	v_lshl_add_u64 v[200:201], v[114:115], 0, s[6:7]
	s_waitcnt vmcnt(7)
	v_lshlrev_b32_e32 v198, 16, v212
	v_and_b32_e32 v199, 0xffff0000, v212
	v_pk_fma_f32 v[178:179], v[178:179], v[198:199], v[76:77]
	v_lshlrev_b32_e32 v212, 16, v213
	v_and_b32_e32 v213, 0xffff0000, v213
	v_pk_fma_f32 v[180:181], v[180:181], v[212:213], v[78:79]
	s_nop 0
	v_bfe_u32 v198, v178, 16, 1
	v_add3_u32 v178, v178, v198, s33
	v_bfe_u32 v198, v179, 16, 1
	v_add3_u32 v179, v179, v198, s33
	v_bfe_u32 v198, v180, 16, 1
	v_add3_u32 v180, v180, v198, s33
	v_bfe_u32 v198, v181, 16, 1
	v_add3_u32 v181, v181, v198, s33
	v_perm_b32 v178, v179, v178, s96
	v_perm_b32 v179, v181, v180, s96
	global_store_dwordx2 v[200:201], v[178:179], off
	s_waitcnt vmcnt(7)
	v_lshlrev_b32_e32 v198, 16, v214
	v_and_b32_e32 v199, 0xffff0000, v214
	v_pk_fma_f32 v[72:73], v[72:73], v[198:199], v[106:107]
	v_lshlrev_b32_e32 v214, 16, v215
	v_and_b32_e32 v215, 0xffff0000, v215
	v_pk_fma_f32 v[74:75], v[74:75], v[214:215], v[108:109]
	s_nop 0
	v_bfe_u32 v198, v72, 16, 1
	v_add3_u32 v72, v72, v198, s33
	v_bfe_u32 v198, v73, 16, 1
	v_add3_u32 v73, v73, v198, s33
	v_bfe_u32 v198, v74, 16, 1
	v_add3_u32 v74, v74, v198, s33
	v_bfe_u32 v198, v75, 16, 1
	v_add3_u32 v75, v75, v198, s33
	v_perm_b32 v72, v73, v72, s96
	v_perm_b32 v73, v75, v74, s96
	global_store_dwordx2 v[200:201], v[72:73], off offset:32
	s_waitcnt vmcnt(7)
	v_lshlrev_b32_e32 v198, 16, v216
	v_and_b32_e32 v199, 0xffff0000, v216
	v_pk_fma_f32 v[68:69], v[68:69], v[198:199], v[110:111]
	v_lshlrev_b32_e32 v216, 16, v217
	v_and_b32_e32 v217, 0xffff0000, v217
	v_pk_fma_f32 v[70:71], v[70:71], v[216:217], v[112:113]
	s_nop 0
	v_bfe_u32 v198, v68, 16, 1
	v_add3_u32 v68, v68, v198, s33
	v_bfe_u32 v198, v69, 16, 1
	v_add3_u32 v69, v69, v198, s33
	v_bfe_u32 v198, v70, 16, 1
	v_add3_u32 v70, v70, v198, s33
	v_bfe_u32 v198, v71, 16, 1
	v_add3_u32 v71, v71, v198, s33
	v_perm_b32 v68, v69, v68, s96
	v_perm_b32 v69, v71, v70, s96
	global_store_dwordx2 v[200:201], v[68:69], off offset:64
	s_waitcnt vmcnt(7)
	v_lshlrev_b32_e32 v198, 16, v218
	v_and_b32_e32 v199, 0xffff0000, v218
	v_pk_fma_f32 v[64:65], v[64:65], v[198:199], v[122:123]
	v_lshlrev_b32_e32 v218, 16, v219
	v_and_b32_e32 v219, 0xffff0000, v219
	v_pk_fma_f32 v[66:67], v[66:67], v[218:219], v[124:125]
	s_nop 0
	v_bfe_u32 v198, v64, 16, 1
	v_add3_u32 v64, v64, v198, s33
	v_bfe_u32 v198, v65, 16, 1
	v_add3_u32 v65, v65, v198, s33
	v_bfe_u32 v198, v66, 16, 1
	v_add3_u32 v66, v66, v198, s33
	v_bfe_u32 v198, v67, 16, 1
	v_add3_u32 v67, v67, v198, s33
	v_perm_b32 v64, v65, v64, s96
	v_perm_b32 v65, v67, v66, s96
	global_store_dwordx2 v[200:201], v[64:65], off offset:96
	v_add_u32_e32 v114, 0x20000, v194
	v_lshl_add_u64 v[206:207], v[114:115], 0, s[4:5]
	global_load_dwordx4 v[76:79], v[206:207], off
	global_load_dwordx4 v[106:109], v[206:207], off offset:64
	global_load_dwordx4 v[110:113], v[206:207], off offset:128
	global_load_dwordx4 v[122:125], v[206:207], off offset:192
	v_add_u32_e32 v114, 0x8000, v195
	v_lshl_add_u64 v[200:201], v[114:115], 0, s[6:7]
	s_waitcnt vmcnt(11)
	v_lshlrev_b32_e32 v198, 16, v220
	v_and_b32_e32 v199, 0xffff0000, v220
	v_pk_fma_f32 v[60:61], v[60:61], v[198:199], v[126:127]
	v_lshlrev_b32_e32 v220, 16, v221
	v_and_b32_e32 v221, 0xffff0000, v221
	v_pk_fma_f32 v[62:63], v[62:63], v[220:221], v[128:129]
	s_nop 0
	v_bfe_u32 v198, v60, 16, 1
	v_add3_u32 v60, v60, v198, s33
	v_bfe_u32 v198, v61, 16, 1
	v_add3_u32 v61, v61, v198, s33
	v_bfe_u32 v198, v62, 16, 1
	v_add3_u32 v62, v62, v198, s33
	v_bfe_u32 v198, v63, 16, 1
	v_add3_u32 v63, v63, v198, s33
	v_perm_b32 v60, v61, v60, s96
	v_perm_b32 v61, v63, v62, s96
	global_store_dwordx2 v[200:201], v[60:61], off
	s_waitcnt vmcnt(11)
	v_lshlrev_b32_e32 v198, 16, v222
	v_and_b32_e32 v199, 0xffff0000, v222
	v_pk_fma_f32 v[56:57], v[56:57], v[198:199], v[130:131]
	v_lshlrev_b32_e32 v222, 16, v223
	v_and_b32_e32 v223, 0xffff0000, v223
	v_pk_fma_f32 v[58:59], v[58:59], v[222:223], v[132:133]
	s_nop 0
	v_bfe_u32 v198, v56, 16, 1
	v_add3_u32 v56, v56, v198, s33
	v_bfe_u32 v198, v57, 16, 1
	v_add3_u32 v57, v57, v198, s33
	v_bfe_u32 v198, v58, 16, 1
	v_add3_u32 v58, v58, v198, s33
	v_bfe_u32 v198, v59, 16, 1
	v_add3_u32 v59, v59, v198, s33
	v_perm_b32 v56, v57, v56, s96
	v_perm_b32 v57, v59, v58, s96
	global_store_dwordx2 v[200:201], v[56:57], off offset:32
	s_waitcnt vmcnt(11)
	v_lshlrev_b32_e32 v198, 16, v224
	v_and_b32_e32 v199, 0xffff0000, v224
	v_pk_fma_f32 v[52:53], v[52:53], v[198:199], v[156:157]
	v_lshlrev_b32_e32 v224, 16, v225
	v_and_b32_e32 v225, 0xffff0000, v225
	v_pk_fma_f32 v[54:55], v[54:55], v[224:225], v[158:159]
	s_nop 0
	v_bfe_u32 v198, v52, 16, 1
	v_add3_u32 v52, v52, v198, s33
	v_bfe_u32 v198, v53, 16, 1
	v_add3_u32 v53, v53, v198, s33
	v_bfe_u32 v198, v54, 16, 1
	v_add3_u32 v54, v54, v198, s33
	v_bfe_u32 v198, v55, 16, 1
	v_add3_u32 v55, v55, v198, s33
	v_perm_b32 v52, v53, v52, s96
	v_perm_b32 v53, v55, v54, s96
	global_store_dwordx2 v[200:201], v[52:53], off offset:64
	s_waitcnt vmcnt(11)
	v_lshlrev_b32_e32 v198, 16, v226
	v_and_b32_e32 v199, 0xffff0000, v226
	v_pk_fma_f32 v[48:49], v[48:49], v[198:199], v[166:167]
	v_lshlrev_b32_e32 v226, 16, v227
	v_and_b32_e32 v227, 0xffff0000, v227
	v_pk_fma_f32 v[50:51], v[50:51], v[226:227], v[168:169]
	s_nop 0
	v_bfe_u32 v198, v48, 16, 1
	v_add3_u32 v48, v48, v198, s33
	v_bfe_u32 v198, v49, 16, 1
	v_add3_u32 v49, v49, v198, s33
	v_bfe_u32 v198, v50, 16, 1
	v_add3_u32 v50, v50, v198, s33
	v_bfe_u32 v198, v51, 16, 1
	v_add3_u32 v51, v51, v198, s33
	v_perm_b32 v48, v49, v48, s96
	v_perm_b32 v49, v51, v50, s96
	global_store_dwordx2 v[200:201], v[48:49], off offset:96
	v_add_u32_e32 v114, 0x30000, v194
	v_lshl_add_u64 v[206:207], v[114:115], 0, s[4:5]
	global_load_dwordx4 v[126:129], v[206:207], off
	global_load_dwordx4 v[130:133], v[206:207], off offset:64
	global_load_dwordx4 v[156:159], v[206:207], off offset:128
	global_load_dwordx4 v[166:169], v[206:207], off offset:192
	v_add_u32_e32 v114, 0x40000, v194
	v_lshl_add_u64 v[206:207], v[114:115], 0, s[4:5]
	global_load_dwordx4 v[212:215], v[206:207], off
	global_load_dwordx4 v[216:219], v[206:207], off offset:64
	global_load_dwordx4 v[220:223], v[206:207], off offset:128
	global_load_dwordx4 v[224:227], v[206:207], off offset:192
	v_add_u32_e32 v114, 0x10000, v195
	v_lshl_add_u64 v[200:201], v[114:115], 0, s[6:7]
	s_waitcnt vmcnt(15)
	v_lshlrev_b32_e32 v198, 16, v202
	v_and_b32_e32 v199, 0xffff0000, v202
	v_pk_fma_f32 v[44:45], v[44:45], v[198:199], v[76:77]
	v_lshlrev_b32_e32 v202, 16, v203
	v_and_b32_e32 v203, 0xffff0000, v203
	v_pk_fma_f32 v[46:47], v[46:47], v[202:203], v[78:79]
	s_nop 0
	v_bfe_u32 v198, v44, 16, 1
	v_add3_u32 v44, v44, v198, s33
	v_bfe_u32 v198, v45, 16, 1
	v_add3_u32 v45, v45, v198, s33
	v_bfe_u32 v198, v46, 16, 1
	v_add3_u32 v46, v46, v198, s33
	v_bfe_u32 v198, v47, 16, 1
	v_add3_u32 v47, v47, v198, s33
	v_perm_b32 v44, v45, v44, s96
	v_perm_b32 v45, v47, v46, s96
	global_store_dwordx2 v[200:201], v[44:45], off
	s_waitcnt vmcnt(15)
	v_lshlrev_b32_e32 v198, 16, v210
	v_and_b32_e32 v199, 0xffff0000, v210
	v_pk_fma_f32 v[40:41], v[40:41], v[198:199], v[106:107]
	v_lshlrev_b32_e32 v210, 16, v211
	v_and_b32_e32 v211, 0xffff0000, v211
	v_pk_fma_f32 v[42:43], v[42:43], v[210:211], v[108:109]
	s_nop 0
	v_bfe_u32 v198, v40, 16, 1
	v_add3_u32 v40, v40, v198, s33
	v_bfe_u32 v198, v41, 16, 1
	v_add3_u32 v41, v41, v198, s33
	v_bfe_u32 v198, v42, 16, 1
	v_add3_u32 v42, v42, v198, s33
	v_bfe_u32 v198, v43, 16, 1
	v_add3_u32 v43, v43, v198, s33
	v_perm_b32 v40, v41, v40, s96
	v_perm_b32 v41, v43, v42, s96
	global_store_dwordx2 v[200:201], v[40:41], off offset:32
	s_waitcnt vmcnt(15)
	v_lshlrev_b32_e32 v198, 16, v230
	v_and_b32_e32 v199, 0xffff0000, v230
	v_pk_fma_f32 v[36:37], v[36:37], v[198:199], v[110:111]
	v_lshlrev_b32_e32 v230, 16, v231
	v_and_b32_e32 v231, 0xffff0000, v231
	v_pk_fma_f32 v[38:39], v[38:39], v[230:231], v[112:113]
	s_nop 0
	v_bfe_u32 v198, v36, 16, 1
	v_add3_u32 v36, v36, v198, s33
	v_bfe_u32 v198, v37, 16, 1
	v_add3_u32 v37, v37, v198, s33
	v_bfe_u32 v198, v38, 16, 1
	v_add3_u32 v38, v38, v198, s33
	v_bfe_u32 v198, v39, 16, 1
	v_add3_u32 v39, v39, v198, s33
	v_perm_b32 v36, v37, v36, s96
	v_perm_b32 v37, v39, v38, s96
	global_store_dwordx2 v[200:201], v[36:37], off offset:64
	s_waitcnt vmcnt(15)
	v_lshlrev_b32_e32 v198, 16, v232
	v_and_b32_e32 v199, 0xffff0000, v232
	v_pk_fma_f32 v[32:33], v[32:33], v[198:199], v[122:123]
	v_lshlrev_b32_e32 v232, 16, v233
	v_and_b32_e32 v233, 0xffff0000, v233
	v_pk_fma_f32 v[34:35], v[34:35], v[232:233], v[124:125]
	s_nop 0
	v_bfe_u32 v198, v32, 16, 1
	v_add3_u32 v32, v32, v198, s33
	v_bfe_u32 v198, v33, 16, 1
	v_add3_u32 v33, v33, v198, s33
	v_bfe_u32 v198, v34, 16, 1
	v_add3_u32 v34, v34, v198, s33
	v_bfe_u32 v198, v35, 16, 1
	v_add3_u32 v35, v35, v198, s33
	v_perm_b32 v32, v33, v32, s96
	v_perm_b32 v33, v35, v34, s96
	global_store_dwordx2 v[200:201], v[32:33], off offset:96
	v_add_u32_e32 v114, 0x18000, v195
	v_lshl_add_u64 v[200:201], v[114:115], 0, s[6:7]
	s_waitcnt vmcnt(11)
	v_lshlrev_b32_e32 v198, 16, v234
	v_and_b32_e32 v199, 0xffff0000, v234
	v_pk_fma_f32 v[28:29], v[28:29], v[198:199], v[126:127]
	v_lshlrev_b32_e32 v234, 16, v235
	v_and_b32_e32 v235, 0xffff0000, v235
	v_pk_fma_f32 v[30:31], v[30:31], v[234:235], v[128:129]
	s_nop 0
	v_bfe_u32 v198, v28, 16, 1
	v_add3_u32 v28, v28, v198, s33
	v_bfe_u32 v198, v29, 16, 1
	v_add3_u32 v29, v29, v198, s33
	v_bfe_u32 v198, v30, 16, 1
	v_add3_u32 v30, v30, v198, s33
	v_bfe_u32 v198, v31, 16, 1
	v_add3_u32 v31, v31, v198, s33
	v_perm_b32 v28, v29, v28, s96
	v_perm_b32 v29, v31, v30, s96
	global_store_dwordx2 v[200:201], v[28:29], off
	s_waitcnt vmcnt(11)
	v_lshlrev_b32_e32 v198, 16, v236
	v_and_b32_e32 v199, 0xffff0000, v236
	v_pk_fma_f32 v[24:25], v[24:25], v[198:199], v[130:131]
	v_lshlrev_b32_e32 v236, 16, v237
	v_and_b32_e32 v237, 0xffff0000, v237
	v_pk_fma_f32 v[26:27], v[26:27], v[236:237], v[132:133]
	s_nop 0
	v_bfe_u32 v198, v24, 16, 1
	v_add3_u32 v24, v24, v198, s33
	v_bfe_u32 v198, v25, 16, 1
	v_add3_u32 v25, v25, v198, s33
	v_bfe_u32 v198, v26, 16, 1
	v_add3_u32 v26, v26, v198, s33
	v_bfe_u32 v198, v27, 16, 1
	v_add3_u32 v27, v27, v198, s33
	v_perm_b32 v24, v25, v24, s96
	v_perm_b32 v25, v27, v26, s96
	global_store_dwordx2 v[200:201], v[24:25], off offset:32
	s_waitcnt vmcnt(11)
	v_lshlrev_b32_e32 v198, 16, v238
	v_and_b32_e32 v199, 0xffff0000, v238
	v_pk_fma_f32 v[20:21], v[20:21], v[198:199], v[156:157]
	v_lshlrev_b32_e32 v238, 16, v239
	v_and_b32_e32 v239, 0xffff0000, v239
	v_pk_fma_f32 v[22:23], v[22:23], v[238:239], v[158:159]
	s_nop 0
	v_bfe_u32 v198, v20, 16, 1
	v_add3_u32 v20, v20, v198, s33
	v_bfe_u32 v198, v21, 16, 1
	v_add3_u32 v21, v21, v198, s33
	v_bfe_u32 v198, v22, 16, 1
	v_add3_u32 v22, v22, v198, s33
	v_bfe_u32 v198, v23, 16, 1
	v_add3_u32 v23, v23, v198, s33
	v_perm_b32 v20, v21, v20, s96
	v_perm_b32 v21, v23, v22, s96
	global_store_dwordx2 v[200:201], v[20:21], off offset:64
	s_waitcnt vmcnt(11)
	v_lshlrev_b32_e32 v198, 16, v240
	v_and_b32_e32 v199, 0xffff0000, v240
	v_pk_fma_f32 v[16:17], v[16:17], v[198:199], v[166:167]
	v_lshlrev_b32_e32 v240, 16, v241
	v_and_b32_e32 v241, 0xffff0000, v241
	v_pk_fma_f32 v[18:19], v[18:19], v[240:241], v[168:169]
	s_nop 0
	v_bfe_u32 v198, v16, 16, 1
	v_add3_u32 v16, v16, v198, s33
	v_bfe_u32 v198, v17, 16, 1
	v_add3_u32 v17, v17, v198, s33
	v_bfe_u32 v198, v18, 16, 1
	v_add3_u32 v18, v18, v198, s33
	v_bfe_u32 v198, v19, 16, 1
	v_add3_u32 v19, v19, v198, s33
	v_perm_b32 v16, v17, v16, s96
	v_perm_b32 v17, v19, v18, s96
	global_store_dwordx2 v[200:201], v[16:17], off offset:96
	v_add_u32_e32 v114, 0x20000, v195
	v_lshl_add_u64 v[200:201], v[114:115], 0, s[6:7]
	s_waitcnt vmcnt(11)
	v_lshlrev_b32_e32 v198, 16, v242
	v_and_b32_e32 v199, 0xffff0000, v242
	v_pk_fma_f32 v[12:13], v[12:13], v[198:199], v[212:213]
	v_lshlrev_b32_e32 v242, 16, v243
	v_and_b32_e32 v243, 0xffff0000, v243
	v_pk_fma_f32 v[14:15], v[14:15], v[242:243], v[214:215]
	s_nop 0
	v_bfe_u32 v198, v12, 16, 1
	v_add3_u32 v12, v12, v198, s33
	v_bfe_u32 v198, v13, 16, 1
	v_add3_u32 v13, v13, v198, s33
	v_bfe_u32 v198, v14, 16, 1
	v_add3_u32 v14, v14, v198, s33
	v_bfe_u32 v198, v15, 16, 1
	v_add3_u32 v15, v15, v198, s33
	v_perm_b32 v12, v13, v12, s96
	v_perm_b32 v13, v15, v14, s96
	global_store_dwordx2 v[200:201], v[12:13], off
	s_waitcnt vmcnt(11)
	v_lshlrev_b32_e32 v198, 16, v244
	v_and_b32_e32 v199, 0xffff0000, v244
	v_pk_fma_f32 v[8:9], v[8:9], v[198:199], v[216:217]
	v_lshlrev_b32_e32 v244, 16, v245
	v_and_b32_e32 v245, 0xffff0000, v245
	v_pk_fma_f32 v[10:11], v[10:11], v[244:245], v[218:219]
	s_nop 0
	v_bfe_u32 v198, v8, 16, 1
	v_add3_u32 v8, v8, v198, s33
	v_bfe_u32 v198, v9, 16, 1
	v_add3_u32 v9, v9, v198, s33
	v_bfe_u32 v198, v10, 16, 1
	v_add3_u32 v10, v10, v198, s33
	v_bfe_u32 v198, v11, 16, 1
	v_add3_u32 v11, v11, v198, s33
	v_perm_b32 v8, v9, v8, s96
	v_perm_b32 v9, v11, v10, s96
	global_store_dwordx2 v[200:201], v[8:9], off offset:32
	s_waitcnt vmcnt(11)
	v_lshlrev_b32_e32 v198, 16, v246
	v_and_b32_e32 v199, 0xffff0000, v246
	v_pk_fma_f32 v[4:5], v[4:5], v[198:199], v[220:221]
	v_lshlrev_b32_e32 v246, 16, v247
	v_and_b32_e32 v247, 0xffff0000, v247
	v_pk_fma_f32 v[6:7], v[6:7], v[246:247], v[222:223]
	s_nop 0
	v_bfe_u32 v198, v4, 16, 1
	v_add3_u32 v4, v4, v198, s33
	v_bfe_u32 v198, v5, 16, 1
	v_add3_u32 v5, v5, v198, s33
	v_bfe_u32 v198, v6, 16, 1
	v_add3_u32 v6, v6, v198, s33
	v_bfe_u32 v198, v7, 16, 1
	v_add3_u32 v7, v7, v198, s33
	v_perm_b32 v4, v5, v4, s96
	v_perm_b32 v5, v7, v6, s96
	global_store_dwordx2 v[200:201], v[4:5], off offset:64
	s_waitcnt vmcnt(11)
	v_lshlrev_b32_e32 v198, 16, v248
	v_and_b32_e32 v199, 0xffff0000, v248
	v_pk_fma_f32 v[0:1], v[0:1], v[198:199], v[224:225]
	v_lshlrev_b32_e32 v248, 16, v249
	v_and_b32_e32 v249, 0xffff0000, v249
	v_pk_fma_f32 v[2:3], v[2:3], v[248:249], v[226:227]
	s_nop 0
	v_bfe_u32 v198, v0, 16, 1
	v_add3_u32 v0, v0, v198, s33
	v_bfe_u32 v198, v1, 16, 1
	v_add3_u32 v1, v1, v198, s33
	v_bfe_u32 v198, v2, 16, 1
	v_add3_u32 v2, v2, v198, s33
	v_bfe_u32 v198, v3, 16, 1
	v_add3_u32 v3, v3, v198, s33
	v_perm_b32 v0, v1, v0, s96
	v_perm_b32 v1, v3, v2, s96
	global_store_dwordx2 v[200:201], v[0:1], off offset:96
	s_mov_b32 s35, 0
	s_movk_i32 s8, 0x50
	s_movk_i32 s10, 0x3200
	s_mov_b64 s[12:13], 0x2800

.LBB0_137:
	s_add_i32 s37, s11, 1
	s_bitcmp1_b32 s11, 0
	s_cselect_b32 s11, 0x9000, 0
	s_add_i32 s11, s11, 0
	v_add_u32_e32 v94, s11, v178
	v_add_u32_e32 v95, v94, v179
	ds_read_b128 v[90:93], v95
	ds_read_b128 v[100:103], v95 offset:2048
	ds_read_b128 v[104:107], v95 offset:4096
	ds_read_b128 v[108:111], v95 offset:6144
	v_add_u32_e32 v94, v94, v180
	ds_read_b128 v[112:115], v95 offset:8192
	ds_read_b128 v[116:119], v94 offset:20480
	ds_read_b128 v[120:123], v94 offset:22528
	ds_read_b128 v[124:127], v94 offset:24576
	ds_read_b128 v[128:131], v94 offset:26624
	v_add_u32_e32 v206, s11, v181
	v_add_u32_e32 v207, v206, v179
	ds_read_b128 v[208:211], v207
	ds_read_b128 v[212:215], v207 offset:2048
	ds_read_b128 v[216:219], v207 offset:4096
	ds_read_b128 v[220:223], v207 offset:6144
	v_add_u32_e32 v224, v206, v180
	ds_read_b128 v[226:229], v207 offset:8192
	ds_read_b128 v[230:233], v224 offset:20480
	ds_read_b128 v[234:237], v224 offset:22528
	ds_read_b128 v[238:241], v224 offset:24576
	ds_read_b128 v[242:245], v224 offset:26624
	s_setprio 1
	s_waitcnt lgkmcnt(9)
	v_mfma_f32_16x16x32_bf16 v[76:79], v[116:119], v[90:93], v[76:79]
	v_mfma_f32_16x16x32_bf16 v[72:75], v[120:123], v[90:93], v[72:75]
	v_mfma_f32_16x16x32_bf16 v[68:71], v[124:127], v[90:93], v[68:71]
	v_mfma_f32_16x16x32_bf16 v[64:67], v[128:131], v[90:93], v[64:67]
	v_mfma_f32_16x16x32_bf16 v[60:63], v[116:119], v[100:103], v[60:63]
	v_mfma_f32_16x16x32_bf16 v[56:59], v[120:123], v[100:103], v[56:59]
	v_mfma_f32_16x16x32_bf16 v[52:55], v[124:127], v[100:103], v[52:55]
	v_mfma_f32_16x16x32_bf16 v[48:51], v[128:131], v[100:103], v[48:51]
	v_mfma_f32_16x16x32_bf16 v[44:47], v[116:119], v[104:107], v[44:47]
	v_mfma_f32_16x16x32_bf16 v[40:43], v[120:123], v[104:107], v[40:43]
	v_mfma_f32_16x16x32_bf16 v[36:39], v[124:127], v[104:107], v[36:39]
	v_mfma_f32_16x16x32_bf16 v[32:35], v[128:131], v[104:107], v[32:35]
	v_mfma_f32_16x16x32_bf16 v[28:31], v[116:119], v[108:111], v[28:31]
	v_mfma_f32_16x16x32_bf16 v[24:27], v[120:123], v[108:111], v[24:27]
	v_mfma_f32_16x16x32_bf16 v[20:23], v[124:127], v[108:111], v[20:23]
	v_mfma_f32_16x16x32_bf16 v[16:19], v[128:131], v[108:111], v[16:19]
	v_mfma_f32_16x16x32_bf16 v[12:15], v[116:119], v[112:115], v[12:15]
	v_mfma_f32_16x16x32_bf16 v[8:11], v[120:123], v[112:115], v[8:11]
	v_mfma_f32_16x16x32_bf16 v[4:7], v[124:127], v[112:115], v[4:7]
	v_mfma_f32_16x16x32_bf16 v[0:3], v[128:131], v[112:115], v[0:3]
	s_waitcnt lgkmcnt(0)
	s_setprio 0
	s_barrier
	s_add_u32 s12, s12, 0x80
	s_addc_u32 s13, s13, 0
	s_mov_b32 s39, s11
	v_add_u32_e32 v196, s39, v177
	v_lshl_add_u64 v[192:193], v[86:87], 0, s[12:13]
	v_readfirstlane_b32 s39, v196
	v_add_u32_e32 v197, 0x1000, v196
	v_lshl_add_u64 v[194:195], v[192:193], 0, s[44:45]
	s_mov_b32 m0, s39
	v_readfirstlane_b32 s39, v197
	v_add_u32_e32 v197, 0x2000, v196
	global_load_lds_dwordx4 v[194:195], off
	v_lshl_add_u64 v[194:195], v[192:193], 0, s[46:47]
	s_mov_b32 m0, s39
	v_readfirstlane_b32 s39, v197
	v_add_u32_e32 v197, 0x3000, v196
	global_load_lds_dwordx4 v[194:195], off
	v_lshl_add_u64 v[194:195], v[192:193], 0, s[48:49]
	s_mov_b32 m0, s39
	v_readfirstlane_b32 s39, v197
	global_load_lds_dwordx4 v[194:195], off
	v_lshl_add_u64 v[194:195], v[192:193], 0, s[52:53]
	s_mov_b32 m0, s39
	s_mov_b64 s[40:41], 0x4141080
	global_load_lds_dwordx4 v[194:195], off
	v_add_u32_e32 v194, 0x4000, v196
	v_lshl_add_u64 v[192:193], v[192:193], 0, s[40:41]
	v_readfirstlane_b32 s39, v194
	s_mov_b32 m0, s39
	v_add_u32_e32 v197, 0x5000, v196
	global_load_lds_dwordx4 v[192:193], off
	v_lshl_add_u64 v[192:193], v[88:89], 0, s[12:13]
	v_readfirstlane_b32 s39, v197
	v_add_u32_e32 v197, 0x6000, v196
	v_lshl_add_u64 v[194:195], v[192:193], 0, s[54:55]
	s_mov_b32 m0, s39
	v_readfirstlane_b32 s39, v197
	v_add_u32_e32 v197, 0x7000, v196
	global_load_lds_dwordx4 v[194:195], off
	v_lshl_add_u64 v[194:195], v[192:193], 0, s[56:57]
	s_mov_b32 m0, s39
	v_readfirstlane_b32 s39, v197
	global_load_lds_dwordx4 v[194:195], off
	v_lshl_add_u64 v[194:195], v[192:193], 0, s[58:59]
	s_mov_b32 m0, s39
	v_lshl_add_u64 v[192:193], v[192:193], 0, s[60:61]
	global_load_lds_dwordx4 v[194:195], off
	v_add_u32_e32 v194, 0x8000, v196
	s_nop 0
	v_readfirstlane_b32 s39, v194
	s_mov_b32 m0, s39
	s_nop 0
	global_load_lds_dwordx4 v[192:193], off
	s_setprio 1
	v_mfma_f32_16x16x32_bf16 v[76:79], v[230:233], v[208:211], v[76:79]
	v_mfma_f32_16x16x32_bf16 v[72:75], v[234:237], v[208:211], v[72:75]
	v_mfma_f32_16x16x32_bf16 v[68:71], v[238:241], v[208:211], v[68:71]
	v_mfma_f32_16x16x32_bf16 v[64:67], v[242:245], v[208:211], v[64:67]
	v_mfma_f32_16x16x32_bf16 v[60:63], v[230:233], v[212:215], v[60:63]
	v_mfma_f32_16x16x32_bf16 v[56:59], v[234:237], v[212:215], v[56:59]
	v_mfma_f32_16x16x32_bf16 v[52:55], v[238:241], v[212:215], v[52:55]
	v_mfma_f32_16x16x32_bf16 v[48:51], v[242:245], v[212:215], v[48:51]
	v_mfma_f32_16x16x32_bf16 v[44:47], v[230:233], v[216:219], v[44:47]
	v_mfma_f32_16x16x32_bf16 v[40:43], v[234:237], v[216:219], v[40:43]
	v_mfma_f32_16x16x32_bf16 v[36:39], v[238:241], v[216:219], v[36:39]
	v_mfma_f32_16x16x32_bf16 v[32:35], v[242:245], v[216:219], v[32:35]
	v_mfma_f32_16x16x32_bf16 v[28:31], v[230:233], v[220:223], v[28:31]
	v_mfma_f32_16x16x32_bf16 v[24:27], v[234:237], v[220:223], v[24:27]
	v_mfma_f32_16x16x32_bf16 v[20:23], v[238:241], v[220:223], v[20:23]
	v_mfma_f32_16x16x32_bf16 v[16:19], v[242:245], v[220:223], v[16:19]
	v_mfma_f32_16x16x32_bf16 v[12:15], v[230:233], v[226:229], v[12:15]
	v_mfma_f32_16x16x32_bf16 v[8:11], v[234:237], v[226:229], v[8:11]
	v_mfma_f32_16x16x32_bf16 v[4:7], v[238:241], v[226:229], v[4:7]
	v_mfma_f32_16x16x32_bf16 v[0:3], v[242:245], v[226:229], v[0:3]
	s_setprio 0
	s_cmpk_lg_i32 s12, 0x700
	s_mov_b32 s11, s37
	s_waitcnt vmcnt(9)
	s_barrier
	s_cbranch_scc1 .LBB0_137
	s_add_i32 s37, s11, 1
	s_bitcmp1_b32 s11, 0
	s_cselect_b32 s11, 0x9000, 0
	s_add_i32 s11, s11, 0
	v_add_u32_e32 v94, s11, v178
	v_add_u32_e32 v95, v94, v179
	ds_read_b128 v[90:93], v95
	ds_read_b128 v[100:103], v95 offset:2048
	ds_read_b128 v[104:107], v95 offset:4096
	ds_read_b128 v[108:111], v95 offset:6144
	v_add_u32_e32 v94, v94, v180
	ds_read_b128 v[112:115], v95 offset:8192
	ds_read_b128 v[116:119], v94 offset:20480
	ds_read_b128 v[120:123], v94 offset:22528
	ds_read_b128 v[124:127], v94 offset:24576
	ds_read_b128 v[128:131], v94 offset:26624
	v_add_u32_e32 v206, s11, v181
	v_add_u32_e32 v207, v206, v179
	ds_read_b128 v[208:211], v207
	ds_read_b128 v[212:215], v207 offset:2048
	ds_read_b128 v[216:219], v207 offset:4096
	ds_read_b128 v[220:223], v207 offset:6144
	v_add_u32_e32 v224, v206, v180
	ds_read_b128 v[226:229], v207 offset:8192
	ds_read_b128 v[230:233], v224 offset:20480
	ds_read_b128 v[234:237], v224 offset:22528
	ds_read_b128 v[238:241], v224 offset:24576
	ds_read_b128 v[242:245], v224 offset:26624
	s_setprio 1
	s_waitcnt lgkmcnt(9)
	v_mfma_f32_16x16x32_bf16 v[76:79], v[116:119], v[90:93], v[76:79]
	v_mfma_f32_16x16x32_bf16 v[72:75], v[120:123], v[90:93], v[72:75]
	v_mfma_f32_16x16x32_bf16 v[68:71], v[124:127], v[90:93], v[68:71]
	v_mfma_f32_16x16x32_bf16 v[64:67], v[128:131], v[90:93], v[64:67]
	v_mfma_f32_16x16x32_bf16 v[60:63], v[116:119], v[100:103], v[60:63]
	v_mfma_f32_16x16x32_bf16 v[56:59], v[120:123], v[100:103], v[56:59]
	v_mfma_f32_16x16x32_bf16 v[52:55], v[124:127], v[100:103], v[52:55]
	v_mfma_f32_16x16x32_bf16 v[48:51], v[128:131], v[100:103], v[48:51]
	v_mfma_f32_16x16x32_bf16 v[44:47], v[116:119], v[104:107], v[44:47]
	v_mfma_f32_16x16x32_bf16 v[40:43], v[120:123], v[104:107], v[40:43]
	v_mfma_f32_16x16x32_bf16 v[36:39], v[124:127], v[104:107], v[36:39]
	v_mfma_f32_16x16x32_bf16 v[32:35], v[128:131], v[104:107], v[32:35]
	v_mfma_f32_16x16x32_bf16 v[28:31], v[116:119], v[108:111], v[28:31]
	v_mfma_f32_16x16x32_bf16 v[24:27], v[120:123], v[108:111], v[24:27]
	v_mfma_f32_16x16x32_bf16 v[20:23], v[124:127], v[108:111], v[20:23]
	v_mfma_f32_16x16x32_bf16 v[16:19], v[128:131], v[108:111], v[16:19]
	v_mfma_f32_16x16x32_bf16 v[12:15], v[116:119], v[112:115], v[12:15]
	v_mfma_f32_16x16x32_bf16 v[8:11], v[120:123], v[112:115], v[8:11]
	v_mfma_f32_16x16x32_bf16 v[4:7], v[124:127], v[112:115], v[4:7]
	v_mfma_f32_16x16x32_bf16 v[0:3], v[128:131], v[112:115], v[0:3]
	s_waitcnt lgkmcnt(0)
	v_mfma_f32_16x16x32_bf16 v[76:79], v[230:233], v[208:211], v[76:79]
	v_mfma_f32_16x16x32_bf16 v[72:75], v[234:237], v[208:211], v[72:75]
	v_mfma_f32_16x16x32_bf16 v[68:71], v[238:241], v[208:211], v[68:71]
	v_mfma_f32_16x16x32_bf16 v[64:67], v[242:245], v[208:211], v[64:67]
	v_mfma_f32_16x16x32_bf16 v[60:63], v[230:233], v[212:215], v[60:63]
	v_mfma_f32_16x16x32_bf16 v[56:59], v[234:237], v[212:215], v[56:59]
	v_mfma_f32_16x16x32_bf16 v[52:55], v[238:241], v[212:215], v[52:55]
	v_mfma_f32_16x16x32_bf16 v[48:51], v[242:245], v[212:215], v[48:51]
	v_mfma_f32_16x16x32_bf16 v[44:47], v[230:233], v[216:219], v[44:47]
	v_mfma_f32_16x16x32_bf16 v[40:43], v[234:237], v[216:219], v[40:43]
	v_mfma_f32_16x16x32_bf16 v[36:39], v[238:241], v[216:219], v[36:39]
	v_mfma_f32_16x16x32_bf16 v[32:35], v[242:245], v[216:219], v[32:35]
	v_mfma_f32_16x16x32_bf16 v[28:31], v[230:233], v[220:223], v[28:31]
	v_mfma_f32_16x16x32_bf16 v[24:27], v[234:237], v[220:223], v[24:27]
	v_mfma_f32_16x16x32_bf16 v[20:23], v[238:241], v[220:223], v[20:23]
	v_mfma_f32_16x16x32_bf16 v[16:19], v[242:245], v[220:223], v[16:19]
	v_mfma_f32_16x16x32_bf16 v[12:15], v[230:233], v[226:229], v[12:15]
	v_mfma_f32_16x16x32_bf16 v[8:11], v[234:237], v[226:229], v[8:11]
	v_mfma_f32_16x16x32_bf16 v[4:7], v[238:241], v[226:229], v[4:7]
	v_mfma_f32_16x16x32_bf16 v[0:3], v[242:245], v[226:229], v[0:3]
	s_setprio 0
	s_add_u32 s12, s12, 0x80
	s_addc_u32 s13, s13, 0
	s_mov_b32 s11, s37
	s_waitcnt vmcnt(0)
	s_barrier
	v_add_u32_e32 v94, v182, v180
	ds_read_b128 v[86:89], v94 offset:63488
	ds_read_b128 v[90:93], v94 offset:61440
	ds_read_b128 v[100:103], v94 offset:59392
	ds_read_b128 v[104:107], v94 offset:57344
	v_add_u32_e32 v94, v182, v179
	ds_read_b128 v[108:111], v94 offset:45056
	ds_read_b128 v[112:115], v94 offset:43008
	ds_read_b128 v[116:119], v94 offset:40960
	ds_read_b128 v[120:123], v94 offset:38912
	ds_read_b128 v[124:127], v94 offset:36864
	s_setprio 1
	s_waitcnt lgkmcnt(0)
	v_mfma_f32_16x16x32_bf16 v[76:79], v[104:107], v[124:127], v[76:79]
	v_mfma_f32_16x16x32_bf16 v[72:75], v[100:103], v[124:127], v[72:75]
	v_mfma_f32_16x16x32_bf16 v[68:71], v[90:93], v[124:127], v[68:71]
	v_mfma_f32_16x16x32_bf16 v[64:67], v[86:89], v[124:127], v[64:67]
	v_mfma_f32_16x16x32_bf16 v[60:63], v[104:107], v[120:123], v[60:63]
	v_mfma_f32_16x16x32_bf16 v[56:59], v[100:103], v[120:123], v[56:59]
	v_mfma_f32_16x16x32_bf16 v[52:55], v[90:93], v[120:123], v[52:55]
	v_mfma_f32_16x16x32_bf16 v[48:51], v[86:89], v[120:123], v[48:51]
	v_mfma_f32_16x16x32_bf16 v[44:47], v[104:107], v[116:119], v[44:47]
	v_mfma_f32_16x16x32_bf16 v[40:43], v[100:103], v[116:119], v[40:43]
	v_mfma_f32_16x16x32_bf16 v[36:39], v[90:93], v[116:119], v[36:39]
	v_mfma_f32_16x16x32_bf16 v[32:35], v[86:89], v[116:119], v[32:35]
	v_mfma_f32_16x16x32_bf16 v[28:31], v[104:107], v[112:115], v[28:31]
	v_mfma_f32_16x16x32_bf16 v[24:27], v[100:103], v[112:115], v[24:27]
	v_mfma_f32_16x16x32_bf16 v[20:23], v[90:93], v[112:115], v[20:23]
	v_mfma_f32_16x16x32_bf16 v[16:19], v[86:89], v[112:115], v[16:19]
	v_mfma_f32_16x16x32_bf16 v[12:15], v[104:107], v[108:111], v[12:15]
	v_mfma_f32_16x16x32_bf16 v[8:11], v[100:103], v[108:111], v[8:11]
	v_mfma_f32_16x16x32_bf16 v[4:7], v[90:93], v[108:111], v[4:7]
	v_mfma_f32_16x16x32_bf16 v[0:3], v[86:89], v[108:111], v[0:3]
	s_setprio 0
	v_add_u32_e32 v94, v183, v179
	ds_read_b128 v[86:89], v94 offset:36864
	ds_read_b128 v[90:93], v94 offset:38912
	ds_read_b128 v[100:103], v94 offset:40960
	ds_read_b128 v[104:107], v94 offset:43008
	v_add_u32_e32 v95, v183, v180
	ds_read_b128 v[108:111], v94 offset:45056
	ds_read_b128 v[112:115], v95 offset:57344
	ds_read_b128 v[116:119], v95 offset:59392
	ds_read_b128 v[120:123], v95 offset:61440
	ds_read_b128 v[124:127], v95 offset:63488
	s_setprio 1
	s_waitcnt lgkmcnt(3)
	v_mfma_f32_16x16x32_bf16 v[76:79], v[112:115], v[86:89], v[76:79]
	s_waitcnt lgkmcnt(2)
	v_mfma_f32_16x16x32_bf16 v[72:75], v[116:119], v[86:89], v[72:75]
	s_waitcnt lgkmcnt(1)
	v_mfma_f32_16x16x32_bf16 v[68:71], v[120:123], v[86:89], v[68:71]
	s_waitcnt lgkmcnt(0)
	v_mfma_f32_16x16x32_bf16 v[64:67], v[124:127], v[86:89], v[64:67]
	v_mfma_f32_16x16x32_bf16 v[60:63], v[112:115], v[90:93], v[60:63]
	v_mfma_f32_16x16x32_bf16 v[56:59], v[116:119], v[90:93], v[56:59]
	v_mfma_f32_16x16x32_bf16 v[52:55], v[120:123], v[90:93], v[52:55]
	v_mfma_f32_16x16x32_bf16 v[48:51], v[124:127], v[90:93], v[48:51]
	v_mfma_f32_16x16x32_bf16 v[44:47], v[112:115], v[100:103], v[44:47]
	v_mfma_f32_16x16x32_bf16 v[40:43], v[116:119], v[100:103], v[40:43]
	v_mfma_f32_16x16x32_bf16 v[36:39], v[120:123], v[100:103], v[36:39]
	v_mfma_f32_16x16x32_bf16 v[32:35], v[124:127], v[100:103], v[32:35]
	v_mfma_f32_16x16x32_bf16 v[28:31], v[112:115], v[104:107], v[28:31]
	v_mfma_f32_16x16x32_bf16 v[24:27], v[116:119], v[104:107], v[24:27]
	v_mfma_f32_16x16x32_bf16 v[20:23], v[120:123], v[104:107], v[20:23]
	v_mfma_f32_16x16x32_bf16 v[16:19], v[124:127], v[104:107], v[16:19]
	v_mfma_f32_16x16x32_bf16 v[12:15], v[112:115], v[108:111], v[12:15]
	v_mfma_f32_16x16x32_bf16 v[8:11], v[116:119], v[108:111], v[8:11]
	v_mfma_f32_16x16x32_bf16 v[4:7], v[120:123], v[108:111], v[4:7]
	v_mfma_f32_16x16x32_bf16 v[0:3], v[124:127], v[108:111], v[0:3]
	s_setprio 0
	v_mov_b32_e32 v86, v97
	s_waitcnt vmcnt(0)
	s_barrier
	s_mulk_i32 s38, 0xa0
	v_add_u32_e32 v87, v86, v176
	v_ashrrev_i32_e32 v88, 7, v87
	v_and_or_b32 v86, v87, 15, s38
	s_movk_i32 s11, 0x50
	v_mad_u64_u32 v[88:89], s[12:13], v88, s11, v[86:87]
	s_lshl_b32 s10, s10, 7
	v_lshrrev_b32_e32 v86, 2, v87
	v_and_b32_e32 v92, 64, v87
	s_and_b32 s11, s10, 0x380
	v_and_b32_e32 v89, 12, v86
	v_or3_b32 v158, v92, s11, v89
	v_cmp_lt_i32_e32 vcc, v140, v138
	s_ashr_i32 s11, s10, 31
	s_lshl_b64 s[10:11], s[10:11], 1
	v_cndmask_b32_e32 v86, v137, v140, vcc
	v_cmp_lt_i32_e32 vcc, v139, v138
	v_lshlrev_b32_e32 v184, 2, v86
	s_add_u32 s10, s34, s10
	v_cndmask_b32_e32 v86, v137, v139, vcc
	v_lshlrev_b32_e32 v185, 2, v86
	s_addc_u32 s11, s35, s11
	v_lshlrev_b32_e32 v86, 1, v92
	v_mov_b32_e32 v87, v97
	s_mov_b32 s37, 0
	v_lshlrev_b32_e32 v96, 1, v158
	v_lshl_add_u64 v[86:87], s[10:11], 0, v[86:87]
	v_lshlrev_b32_e32 v92, 1, v89
	v_mov_b32_e32 v93, v97
	v_lshl_add_u64 v[90:91], s[6:7], 0, v[96:97]
	v_lshl_add_u64 v[86:87], v[86:87], 0, v[92:93]
	v_ashrrev_i32_e32 v89, 31, v88
	v_lshlrev_b64 v[92:93], 11, v[88:89]
	v_lshl_add_u64 v[94:95], v[90:91], 0, v[92:93]
	global_load_dwordx2 v[102:103], v[94:95], off
	global_load_dwordx2 v[100:101], v[94:95], off offset:32
	s_mov_b32 s38, 0x3c800000
	s_mov_b32 s12, 0x800000
	s_movk_i32 s13, 0x3200
	s_waitcnt vmcnt(1)
	v_lshlrev_b32_e32 v132, 16, v102
	s_waitcnt vmcnt(0)
	v_lshlrev_b32_e32 v123, 16, v100
	v_and_b32_e32 v119, 0xffff0000, v100
	v_alignbit_b32 v89, v101, v100, 16
	v_and_b32_e32 v121, 0xffff0000, v101
	global_load_dwordx2 v[100:101], v[94:95], off offset:64
	v_and_b32_e32 v125, 0xffff0000, v89
	v_and_b32_e32 v129, 0xffff0000, v103
	v_and_b32_e32 v130, 0xffff0000, v102
	v_mov_b32_e32 v128, v132
	v_mov_b32_e32 v131, v132
	v_mul_f32_e32 v108, v132, v132
	v_mul_f32_e32 v122, v123, v123
	v_mul_f32_e32 v118, v119, v119
	v_mul_f32_e32 v124, v125, v125
	v_mul_f32_e32 v120, v121, v121
	s_waitcnt vmcnt(0)
	v_lshlrev_b32_e32 v115, 16, v100
	v_and_b32_e32 v111, 0xffff0000, v100
	v_alignbit_b32 v89, v101, v100, 16
	v_and_b32_e32 v113, 0xffff0000, v101
	global_load_dwordx2 v[100:101], v[94:95], off offset:96
	v_and_b32_e32 v117, 0xffff0000, v89
	v_mul_f32_e32 v114, v115, v115
	v_mul_f32_e32 v110, v111, v111
	v_mul_f32_e32 v116, v117, v117
	v_mul_f32_e32 v112, v113, v113
	s_waitcnt vmcnt(0)
	v_alignbit_b32 v89, v101, v100, 16
	v_and_b32_e32 v107, 0xffff0000, v89
	v_alignbit_b32 v89, v103, v102, 16
	v_and_b32_e32 v103, 0xffff0000, v89
	v_and_b32_e32 v102, 16, v102
	v_mov_b32_e32 v89, v132
	v_pk_add_f32 v[126:127], v[102:103], v[128:129]
	v_pk_add_f32 v[156:157], v[130:131], v[88:89] op_sel_hi:[0,1]
	v_mov_b32_e32 v109, v127
	v_pk_mul_f32 v[126:127], v[130:131], v[130:131]
	v_mov_b32_e32 v128, v103
	v_mul_f32_e32 v102, v129, v129
	v_mov_b32_e32 v133, v103
	v_mov_b32_e32 v127, v157
	v_pk_fma_f32 v[102:103], v[128:129], v[128:129], v[102:103] op_sel_hi:[1,1,0]
	v_pk_add_f32 v[108:109], v[108:109], v[126:127]
	v_mov_b32_e32 v103, v97
	v_pk_add_f32 v[102:103], v[108:109], v[102:103]
	v_pk_add_f32 v[108:109], v[122:123], v[118:119]
	v_pk_add_f32 v[126:127], v[124:125], v[120:121]
	v_lshlrev_b32_e32 v105, 16, v100
	v_pk_add_f32 v[108:109], v[108:109], v[126:127]
	v_and_b32_e32 v95, 0xffff0000, v100
	v_and_b32_e32 v101, 0xffff0000, v101
	v_pk_add_f32 v[102:103], v[102:103], v[108:109]
	v_pk_add_f32 v[108:109], v[114:115], v[110:111]
	v_pk_add_f32 v[126:127], v[116:117], v[112:113]
	v_mul_f32_e32 v104, v105, v105
	v_mul_f32_e32 v94, v95, v95
	v_mul_f32_e32 v106, v107, v107
	v_mul_f32_e32 v100, v101, v101
	v_pk_add_f32 v[108:109], v[108:109], v[126:127]
	v_pk_add_f32 v[126:127], v[106:107], v[100:101]
	v_pk_add_f32 v[102:103], v[102:103], v[108:109]
	v_pk_add_f32 v[108:109], v[104:105], v[94:95]
	v_mul_f32_e32 v100, 0xbfb8aa3b, v76
	v_pk_add_f32 v[108:109], v[108:109], v[126:127]
	v_exp_f32_e32 v186, v100
	v_pk_add_f32 v[102:103], v[102:103], v[108:109]
	s_nop 0
	ds_bpermute_b32 v109, v184, v103
	ds_bpermute_b32 v108, v184, v102
	v_mul_f32_e32 v100, 0xbfb8aa3b, v77
	v_exp_f32_e32 v126, v100
	v_mul_f32_e32 v100, 0xbfb8aa3b, v78
	v_exp_f32_e32 v187, v100
	s_waitcnt lgkmcnt(0)
	v_pk_add_f32 v[102:103], v[102:103], v[108:109]
	s_nop 0
	ds_bpermute_b32 v109, v185, v103
	ds_bpermute_b32 v108, v185, v102
	v_mov_b32_e32 v131, v129
	v_mul_f32_e32 v100, 0xbfb8aa3b, v79
	v_exp_f32_e32 v127, v100
	v_mov_b32_e32 v124, v123
	s_waitcnt lgkmcnt(0)
	v_pk_add_f32 v[102:103], v[102:103], v[108:109]
	v_lshl_add_u64 v[108:109], s[8:9], 0, v[92:93]
	v_pk_mul_f32 v[102:103], v[102:103], s[38:39] op_sel_hi:[1,0]
	v_lshl_add_u64 v[108:109], v[108:109], 0, v[96:97]
	v_fma_f32 v89, -v103, v103, v102
	v_max_f32_e32 v89, 0, v89
	v_add_f32_e32 v89, 0x3a27c5ac, v89
	v_cmp_gt_f32_e32 vcc, s12, v89
	v_mul_f32_e32 v94, 0x4b800000, v89
	v_pk_add_f32 v[132:133], v[132:133], v[102:103] op_sel:[0,1] neg_lo:[0,1] neg_hi:[0,1]
	v_cndmask_b32_e32 v89, v89, v94, vcc
	v_rsq_f32_e32 v89, v89
	v_pk_add_f32 v[128:129], v[130:131], v[102:103] op_sel:[0,1] neg_lo:[0,1] neg_hi:[0,1]
	v_pk_add_f32 v[126:127], v[126:127], 1.0 op_sel_hi:[1,0]
	v_mad_i64_i32 v[92:93], s[10:11], v88, s13, v[86:87]
	v_mul_f32_e32 v94, 0x45800000, v89
	v_cndmask_b32_e32 v94, v89, v94, vcc
	v_lshlrev_b32_e32 v89, 2, v158
	global_load_dwordx4 v[156:159], v89, s[0:1]
	global_load_dwordx4 v[166:169], v89, s[4:5]
	v_pk_mul_f32 v[132:133], v[132:133], v[94:95] op_sel_hi:[1,0]
	v_pk_mul_f32 v[128:129], v[128:129], v[94:95] op_sel_hi:[1,0]
	v_pk_add_f32 v[122:123], v[124:125], v[102:103] op_sel:[0,1] neg_lo:[0,1] neg_hi:[0,1]
	v_mov_b32_e32 v120, v119
	v_pk_mul_f32 v[122:123], v[122:123], v[94:95] op_sel_hi:[1,0]
	v_pk_add_f32 v[118:119], v[120:121], v[102:103] op_sel:[0,1] neg_lo:[0,1] neg_hi:[0,1]
	v_mov_b32_e32 v116, v115
	v_pk_mul_f32 v[118:119], v[118:119], v[94:95] op_sel_hi:[1,0]
	v_pk_add_f32 v[114:115], v[116:117], v[102:103] op_sel:[0,1] neg_lo:[0,1] neg_hi:[0,1]
	s_waitcnt vmcnt(1)
	v_mov_b32_e32 v188, v156
	v_mov_b32_e32 v189, v158
	s_waitcnt vmcnt(0)
	v_mov_b32_e32 v190, v166
	v_mov_b32_e32 v191, v168
	v_pk_fma_f32 v[132:133], v[188:189], v[132:133], v[190:191]
	global_load_dwordx2 v[188:189], v[108:109], off
	v_mov_b32_e32 v158, v157
	v_mov_b32_e32 v168, v167
	v_pk_fma_f32 v[128:129], v[158:159], v[128:129], v[168:169]
	v_pk_mul_f32 v[114:115], v[114:115], v[94:95] op_sel_hi:[1,0]
	s_waitcnt vmcnt(0)
	v_and_b32_e32 v131, 0xffff0000, v189
	v_and_b32_e32 v130, 0xffff0000, v188
	v_pk_add_f32 v[128:129], v[128:129], v[130:131]
	v_pk_add_f32 v[130:131], v[186:187], 1.0 op_sel_hi:[1,0]
	v_lshlrev_b32_e32 v191, 16, v189
	v_lshlrev_b32_e32 v190, 16, v188
	v_pk_add_f32 v[132:133], v[132:133], v[190:191]
	v_rcp_f32_e32 v100, v131
	s_nop 0
	v_mul_f32_e32 v131, v78, v100
	s_nop 0
	v_rcp_f32_e32 v78, v130
	s_nop 0
	v_mul_f32_e32 v130, v76, v78
	v_pk_mul_f32 v[130:131], v[130:131], v[132:133]
	v_rcp_f32_e32 v76, v127
	s_nop 0
	v_mul_f32_e32 v79, v79, v76
	s_nop 0
	v_rcp_f32_e32 v76, v126
	s_nop 0
	v_mul_f32_e32 v78, v77, v76
	v_pk_mul_f32 v[76:77], v[78:79], v[128:129]
	v_and_b32_sdwa v78, v131, v154 dst_sel:DWORD dst_unused:UNUSED_PAD src0_sel:WORD_1 src1_sel:DWORD
	v_and_b32_sdwa v100, v77, v154 dst_sel:DWORD dst_unused:UNUSED_PAD src0_sel:WORD_1 src1_sel:DWORD
	v_and_b32_sdwa v104, v76, v154 dst_sel:DWORD dst_unused:UNUSED_PAD src0_sel:WORD_1 src1_sel:DWORD
	v_and_b32_sdwa v79, v130, v154 dst_sel:DWORD dst_unused:UNUSED_PAD src0_sel:WORD_1 src1_sel:DWORD
	v_add3_u32 v77, v77, v100, s33
	v_add3_u32 v76, v76, v104, s33
	v_add3_u32 v79, v130, v79, s33
	v_add3_u32 v78, v131, v78, s33
	v_and_b32_e32 v77, 0xffff0000, v77
	v_and_b32_e32 v76, 0xffff0000, v76
	v_or_b32_sdwa v77, v77, v78 dst_sel:DWORD dst_unused:UNUSED_PAD src0_sel:DWORD src1_sel:WORD_1
	v_or_b32_sdwa v76, v76, v79 dst_sel:DWORD dst_unused:UNUSED_PAD src0_sel:DWORD src1_sel:WORD_1
	global_store_dwordx2 v[92:93], v[76:77], off
	global_load_dwordx4 v[126:129], v89, s[0:1] offset:64
	global_load_dwordx4 v[130:133], v89, s[4:5] offset:64
	v_mul_f32_e32 v76, 0xbfb8aa3b, v72
	v_mul_f32_e32 v77, 0xbfb8aa3b, v74
	v_exp_f32_e32 v78, v76
	v_exp_f32_e32 v79, v77
	v_mul_f32_e32 v76, 0xbfb8aa3b, v73
	v_mul_f32_e32 v77, 0xbfb8aa3b, v75
	v_exp_f32_e32 v76, v76
	v_pk_add_f32 v[78:79], v[78:79], 1.0 op_sel_hi:[1,0]
	v_exp_f32_e32 v77, v77
	s_nop 0
	v_pk_add_f32 v[76:77], v[76:77], 1.0 op_sel_hi:[1,0]
	v_rcp_f32_e32 v100, v79
	s_nop 0
	v_mul_f32_e32 v79, v74, v100
	v_mov_b32_e32 v112, v111
	v_rcp_f32_e32 v74, v78
	s_nop 0
	v_mul_f32_e32 v78, v72, v74
	v_pk_add_f32 v[110:111], v[112:113], v[102:103] op_sel:[0,1] neg_lo:[0,1] neg_hi:[0,1]
	v_rcp_f32_e32 v72, v77
	s_nop 0
	v_mul_f32_e32 v75, v75, v72
	v_pk_mul_f32 v[110:111], v[110:111], v[94:95] op_sel_hi:[1,0]
	v_rcp_f32_e32 v72, v76
	s_nop 0
	v_mul_f32_e32 v74, v73, v72
	s_waitcnt vmcnt(1)
	v_mov_b32_e32 v124, v126
	v_mov_b32_e32 v125, v128
	s_waitcnt vmcnt(0)
	v_mov_b32_e32 v156, v130
	v_mov_b32_e32 v157, v132
	v_pk_fma_f32 v[122:123], v[122:123], v[124:125], v[156:157]
	global_load_dwordx2 v[124:125], v[108:109], off offset:32
	v_mov_b32_e32 v128, v127
	v_mov_b32_e32 v132, v131
	v_pk_fma_f32 v[118:119], v[118:119], v[128:129], v[132:133]
	s_waitcnt vmcnt(0)
	v_and_b32_e32 v121, 0xffff0000, v125
	v_and_b32_e32 v120, 0xffff0000, v124
	v_lshlrev_b32_e32 v157, 16, v125
	v_lshlrev_b32_e32 v156, 16, v124
	v_pk_add_f32 v[118:119], v[118:119], v[120:121]
	v_pk_add_f32 v[122:123], v[122:123], v[156:157]
	v_pk_mul_f32 v[72:73], v[74:75], v[118:119]
	v_pk_mul_f32 v[78:79], v[78:79], v[122:123]
	v_and_b32_sdwa v76, v73, v154 dst_sel:DWORD dst_unused:UNUSED_PAD src0_sel:WORD_1 src1_sel:DWORD
	v_and_b32_sdwa v77, v72, v154 dst_sel:DWORD dst_unused:UNUSED_PAD src0_sel:WORD_1 src1_sel:DWORD
	v_and_b32_sdwa v74, v79, v154 dst_sel:DWORD dst_unused:UNUSED_PAD src0_sel:WORD_1 src1_sel:DWORD
	v_and_b32_sdwa v75, v78, v154 dst_sel:DWORD dst_unused:UNUSED_PAD src0_sel:WORD_1 src1_sel:DWORD
	v_add3_u32 v73, v73, v76, s33
	v_add3_u32 v72, v72, v77, s33
	v_add3_u32 v75, v78, v75, s33
	v_add3_u32 v74, v79, v74, s33
	v_and_b32_e32 v73, 0xffff0000, v73
	v_and_b32_e32 v72, 0xffff0000, v72
	v_or_b32_sdwa v73, v73, v74 dst_sel:DWORD dst_unused:UNUSED_PAD src0_sel:DWORD src1_sel:WORD_1
	v_or_b32_sdwa v72, v72, v75 dst_sel:DWORD dst_unused:UNUSED_PAD src0_sel:DWORD src1_sel:WORD_1
	global_store_dwordx2 v[92:93], v[72:73], off offset:32
	global_load_dwordx4 v[74:77], v89, s[0:1] offset:128
	global_load_dwordx4 v[118:121], v89, s[4:5] offset:128
	v_mul_f32_e32 v72, 0xbfb8aa3b, v68
	v_mul_f32_e32 v73, 0xbfb8aa3b, v70
	v_exp_f32_e32 v78, v72
	v_exp_f32_e32 v79, v73
	v_mul_f32_e32 v72, 0xbfb8aa3b, v69
	v_mul_f32_e32 v73, 0xbfb8aa3b, v71
	v_exp_f32_e32 v72, v72
	v_exp_f32_e32 v73, v73
	s_waitcnt vmcnt(1)
	v_mov_b32_e32 v116, v74
	v_mov_b32_e32 v117, v76
	s_waitcnt vmcnt(0)
	v_mov_b32_e32 v122, v118
	v_mov_b32_e32 v123, v120
	v_pk_fma_f32 v[114:115], v[114:115], v[116:117], v[122:123]
	global_load_dwordx2 v[116:117], v[108:109], off offset:64
	v_mov_b32_e32 v76, v75
	v_mov_b32_e32 v120, v119
	v_pk_fma_f32 v[74:75], v[110:111], v[76:77], v[120:121]
	v_pk_add_f32 v[72:73], v[72:73], 1.0 op_sel_hi:[1,0]
	s_waitcnt vmcnt(0)
	v_and_b32_e32 v77, 0xffff0000, v117
	v_and_b32_e32 v76, 0xffff0000, v116
	v_pk_add_f32 v[74:75], v[74:75], v[76:77]
	v_pk_add_f32 v[76:77], v[78:79], 1.0 op_sel_hi:[1,0]
	v_lshlrev_b32_e32 v123, 16, v117
	v_lshlrev_b32_e32 v122, 16, v116
	v_pk_add_f32 v[114:115], v[114:115], v[122:123]
	v_rcp_f32_e32 v78, v77
	s_nop 0
	v_mul_f32_e32 v77, v70, v78
	v_mov_b32_e32 v106, v105
	v_rcp_f32_e32 v70, v76
	s_nop 0
	v_mul_f32_e32 v76, v68, v70
	v_pk_mul_f32 v[76:77], v[76:77], v[114:115]
	v_pk_add_f32 v[104:105], v[106:107], v[102:103] op_sel:[0,1] neg_lo:[0,1] neg_hi:[0,1]
	v_rcp_f32_e32 v68, v73
	s_nop 0
	v_mul_f32_e32 v71, v71, v68
	v_pk_mul_f32 v[104:105], v[104:105], v[94:95] op_sel_hi:[1,0]
	v_mov_b32_e32 v100, v95
	v_pk_add_f32 v[100:101], v[100:101], v[102:103] op_sel:[0,1] neg_lo:[0,1] neg_hi:[0,1]
	v_rcp_f32_e32 v68, v72
	s_nop 0
	v_mul_f32_e32 v70, v69, v68
	v_pk_mul_f32 v[68:69], v[70:71], v[74:75]
	v_and_b32_sdwa v70, v77, v154 dst_sel:DWORD dst_unused:UNUSED_PAD src0_sel:WORD_1 src1_sel:DWORD
	v_and_b32_sdwa v72, v69, v154 dst_sel:DWORD dst_unused:UNUSED_PAD src0_sel:WORD_1 src1_sel:DWORD
	v_and_b32_sdwa v73, v68, v154 dst_sel:DWORD dst_unused:UNUSED_PAD src0_sel:WORD_1 src1_sel:DWORD
	v_and_b32_sdwa v71, v76, v154 dst_sel:DWORD dst_unused:UNUSED_PAD src0_sel:WORD_1 src1_sel:DWORD
	v_add3_u32 v69, v69, v72, s33
	v_add3_u32 v68, v68, v73, s33
	v_add3_u32 v71, v76, v71, s33
	v_add3_u32 v70, v77, v70, s33
	v_and_b32_e32 v69, 0xffff0000, v69
	v_and_b32_e32 v68, 0xffff0000, v68
	v_or_b32_sdwa v69, v69, v70 dst_sel:DWORD dst_unused:UNUSED_PAD src0_sel:DWORD src1_sel:WORD_1
	v_or_b32_sdwa v68, v68, v71 dst_sel:DWORD dst_unused:UNUSED_PAD src0_sel:DWORD src1_sel:WORD_1
	global_store_dwordx2 v[92:93], v[68:69], off offset:64
	global_load_dwordx4 v[70:73], v89, s[0:1] offset:192
	global_load_dwordx4 v[74:77], v89, s[4:5] offset:192
	v_mul_f32_e32 v68, 0xbfb8aa3b, v64
	v_mul_f32_e32 v69, 0xbfb8aa3b, v66
	v_exp_f32_e32 v78, v68
	v_exp_f32_e32 v79, v69
	v_pk_mul_f32 v[94:95], v[100:101], v[94:95] op_sel_hi:[1,0]
	v_mul_f32_e32 v68, 0xbfb8aa3b, v65
	v_mul_f32_e32 v69, 0xbfb8aa3b, v67
	v_exp_f32_e32 v68, v68
	v_exp_f32_e32 v69, v69
	s_waitcnt vmcnt(1)
	v_mov_b32_e32 v106, v70
	v_mov_b32_e32 v107, v72
	s_waitcnt vmcnt(0)
	v_mov_b32_e32 v110, v74
	v_mov_b32_e32 v111, v76
	v_pk_fma_f32 v[104:105], v[104:105], v[106:107], v[110:111]
	global_load_dwordx2 v[106:107], v[108:109], off offset:96
	v_mov_b32_e32 v72, v71
	v_mov_b32_e32 v76, v75
	v_pk_fma_f32 v[70:71], v[94:95], v[72:73], v[76:77]
	v_pk_add_f32 v[68:69], v[68:69], 1.0 op_sel_hi:[1,0]
	s_waitcnt vmcnt(0)
	v_and_b32_e32 v73, 0xffff0000, v107
	v_and_b32_e32 v72, 0xffff0000, v106
	v_pk_add_f32 v[70:71], v[70:71], v[72:73]
	v_pk_add_f32 v[72:73], v[78:79], 1.0 op_sel_hi:[1,0]
	v_lshlrev_b32_e32 v109, 16, v107
	v_lshlrev_b32_e32 v108, 16, v106
	v_pk_add_f32 v[104:105], v[104:105], v[108:109]
	v_rcp_f32_e32 v74, v73
	s_nop 0
	v_mul_f32_e32 v73, v66, v74
	s_nop 0
	v_rcp_f32_e32 v66, v72
	s_nop 0
	v_mul_f32_e32 v72, v64, v66
	v_pk_mul_f32 v[72:73], v[72:73], v[104:105]
	v_rcp_f32_e32 v64, v69
	s_nop 0
	v_mul_f32_e32 v67, v67, v64
	s_nop 0
	v_rcp_f32_e32 v64, v68
	s_nop 0
	v_mul_f32_e32 v66, v65, v64
	v_pk_mul_f32 v[64:65], v[66:67], v[70:71]
	v_and_b32_sdwa v66, v73, v154 dst_sel:DWORD dst_unused:UNUSED_PAD src0_sel:WORD_1 src1_sel:DWORD
	v_and_b32_sdwa v68, v65, v154 dst_sel:DWORD dst_unused:UNUSED_PAD src0_sel:WORD_1 src1_sel:DWORD
	v_and_b32_sdwa v69, v64, v154 dst_sel:DWORD dst_unused:UNUSED_PAD src0_sel:WORD_1 src1_sel:DWORD
	v_and_b32_sdwa v67, v72, v154 dst_sel:DWORD dst_unused:UNUSED_PAD src0_sel:WORD_1 src1_sel:DWORD
	v_add3_u32 v65, v65, v68, s33
	v_add3_u32 v64, v64, v69, s33
	v_add3_u32 v67, v72, v67, s33
	v_add3_u32 v66, v73, v66, s33
	v_and_b32_e32 v65, 0xffff0000, v65
	v_and_b32_e32 v64, 0xffff0000, v64
	v_or_b32_sdwa v65, v65, v66 dst_sel:DWORD dst_unused:UNUSED_PAD src0_sel:DWORD src1_sel:WORD_1
	v_or_b32_sdwa v64, v64, v67 dst_sel:DWORD dst_unused:UNUSED_PAD src0_sel:DWORD src1_sel:WORD_1
	global_store_dwordx2 v[92:93], v[64:65], off offset:96
	v_add_u32_e32 v64, 16, v88
	v_ashrrev_i32_e32 v65, 31, v64
	v_lshlrev_b64 v[76:77], 11, v[64:65]
	v_lshl_add_u64 v[66:67], v[90:91], 0, v[76:77]
	global_load_dwordx2 v[70:71], v[66:67], off
	global_load_dwordx2 v[68:69], v[66:67], off offset:32
	v_lshl_add_u64 v[76:77], s[8:9], 0, v[76:77]
	v_lshl_add_u64 v[76:77], v[76:77], 0, v[96:97]
	s_waitcnt vmcnt(1)
	v_lshlrev_b32_e32 v118, 16, v70
	s_waitcnt vmcnt(0)
	v_lshlrev_b32_e32 v107, 16, v68
	v_and_b32_e32 v103, 0xffff0000, v68
	v_alignbit_b32 v65, v69, v68, 16
	v_and_b32_e32 v105, 0xffff0000, v69
	global_load_dwordx2 v[68:69], v[66:67], off offset:64
	v_and_b32_e32 v109, 0xffff0000, v65
	v_and_b32_e32 v113, 0xffff0000, v71
	v_and_b32_e32 v116, 0xffff0000, v70
	v_mov_b32_e32 v112, v118
	v_mov_b32_e32 v117, v118
	v_mul_f32_e32 v110, v118, v118
	v_mul_f32_e32 v106, v107, v107
	v_mul_f32_e32 v102, v103, v103
	v_mul_f32_e32 v108, v109, v109
	v_mul_f32_e32 v104, v105, v105
	s_waitcnt vmcnt(0)
	v_lshlrev_b32_e32 v95, 16, v68
	v_and_b32_e32 v79, 0xffff0000, v68
	v_alignbit_b32 v65, v69, v68, 16
	v_and_b32_e32 v93, 0xffff0000, v69
	global_load_dwordx2 v[68:69], v[66:67], off offset:96
	v_and_b32_e32 v101, 0xffff0000, v65
	v_mul_f32_e32 v94, v95, v95
	v_mul_f32_e32 v78, v79, v79
	v_mul_f32_e32 v100, v101, v101
	v_mul_f32_e32 v92, v93, v93
	s_waitcnt vmcnt(0)
	v_alignbit_b32 v65, v69, v68, 16
	v_and_b32_e32 v75, 0xffff0000, v65
	v_alignbit_b32 v65, v71, v70, 16
	v_and_b32_e32 v71, 0xffff0000, v65
	v_and_b32_e32 v70, 16, v70
	v_mov_b32_e32 v65, v118
	v_pk_add_f32 v[114:115], v[70:71], v[112:113]
	v_pk_add_f32 v[120:121], v[116:117], v[64:65] op_sel_hi:[0,1]
	v_mov_b32_e32 v111, v115
	v_pk_mul_f32 v[114:115], v[116:117], v[116:117]
	v_mov_b32_e32 v112, v71
	v_mov_b32_e32 v115, v121
	global_load_dwordx4 v[120:123], v89, s[0:1]
	global_load_dwordx4 v[124:127], v89, s[4:5]
	v_mul_f32_e32 v70, v113, v113
	v_mov_b32_e32 v119, v71
	v_pk_fma_f32 v[70:71], v[112:113], v[112:113], v[70:71] op_sel_hi:[1,1,0]
	v_pk_add_f32 v[110:111], v[110:111], v[114:115]
	v_mov_b32_e32 v71, v97
	v_pk_add_f32 v[70:71], v[110:111], v[70:71]
	v_pk_add_f32 v[110:111], v[106:107], v[102:103]
	v_pk_add_f32 v[114:115], v[108:109], v[104:105]
	v_lshlrev_b32_e32 v73, 16, v68
	v_pk_add_f32 v[110:111], v[110:111], v[114:115]
	v_and_b32_e32 v67, 0xffff0000, v68
	v_and_b32_e32 v69, 0xffff0000, v69
	v_pk_add_f32 v[70:71], v[70:71], v[110:111]
	v_pk_add_f32 v[110:111], v[94:95], v[78:79]
	v_pk_add_f32 v[114:115], v[100:101], v[92:93]
	v_mul_f32_e32 v72, v73, v73
	v_mul_f32_e32 v66, v67, v67
	v_mul_f32_e32 v74, v75, v75
	v_mul_f32_e32 v68, v69, v69
	v_pk_add_f32 v[110:111], v[110:111], v[114:115]
	v_pk_add_f32 v[114:115], v[74:75], v[68:69]
	v_pk_add_f32 v[70:71], v[70:71], v[110:111]
	v_pk_add_f32 v[110:111], v[72:73], v[66:67]
	v_mul_f32_e32 v68, 0xbfb8aa3b, v60
	v_pk_add_f32 v[110:111], v[110:111], v[114:115]
	v_exp_f32_e32 v114, v68
	v_pk_add_f32 v[70:71], v[70:71], v[110:111]
	s_nop 0
	ds_bpermute_b32 v111, v184, v71
	ds_bpermute_b32 v110, v184, v70
	v_mul_f32_e32 v68, 0xbfb8aa3b, v61
	v_mov_b32_e32 v117, v113
	v_mov_b32_e32 v108, v107
	v_mov_b32_e32 v104, v103
	s_waitcnt lgkmcnt(0)
	v_pk_add_f32 v[70:71], v[70:71], v[110:111]
	s_nop 0
	ds_bpermute_b32 v111, v185, v71
	ds_bpermute_b32 v110, v185, v70
	v_mov_b32_e32 v100, v95
	s_waitcnt lgkmcnt(0)
	v_pk_add_f32 v[70:71], v[70:71], v[110:111]
	s_nop 0
	v_pk_mul_f32 v[70:71], v[70:71], s[38:39] op_sel_hi:[1,0]
	v_exp_f32_e32 v110, v68
	v_fma_f32 v65, -v71, v71, v70
	v_max_f32_e32 v65, 0, v65
	v_add_f32_e32 v65, 0x3a27c5ac, v65
	v_cmp_gt_f32_e32 vcc, s12, v65
	v_mul_f32_e32 v66, 0x4b800000, v65
	v_pk_add_f32 v[118:119], v[118:119], v[70:71] op_sel:[0,1] neg_lo:[0,1] neg_hi:[0,1]
	v_cndmask_b32_e32 v65, v65, v66, vcc
	v_rsq_f32_e32 v65, v65
	v_mul_f32_e32 v68, 0xbfb8aa3b, v62
	v_exp_f32_e32 v115, v68
	v_mul_f32_e32 v68, 0xbfb8aa3b, v63
	v_mul_f32_e32 v66, 0x45800000, v65
	v_cndmask_b32_e32 v66, v65, v66, vcc
	v_pk_mul_f32 v[118:119], v[118:119], v[66:67] op_sel_hi:[1,0]
	v_pk_add_f32 v[114:115], v[114:115], 1.0 op_sel_hi:[1,0]
	v_exp_f32_e32 v111, v68
	s_nop 0
	v_pk_add_f32 v[110:111], v[110:111], 1.0 op_sel_hi:[1,0]
	v_pk_add_f32 v[112:113], v[116:117], v[70:71] op_sel:[0,1] neg_lo:[0,1] neg_hi:[0,1]
	v_mad_i64_i32 v[64:65], s[10:11], v64, s13, v[86:87]
	v_rcp_f32_e32 v68, v115
	s_nop 0
	v_mul_f32_e32 v115, v62, v68
	s_waitcnt vmcnt(1)
	v_mov_b32_e32 v128, v120
	v_mov_b32_e32 v129, v122
	s_waitcnt vmcnt(0)
	v_mov_b32_e32 v130, v124
	v_mov_b32_e32 v131, v126
	v_pk_fma_f32 v[118:119], v[128:129], v[118:119], v[130:131]
	global_load_dwordx2 v[128:129], v[76:77], off
	v_pk_mul_f32 v[112:113], v[112:113], v[66:67] op_sel_hi:[1,0]
	v_mov_b32_e32 v122, v121
	v_mov_b32_e32 v126, v125
	v_rcp_f32_e32 v62, v114
	s_nop 0
	v_mul_f32_e32 v114, v60, v62
	v_pk_fma_f32 v[112:113], v[122:123], v[112:113], v[126:127]
	v_pk_add_f32 v[106:107], v[108:109], v[70:71] op_sel:[0,1] neg_lo:[0,1] neg_hi:[0,1]
	v_pk_add_f32 v[102:103], v[104:105], v[70:71] op_sel:[0,1] neg_lo:[0,1] neg_hi:[0,1]
	v_rcp_f32_e32 v60, v111
	s_nop 0
	v_mul_f32_e32 v63, v63, v60
	v_pk_mul_f32 v[106:107], v[106:107], v[66:67] op_sel_hi:[1,0]
	v_pk_mul_f32 v[102:103], v[102:103], v[66:67] op_sel_hi:[1,0]
	v_pk_add_f32 v[94:95], v[100:101], v[70:71] op_sel:[0,1] neg_lo:[0,1] neg_hi:[0,1]
	v_rcp_f32_e32 v60, v110
	s_nop 0
	v_mul_f32_e32 v62, v61, v60
	v_pk_mul_f32 v[94:95], v[94:95], v[66:67] op_sel_hi:[1,0]
	s_waitcnt vmcnt(0)
	v_and_b32_e32 v117, 0xffff0000, v129
	v_and_b32_e32 v116, 0xffff0000, v128
	v_lshlrev_b32_e32 v131, 16, v129
	v_lshlrev_b32_e32 v130, 16, v128
	v_pk_add_f32 v[112:113], v[112:113], v[116:117]
	v_pk_add_f32 v[118:119], v[118:119], v[130:131]
	v_pk_mul_f32 v[60:61], v[62:63], v[112:113]
	v_pk_mul_f32 v[114:115], v[114:115], v[118:119]
	v_and_b32_sdwa v68, v61, v154 dst_sel:DWORD dst_unused:UNUSED_PAD src0_sel:WORD_1 src1_sel:DWORD
	v_and_b32_sdwa v72, v60, v154 dst_sel:DWORD dst_unused:UNUSED_PAD src0_sel:WORD_1 src1_sel:DWORD
	v_and_b32_sdwa v62, v115, v154 dst_sel:DWORD dst_unused:UNUSED_PAD src0_sel:WORD_1 src1_sel:DWORD
	v_and_b32_sdwa v63, v114, v154 dst_sel:DWORD dst_unused:UNUSED_PAD src0_sel:WORD_1 src1_sel:DWORD
	v_add3_u32 v61, v61, v68, s33
	v_add3_u32 v60, v60, v72, s33
	v_add3_u32 v63, v114, v63, s33
	v_add3_u32 v62, v115, v62, s33
	v_and_b32_e32 v61, 0xffff0000, v61
	v_and_b32_e32 v60, 0xffff0000, v60
	v_or_b32_sdwa v61, v61, v62 dst_sel:DWORD dst_unused:UNUSED_PAD src0_sel:DWORD src1_sel:WORD_1
	v_or_b32_sdwa v60, v60, v63 dst_sel:DWORD dst_unused:UNUSED_PAD src0_sel:DWORD src1_sel:WORD_1
	global_store_dwordx2 v[64:65], v[60:61], off
	global_load_dwordx4 v[110:113], v89, s[0:1] offset:64
	global_load_dwordx4 v[114:117], v89, s[4:5] offset:64
	v_mul_f32_e32 v60, 0xbfb8aa3b, v56
	v_mul_f32_e32 v61, 0xbfb8aa3b, v58
	v_exp_f32_e32 v62, v60
	v_exp_f32_e32 v63, v61
	v_mul_f32_e32 v60, 0xbfb8aa3b, v57
	v_mul_f32_e32 v61, 0xbfb8aa3b, v59
	v_exp_f32_e32 v60, v60
	v_pk_add_f32 v[62:63], v[62:63], 1.0 op_sel_hi:[1,0]
	v_exp_f32_e32 v61, v61
	s_nop 0
	v_pk_add_f32 v[60:61], v[60:61], 1.0 op_sel_hi:[1,0]
	v_rcp_f32_e32 v68, v63
	s_nop 0
	v_mul_f32_e32 v63, v58, v68
	v_mov_b32_e32 v92, v79
	v_rcp_f32_e32 v58, v62
	s_nop 0
	v_mul_f32_e32 v62, v56, v58
	v_pk_add_f32 v[78:79], v[92:93], v[70:71] op_sel:[0,1] neg_lo:[0,1] neg_hi:[0,1]
	v_rcp_f32_e32 v56, v61
	s_nop 0
	v_mul_f32_e32 v59, v59, v56
	v_pk_mul_f32 v[78:79], v[78:79], v[66:67] op_sel_hi:[1,0]
	v_rcp_f32_e32 v56, v60
	s_nop 0
	v_mul_f32_e32 v58, v57, v56
	s_waitcnt vmcnt(1)
	v_mov_b32_e32 v108, v110
	v_mov_b32_e32 v109, v112
	s_waitcnt vmcnt(0)
	v_mov_b32_e32 v118, v114
	v_mov_b32_e32 v119, v116
	v_pk_fma_f32 v[106:107], v[106:107], v[108:109], v[118:119]
	global_load_dwordx2 v[108:109], v[76:77], off offset:32
	v_mov_b32_e32 v112, v111
	v_mov_b32_e32 v116, v115
	v_pk_fma_f32 v[102:103], v[102:103], v[112:113], v[116:117]
	s_waitcnt vmcnt(0)
	v_and_b32_e32 v105, 0xffff0000, v109
	v_and_b32_e32 v104, 0xffff0000, v108
	v_lshlrev_b32_e32 v119, 16, v109
	v_lshlrev_b32_e32 v118, 16, v108
	v_pk_add_f32 v[102:103], v[102:103], v[104:105]
	v_pk_add_f32 v[106:107], v[106:107], v[118:119]
	v_pk_mul_f32 v[56:57], v[58:59], v[102:103]
	v_pk_mul_f32 v[62:63], v[62:63], v[106:107]
	v_and_b32_sdwa v60, v57, v154 dst_sel:DWORD dst_unused:UNUSED_PAD src0_sel:WORD_1 src1_sel:DWORD
	v_and_b32_sdwa v61, v56, v154 dst_sel:DWORD dst_unused:UNUSED_PAD src0_sel:WORD_1 src1_sel:DWORD
	v_and_b32_sdwa v58, v63, v154 dst_sel:DWORD dst_unused:UNUSED_PAD src0_sel:WORD_1 src1_sel:DWORD
	v_and_b32_sdwa v59, v62, v154 dst_sel:DWORD dst_unused:UNUSED_PAD src0_sel:WORD_1 src1_sel:DWORD
	v_add3_u32 v57, v57, v60, s33
	v_add3_u32 v56, v56, v61, s33
	v_add3_u32 v59, v62, v59, s33
	v_add3_u32 v58, v63, v58, s33
	v_and_b32_e32 v57, 0xffff0000, v57
	v_and_b32_e32 v56, 0xffff0000, v56
	v_or_b32_sdwa v57, v57, v58 dst_sel:DWORD dst_unused:UNUSED_PAD src0_sel:DWORD src1_sel:WORD_1
	v_or_b32_sdwa v56, v56, v59 dst_sel:DWORD dst_unused:UNUSED_PAD src0_sel:DWORD src1_sel:WORD_1
	global_store_dwordx2 v[64:65], v[56:57], off offset:32
	global_load_dwordx4 v[58:61], v89, s[0:1] offset:128
	global_load_dwordx4 v[102:105], v89, s[4:5] offset:128
	v_mul_f32_e32 v56, 0xbfb8aa3b, v52
	v_mul_f32_e32 v57, 0xbfb8aa3b, v54
	v_exp_f32_e32 v62, v56
	v_exp_f32_e32 v63, v57
	v_mul_f32_e32 v56, 0xbfb8aa3b, v53
	v_mul_f32_e32 v57, 0xbfb8aa3b, v55
	v_exp_f32_e32 v56, v56
	v_exp_f32_e32 v57, v57
	s_waitcnt vmcnt(1)
	v_mov_b32_e32 v100, v58
	v_mov_b32_e32 v101, v60
	s_waitcnt vmcnt(0)
	v_mov_b32_e32 v106, v102
	v_mov_b32_e32 v107, v104
	v_pk_fma_f32 v[94:95], v[94:95], v[100:101], v[106:107]
	global_load_dwordx2 v[100:101], v[76:77], off offset:64
	v_mov_b32_e32 v60, v59
	v_mov_b32_e32 v104, v103
	v_pk_fma_f32 v[58:59], v[78:79], v[60:61], v[104:105]
	v_pk_add_f32 v[56:57], v[56:57], 1.0 op_sel_hi:[1,0]
	s_waitcnt vmcnt(0)
	v_and_b32_e32 v61, 0xffff0000, v101
	v_and_b32_e32 v60, 0xffff0000, v100
	v_pk_add_f32 v[58:59], v[58:59], v[60:61]
	v_pk_add_f32 v[60:61], v[62:63], 1.0 op_sel_hi:[1,0]
	v_lshlrev_b32_e32 v107, 16, v101
	v_lshlrev_b32_e32 v106, 16, v100
	v_pk_add_f32 v[94:95], v[94:95], v[106:107]
	v_rcp_f32_e32 v62, v61
	s_nop 0
	v_mul_f32_e32 v61, v54, v62
	v_mov_b32_e32 v74, v73
	v_rcp_f32_e32 v54, v60
	s_nop 0
	v_mul_f32_e32 v60, v52, v54
	v_pk_mul_f32 v[60:61], v[60:61], v[94:95]
	v_pk_add_f32 v[72:73], v[74:75], v[70:71] op_sel:[0,1] neg_lo:[0,1] neg_hi:[0,1]
	v_rcp_f32_e32 v52, v57
	s_nop 0
	v_mul_f32_e32 v55, v55, v52
	v_pk_mul_f32 v[72:73], v[72:73], v[66:67] op_sel_hi:[1,0]
	v_mov_b32_e32 v68, v67
	v_pk_add_f32 v[68:69], v[68:69], v[70:71] op_sel:[0,1] neg_lo:[0,1] neg_hi:[0,1]
	v_rcp_f32_e32 v52, v56
	s_nop 0
	v_mul_f32_e32 v54, v53, v52
	v_pk_mul_f32 v[52:53], v[54:55], v[58:59]
	v_and_b32_sdwa v54, v61, v154 dst_sel:DWORD dst_unused:UNUSED_PAD src0_sel:WORD_1 src1_sel:DWORD
	v_and_b32_sdwa v56, v53, v154 dst_sel:DWORD dst_unused:UNUSED_PAD src0_sel:WORD_1 src1_sel:DWORD
	v_and_b32_sdwa v57, v52, v154 dst_sel:DWORD dst_unused:UNUSED_PAD src0_sel:WORD_1 src1_sel:DWORD
	v_and_b32_sdwa v55, v60, v154 dst_sel:DWORD dst_unused:UNUSED_PAD src0_sel:WORD_1 src1_sel:DWORD
	v_add3_u32 v53, v53, v56, s33
	v_add3_u32 v52, v52, v57, s33
	v_add3_u32 v55, v60, v55, s33
	v_add3_u32 v54, v61, v54, s33
	v_and_b32_e32 v53, 0xffff0000, v53
	v_and_b32_e32 v52, 0xffff0000, v52
	v_or_b32_sdwa v53, v53, v54 dst_sel:DWORD dst_unused:UNUSED_PAD src0_sel:DWORD src1_sel:WORD_1
	v_or_b32_sdwa v52, v52, v55 dst_sel:DWORD dst_unused:UNUSED_PAD src0_sel:DWORD src1_sel:WORD_1
	global_store_dwordx2 v[64:65], v[52:53], off offset:64
	global_load_dwordx4 v[54:57], v89, s[0:1] offset:192
	global_load_dwordx4 v[58:61], v89, s[4:5] offset:192
	v_mul_f32_e32 v52, 0xbfb8aa3b, v48
	v_mul_f32_e32 v53, 0xbfb8aa3b, v50
	v_exp_f32_e32 v62, v52
	v_exp_f32_e32 v63, v53
	v_pk_mul_f32 v[66:67], v[68:69], v[66:67] op_sel_hi:[1,0]
	v_mul_f32_e32 v52, 0xbfb8aa3b, v49
	v_mul_f32_e32 v53, 0xbfb8aa3b, v51
	v_exp_f32_e32 v52, v52
	v_exp_f32_e32 v53, v53
	s_waitcnt vmcnt(1)
	v_mov_b32_e32 v74, v54
	v_mov_b32_e32 v75, v56
	s_waitcnt vmcnt(0)
	v_mov_b32_e32 v78, v58
	v_mov_b32_e32 v79, v60
	v_pk_fma_f32 v[72:73], v[72:73], v[74:75], v[78:79]
	global_load_dwordx2 v[74:75], v[76:77], off offset:96
	v_mov_b32_e32 v56, v55
	v_mov_b32_e32 v60, v59
	v_pk_fma_f32 v[54:55], v[66:67], v[56:57], v[60:61]
	v_pk_add_f32 v[52:53], v[52:53], 1.0 op_sel_hi:[1,0]
	s_waitcnt vmcnt(0)
	v_and_b32_e32 v57, 0xffff0000, v75
	v_and_b32_e32 v56, 0xffff0000, v74
	v_pk_add_f32 v[54:55], v[54:55], v[56:57]
	v_pk_add_f32 v[56:57], v[62:63], 1.0 op_sel_hi:[1,0]
	v_lshlrev_b32_e32 v77, 16, v75
	v_lshlrev_b32_e32 v76, 16, v74
	v_pk_add_f32 v[72:73], v[72:73], v[76:77]
	v_rcp_f32_e32 v58, v57
	s_nop 0
	v_mul_f32_e32 v57, v50, v58
	s_nop 0
	v_rcp_f32_e32 v50, v56
	s_nop 0
	v_mul_f32_e32 v56, v48, v50
	v_pk_mul_f32 v[56:57], v[56:57], v[72:73]
	v_rcp_f32_e32 v48, v53
	s_nop 0
	v_mul_f32_e32 v51, v51, v48
	s_nop 0
	v_rcp_f32_e32 v48, v52
	s_nop 0
	v_mul_f32_e32 v50, v49, v48
	v_pk_mul_f32 v[48:49], v[50:51], v[54:55]
	v_and_b32_sdwa v50, v57, v154 dst_sel:DWORD dst_unused:UNUSED_PAD src0_sel:WORD_1 src1_sel:DWORD
	v_and_b32_sdwa v52, v49, v154 dst_sel:DWORD dst_unused:UNUSED_PAD src0_sel:WORD_1 src1_sel:DWORD
	v_and_b32_sdwa v53, v48, v154 dst_sel:DWORD dst_unused:UNUSED_PAD src0_sel:WORD_1 src1_sel:DWORD
	v_and_b32_sdwa v51, v56, v154 dst_sel:DWORD dst_unused:UNUSED_PAD src0_sel:WORD_1 src1_sel:DWORD
	v_add3_u32 v49, v49, v52, s33
	v_add3_u32 v48, v48, v53, s33
	v_add3_u32 v51, v56, v51, s33
	v_add3_u32 v50, v57, v50, s33
	v_and_b32_e32 v49, 0xffff0000, v49
	v_and_b32_e32 v48, 0xffff0000, v48
	v_or_b32_sdwa v49, v49, v50 dst_sel:DWORD dst_unused:UNUSED_PAD src0_sel:DWORD src1_sel:WORD_1
	v_or_b32_sdwa v48, v48, v51 dst_sel:DWORD dst_unused:UNUSED_PAD src0_sel:DWORD src1_sel:WORD_1
	global_store_dwordx2 v[64:65], v[48:49], off offset:96
	v_add_u32_e32 v48, 32, v88
	v_ashrrev_i32_e32 v49, 31, v48
	v_lshlrev_b64 v[60:61], 11, v[48:49]
	v_lshl_add_u64 v[50:51], v[90:91], 0, v[60:61]
	global_load_dwordx2 v[54:55], v[50:51], off
	global_load_dwordx2 v[52:53], v[50:51], off offset:32
	v_lshl_add_u64 v[60:61], s[8:9], 0, v[60:61]
	v_lshl_add_u64 v[60:61], v[60:61], 0, v[96:97]
	s_waitcnt vmcnt(1)
	v_lshlrev_b32_e32 v102, 16, v54
	s_waitcnt vmcnt(0)
	v_lshlrev_b32_e32 v75, 16, v52
	v_and_b32_e32 v71, 0xffff0000, v52
	v_alignbit_b32 v49, v53, v52, 16
	v_and_b32_e32 v73, 0xffff0000, v53
	global_load_dwordx2 v[52:53], v[50:51], off offset:64
	v_and_b32_e32 v77, 0xffff0000, v49
	v_and_b32_e32 v93, 0xffff0000, v55
	v_and_b32_e32 v100, 0xffff0000, v54
	v_mov_b32_e32 v92, v102
	v_mov_b32_e32 v101, v102
	v_mul_f32_e32 v78, v102, v102
	v_mul_f32_e32 v74, v75, v75
	v_mul_f32_e32 v70, v71, v71
	v_mul_f32_e32 v76, v77, v77
	v_mul_f32_e32 v72, v73, v73
	s_waitcnt vmcnt(0)
	v_lshlrev_b32_e32 v67, 16, v52
	v_and_b32_e32 v63, 0xffff0000, v52
	v_alignbit_b32 v49, v53, v52, 16
	v_and_b32_e32 v65, 0xffff0000, v53
	global_load_dwordx2 v[52:53], v[50:51], off offset:96
	v_and_b32_e32 v69, 0xffff0000, v49
	v_mul_f32_e32 v66, v67, v67
	v_mul_f32_e32 v62, v63, v63
	v_mul_f32_e32 v68, v69, v69
	v_mul_f32_e32 v64, v65, v65
	s_waitcnt vmcnt(0)
	v_alignbit_b32 v49, v53, v52, 16
	v_and_b32_e32 v59, 0xffff0000, v49
	v_alignbit_b32 v49, v55, v54, 16
	v_and_b32_e32 v55, 0xffff0000, v49
	v_and_b32_e32 v54, 16, v54
	v_mov_b32_e32 v49, v102
	v_pk_add_f32 v[94:95], v[54:55], v[92:93]
	v_pk_add_f32 v[104:105], v[100:101], v[48:49] op_sel_hi:[0,1]
	v_mov_b32_e32 v79, v95
	v_pk_mul_f32 v[94:95], v[100:101], v[100:101]
	v_mov_b32_e32 v92, v55
	v_mov_b32_e32 v95, v105
	global_load_dwordx4 v[104:107], v89, s[0:1]
	global_load_dwordx4 v[108:111], v89, s[4:5]
	v_mul_f32_e32 v54, v93, v93
	v_mov_b32_e32 v103, v55
	v_pk_fma_f32 v[54:55], v[92:93], v[92:93], v[54:55] op_sel_hi:[1,1,0]
	v_pk_add_f32 v[78:79], v[78:79], v[94:95]
	v_mov_b32_e32 v55, v97
	v_pk_add_f32 v[54:55], v[78:79], v[54:55]
	v_pk_add_f32 v[78:79], v[74:75], v[70:71]
	v_pk_add_f32 v[94:95], v[76:77], v[72:73]
	v_lshlrev_b32_e32 v57, 16, v52
	v_pk_add_f32 v[78:79], v[78:79], v[94:95]
	v_and_b32_e32 v51, 0xffff0000, v52
	v_and_b32_e32 v53, 0xffff0000, v53
	v_pk_add_f32 v[54:55], v[54:55], v[78:79]
	v_pk_add_f32 v[78:79], v[66:67], v[62:63]
	v_pk_add_f32 v[94:95], v[68:69], v[64:65]
	v_mul_f32_e32 v56, v57, v57
	v_mul_f32_e32 v50, v51, v51
	v_mul_f32_e32 v58, v59, v59
	v_mul_f32_e32 v52, v53, v53
	v_pk_add_f32 v[78:79], v[78:79], v[94:95]
	v_pk_add_f32 v[94:95], v[58:59], v[52:53]
	v_pk_add_f32 v[54:55], v[54:55], v[78:79]
	v_pk_add_f32 v[78:79], v[56:57], v[50:51]
	v_mul_f32_e32 v52, 0xbfb8aa3b, v44
	v_pk_add_f32 v[78:79], v[78:79], v[94:95]
	v_exp_f32_e32 v94, v52
	v_pk_add_f32 v[54:55], v[54:55], v[78:79]
	s_nop 0
	ds_bpermute_b32 v79, v184, v55
	ds_bpermute_b32 v78, v184, v54
	v_mul_f32_e32 v52, 0xbfb8aa3b, v45
	v_mov_b32_e32 v101, v93
	v_mov_b32_e32 v76, v75
	v_mov_b32_e32 v72, v71
	s_waitcnt lgkmcnt(0)
	v_pk_add_f32 v[54:55], v[54:55], v[78:79]
	s_nop 0
	ds_bpermute_b32 v79, v185, v55
	ds_bpermute_b32 v78, v185, v54
	v_mov_b32_e32 v68, v67
	s_waitcnt lgkmcnt(0)
	v_pk_add_f32 v[54:55], v[54:55], v[78:79]
	s_nop 0
	v_pk_mul_f32 v[54:55], v[54:55], s[38:39] op_sel_hi:[1,0]
	v_exp_f32_e32 v78, v52
	v_fma_f32 v49, -v55, v55, v54
	v_max_f32_e32 v49, 0, v49
	v_add_f32_e32 v49, 0x3a27c5ac, v49
	v_cmp_gt_f32_e32 vcc, s12, v49
	v_mul_f32_e32 v50, 0x4b800000, v49
	v_pk_add_f32 v[102:103], v[102:103], v[54:55] op_sel:[0,1] neg_lo:[0,1] neg_hi:[0,1]
	v_cndmask_b32_e32 v49, v49, v50, vcc
	v_rsq_f32_e32 v49, v49
	v_mul_f32_e32 v52, 0xbfb8aa3b, v46
	v_exp_f32_e32 v95, v52
	v_mul_f32_e32 v52, 0xbfb8aa3b, v47
	v_mul_f32_e32 v50, 0x45800000, v49
	v_cndmask_b32_e32 v50, v49, v50, vcc
	v_pk_mul_f32 v[102:103], v[102:103], v[50:51] op_sel_hi:[1,0]
	v_pk_add_f32 v[94:95], v[94:95], 1.0 op_sel_hi:[1,0]
	v_exp_f32_e32 v79, v52
	s_nop 0
	v_pk_add_f32 v[78:79], v[78:79], 1.0 op_sel_hi:[1,0]
	v_pk_add_f32 v[92:93], v[100:101], v[54:55] op_sel:[0,1] neg_lo:[0,1] neg_hi:[0,1]
	v_mad_i64_i32 v[48:49], s[10:11], v48, s13, v[86:87]
	v_rcp_f32_e32 v52, v95
	s_nop 0
	v_mul_f32_e32 v95, v46, v52
	s_waitcnt vmcnt(1)
	v_mov_b32_e32 v112, v104
	v_mov_b32_e32 v113, v106
	s_waitcnt vmcnt(0)
	v_mov_b32_e32 v114, v108
	v_mov_b32_e32 v115, v110
	v_pk_fma_f32 v[102:103], v[112:113], v[102:103], v[114:115]
	global_load_dwordx2 v[112:113], v[60:61], off
	v_pk_mul_f32 v[92:93], v[92:93], v[50:51] op_sel_hi:[1,0]
	v_mov_b32_e32 v106, v105
	v_mov_b32_e32 v110, v109
	v_rcp_f32_e32 v46, v94
	s_nop 0
	v_mul_f32_e32 v94, v44, v46
	v_pk_fma_f32 v[92:93], v[106:107], v[92:93], v[110:111]
	v_pk_add_f32 v[74:75], v[76:77], v[54:55] op_sel:[0,1] neg_lo:[0,1] neg_hi:[0,1]
	v_pk_add_f32 v[70:71], v[72:73], v[54:55] op_sel:[0,1] neg_lo:[0,1] neg_hi:[0,1]
	v_rcp_f32_e32 v44, v79
	s_nop 0
	v_mul_f32_e32 v47, v47, v44
	v_pk_mul_f32 v[74:75], v[74:75], v[50:51] op_sel_hi:[1,0]
	v_pk_mul_f32 v[70:71], v[70:71], v[50:51] op_sel_hi:[1,0]
	v_pk_add_f32 v[66:67], v[68:69], v[54:55] op_sel:[0,1] neg_lo:[0,1] neg_hi:[0,1]
	v_rcp_f32_e32 v44, v78
	s_nop 0
	v_mul_f32_e32 v46, v45, v44
	v_pk_mul_f32 v[66:67], v[66:67], v[50:51] op_sel_hi:[1,0]
	s_waitcnt vmcnt(0)
	v_and_b32_e32 v101, 0xffff0000, v113
	v_and_b32_e32 v100, 0xffff0000, v112
	v_lshlrev_b32_e32 v115, 16, v113
	v_lshlrev_b32_e32 v114, 16, v112
	v_pk_add_f32 v[92:93], v[92:93], v[100:101]
	v_pk_add_f32 v[102:103], v[102:103], v[114:115]
	v_pk_mul_f32 v[44:45], v[46:47], v[92:93]
	v_pk_mul_f32 v[94:95], v[94:95], v[102:103]
	v_and_b32_sdwa v52, v45, v154 dst_sel:DWORD dst_unused:UNUSED_PAD src0_sel:WORD_1 src1_sel:DWORD
	v_and_b32_sdwa v56, v44, v154 dst_sel:DWORD dst_unused:UNUSED_PAD src0_sel:WORD_1 src1_sel:DWORD
	v_and_b32_sdwa v46, v95, v154 dst_sel:DWORD dst_unused:UNUSED_PAD src0_sel:WORD_1 src1_sel:DWORD
	v_and_b32_sdwa v47, v94, v154 dst_sel:DWORD dst_unused:UNUSED_PAD src0_sel:WORD_1 src1_sel:DWORD
	v_add3_u32 v45, v45, v52, s33
	v_add3_u32 v44, v44, v56, s33
	v_add3_u32 v47, v94, v47, s33
	v_add3_u32 v46, v95, v46, s33
	v_and_b32_e32 v45, 0xffff0000, v45
	v_and_b32_e32 v44, 0xffff0000, v44
	v_or_b32_sdwa v45, v45, v46 dst_sel:DWORD dst_unused:UNUSED_PAD src0_sel:DWORD src1_sel:WORD_1
	v_or_b32_sdwa v44, v44, v47 dst_sel:DWORD dst_unused:UNUSED_PAD src0_sel:DWORD src1_sel:WORD_1
	global_store_dwordx2 v[48:49], v[44:45], off
	global_load_dwordx4 v[92:95], v89, s[0:1] offset:64
	global_load_dwordx4 v[100:103], v89, s[4:5] offset:64
	v_mul_f32_e32 v44, 0xbfb8aa3b, v40
	v_mul_f32_e32 v45, 0xbfb8aa3b, v42
	v_exp_f32_e32 v46, v44
	v_exp_f32_e32 v47, v45
	v_mul_f32_e32 v44, 0xbfb8aa3b, v41
	v_mul_f32_e32 v45, 0xbfb8aa3b, v43
	v_exp_f32_e32 v44, v44
	v_pk_add_f32 v[46:47], v[46:47], 1.0 op_sel_hi:[1,0]
	v_exp_f32_e32 v45, v45
	s_nop 0
	v_pk_add_f32 v[44:45], v[44:45], 1.0 op_sel_hi:[1,0]
	v_rcp_f32_e32 v52, v47
	s_nop 0
	v_mul_f32_e32 v47, v42, v52
	v_mov_b32_e32 v64, v63
	v_rcp_f32_e32 v42, v46
	s_nop 0
	v_mul_f32_e32 v46, v40, v42
	v_pk_add_f32 v[62:63], v[64:65], v[54:55] op_sel:[0,1] neg_lo:[0,1] neg_hi:[0,1]
	v_rcp_f32_e32 v40, v45
	s_nop 0
	v_mul_f32_e32 v43, v43, v40
	v_pk_mul_f32 v[62:63], v[62:63], v[50:51] op_sel_hi:[1,0]
	v_rcp_f32_e32 v40, v44
	s_nop 0
	v_mul_f32_e32 v42, v41, v40
	s_waitcnt vmcnt(1)
	v_mov_b32_e32 v76, v92
	v_mov_b32_e32 v77, v94
	s_waitcnt vmcnt(0)
	v_mov_b32_e32 v78, v100
	v_mov_b32_e32 v79, v102
	v_pk_fma_f32 v[74:75], v[74:75], v[76:77], v[78:79]
	global_load_dwordx2 v[76:77], v[60:61], off offset:32
	v_mov_b32_e32 v94, v93
	v_mov_b32_e32 v102, v101
	v_pk_fma_f32 v[70:71], v[70:71], v[94:95], v[102:103]
	s_waitcnt vmcnt(0)
	v_and_b32_e32 v73, 0xffff0000, v77
	v_and_b32_e32 v72, 0xffff0000, v76
	v_lshlrev_b32_e32 v79, 16, v77
	v_lshlrev_b32_e32 v78, 16, v76
	v_pk_add_f32 v[70:71], v[70:71], v[72:73]
	v_pk_add_f32 v[74:75], v[74:75], v[78:79]
	v_pk_mul_f32 v[40:41], v[42:43], v[70:71]
	v_pk_mul_f32 v[46:47], v[46:47], v[74:75]
	v_and_b32_sdwa v44, v41, v154 dst_sel:DWORD dst_unused:UNUSED_PAD src0_sel:WORD_1 src1_sel:DWORD
	v_and_b32_sdwa v45, v40, v154 dst_sel:DWORD dst_unused:UNUSED_PAD src0_sel:WORD_1 src1_sel:DWORD
	v_and_b32_sdwa v42, v47, v154 dst_sel:DWORD dst_unused:UNUSED_PAD src0_sel:WORD_1 src1_sel:DWORD
	v_and_b32_sdwa v43, v46, v154 dst_sel:DWORD dst_unused:UNUSED_PAD src0_sel:WORD_1 src1_sel:DWORD
	v_add3_u32 v41, v41, v44, s33
	v_add3_u32 v40, v40, v45, s33
	v_add3_u32 v43, v46, v43, s33
	v_add3_u32 v42, v47, v42, s33
	v_and_b32_e32 v41, 0xffff0000, v41
	v_and_b32_e32 v40, 0xffff0000, v40
	v_or_b32_sdwa v41, v41, v42 dst_sel:DWORD dst_unused:UNUSED_PAD src0_sel:DWORD src1_sel:WORD_1
	v_or_b32_sdwa v40, v40, v43 dst_sel:DWORD dst_unused:UNUSED_PAD src0_sel:DWORD src1_sel:WORD_1
	global_store_dwordx2 v[48:49], v[40:41], off offset:32
	global_load_dwordx4 v[42:45], v89, s[0:1] offset:128
	global_load_dwordx4 v[70:73], v89, s[4:5] offset:128
	v_mul_f32_e32 v40, 0xbfb8aa3b, v36
	v_mul_f32_e32 v41, 0xbfb8aa3b, v38
	v_exp_f32_e32 v46, v40
	v_exp_f32_e32 v47, v41
	v_mul_f32_e32 v40, 0xbfb8aa3b, v37
	v_mul_f32_e32 v41, 0xbfb8aa3b, v39
	v_exp_f32_e32 v40, v40
	v_exp_f32_e32 v41, v41
	s_waitcnt vmcnt(1)
	v_mov_b32_e32 v68, v42
	v_mov_b32_e32 v69, v44
	s_waitcnt vmcnt(0)
	v_mov_b32_e32 v74, v70
	v_mov_b32_e32 v75, v72
	v_pk_fma_f32 v[66:67], v[66:67], v[68:69], v[74:75]
	global_load_dwordx2 v[68:69], v[60:61], off offset:64
	v_mov_b32_e32 v44, v43
	v_mov_b32_e32 v72, v71
	v_pk_fma_f32 v[42:43], v[62:63], v[44:45], v[72:73]
	v_pk_add_f32 v[40:41], v[40:41], 1.0 op_sel_hi:[1,0]
	s_waitcnt vmcnt(0)
	v_and_b32_e32 v45, 0xffff0000, v69
	v_and_b32_e32 v44, 0xffff0000, v68
	v_pk_add_f32 v[42:43], v[42:43], v[44:45]
	v_pk_add_f32 v[44:45], v[46:47], 1.0 op_sel_hi:[1,0]
	v_lshlrev_b32_e32 v75, 16, v69
	v_lshlrev_b32_e32 v74, 16, v68
	v_pk_add_f32 v[66:67], v[66:67], v[74:75]
	v_rcp_f32_e32 v46, v45
	s_nop 0
	v_mul_f32_e32 v45, v38, v46
	v_mov_b32_e32 v58, v57
	v_rcp_f32_e32 v38, v44
	s_nop 0
	v_mul_f32_e32 v44, v36, v38
	v_pk_mul_f32 v[44:45], v[44:45], v[66:67]
	v_pk_add_f32 v[56:57], v[58:59], v[54:55] op_sel:[0,1] neg_lo:[0,1] neg_hi:[0,1]
	v_rcp_f32_e32 v36, v41
	s_nop 0
	v_mul_f32_e32 v39, v39, v36
	v_pk_mul_f32 v[56:57], v[56:57], v[50:51] op_sel_hi:[1,0]
	v_mov_b32_e32 v52, v51
	v_pk_add_f32 v[52:53], v[52:53], v[54:55] op_sel:[0,1] neg_lo:[0,1] neg_hi:[0,1]
	v_rcp_f32_e32 v36, v40
	s_nop 0
	v_mul_f32_e32 v38, v37, v36
	v_pk_mul_f32 v[36:37], v[38:39], v[42:43]
	v_and_b32_sdwa v38, v45, v154 dst_sel:DWORD dst_unused:UNUSED_PAD src0_sel:WORD_1 src1_sel:DWORD
	v_and_b32_sdwa v40, v37, v154 dst_sel:DWORD dst_unused:UNUSED_PAD src0_sel:WORD_1 src1_sel:DWORD
	v_and_b32_sdwa v41, v36, v154 dst_sel:DWORD dst_unused:UNUSED_PAD src0_sel:WORD_1 src1_sel:DWORD
	v_and_b32_sdwa v39, v44, v154 dst_sel:DWORD dst_unused:UNUSED_PAD src0_sel:WORD_1 src1_sel:DWORD
	v_add3_u32 v37, v37, v40, s33
	v_add3_u32 v36, v36, v41, s33
	v_add3_u32 v39, v44, v39, s33
	v_add3_u32 v38, v45, v38, s33
	v_and_b32_e32 v37, 0xffff0000, v37
	v_and_b32_e32 v36, 0xffff0000, v36
	v_or_b32_sdwa v37, v37, v38 dst_sel:DWORD dst_unused:UNUSED_PAD src0_sel:DWORD src1_sel:WORD_1
	v_or_b32_sdwa v36, v36, v39 dst_sel:DWORD dst_unused:UNUSED_PAD src0_sel:DWORD src1_sel:WORD_1
	global_store_dwordx2 v[48:49], v[36:37], off offset:64
	global_load_dwordx4 v[38:41], v89, s[0:1] offset:192
	global_load_dwordx4 v[42:45], v89, s[4:5] offset:192
	v_mul_f32_e32 v36, 0xbfb8aa3b, v32
	v_mul_f32_e32 v37, 0xbfb8aa3b, v34
	v_exp_f32_e32 v46, v36
	v_exp_f32_e32 v47, v37
	v_pk_mul_f32 v[50:51], v[52:53], v[50:51] op_sel_hi:[1,0]
	v_mul_f32_e32 v36, 0xbfb8aa3b, v33
	v_mul_f32_e32 v37, 0xbfb8aa3b, v35
	v_exp_f32_e32 v36, v36
	v_exp_f32_e32 v37, v37
	s_waitcnt vmcnt(1)
	v_mov_b32_e32 v58, v38
	v_mov_b32_e32 v59, v40
	s_waitcnt vmcnt(0)
	v_mov_b32_e32 v62, v42
	v_mov_b32_e32 v63, v44
	v_pk_fma_f32 v[56:57], v[56:57], v[58:59], v[62:63]
	global_load_dwordx2 v[58:59], v[60:61], off offset:96
	v_mov_b32_e32 v40, v39
	v_mov_b32_e32 v44, v43
	v_pk_fma_f32 v[38:39], v[50:51], v[40:41], v[44:45]
	v_pk_add_f32 v[36:37], v[36:37], 1.0 op_sel_hi:[1,0]
	s_waitcnt vmcnt(0)
	v_and_b32_e32 v41, 0xffff0000, v59
	v_and_b32_e32 v40, 0xffff0000, v58
	v_pk_add_f32 v[38:39], v[38:39], v[40:41]
	v_pk_add_f32 v[40:41], v[46:47], 1.0 op_sel_hi:[1,0]
	v_lshlrev_b32_e32 v61, 16, v59
	v_lshlrev_b32_e32 v60, 16, v58
	v_pk_add_f32 v[56:57], v[56:57], v[60:61]
	v_rcp_f32_e32 v42, v41
	s_nop 0
	v_mul_f32_e32 v41, v34, v42
	s_nop 0
	v_rcp_f32_e32 v34, v40
	s_nop 0
	v_mul_f32_e32 v40, v32, v34
	v_pk_mul_f32 v[40:41], v[40:41], v[56:57]
	v_rcp_f32_e32 v32, v37
	s_nop 0
	v_mul_f32_e32 v35, v35, v32
	s_nop 0
	v_rcp_f32_e32 v32, v36
	s_nop 0
	v_mul_f32_e32 v34, v33, v32
	v_pk_mul_f32 v[32:33], v[34:35], v[38:39]
	v_and_b32_sdwa v34, v41, v154 dst_sel:DWORD dst_unused:UNUSED_PAD src0_sel:WORD_1 src1_sel:DWORD
	v_and_b32_sdwa v36, v33, v154 dst_sel:DWORD dst_unused:UNUSED_PAD src0_sel:WORD_1 src1_sel:DWORD
	v_and_b32_sdwa v37, v32, v154 dst_sel:DWORD dst_unused:UNUSED_PAD src0_sel:WORD_1 src1_sel:DWORD
	v_and_b32_sdwa v35, v40, v154 dst_sel:DWORD dst_unused:UNUSED_PAD src0_sel:WORD_1 src1_sel:DWORD
	v_add3_u32 v33, v33, v36, s33
	v_add3_u32 v32, v32, v37, s33
	v_add3_u32 v35, v40, v35, s33
	v_add3_u32 v34, v41, v34, s33
	v_and_b32_e32 v33, 0xffff0000, v33
	v_and_b32_e32 v32, 0xffff0000, v32
	v_or_b32_sdwa v33, v33, v34 dst_sel:DWORD dst_unused:UNUSED_PAD src0_sel:DWORD src1_sel:WORD_1
	v_or_b32_sdwa v32, v32, v35 dst_sel:DWORD dst_unused:UNUSED_PAD src0_sel:DWORD src1_sel:WORD_1
	global_store_dwordx2 v[48:49], v[32:33], off offset:96
	v_add_u32_e32 v32, 48, v88
	v_ashrrev_i32_e32 v33, 31, v32
	v_lshlrev_b64 v[44:45], 11, v[32:33]
	v_lshl_add_u64 v[34:35], v[90:91], 0, v[44:45]
	global_load_dwordx2 v[38:39], v[34:35], off
	global_load_dwordx2 v[36:37], v[34:35], off offset:32
	v_lshl_add_u64 v[44:45], s[8:9], 0, v[44:45]
	v_lshl_add_u64 v[44:45], v[44:45], 0, v[96:97]
	s_waitcnt vmcnt(1)
	v_lshlrev_b32_e32 v70, 16, v38
	s_waitcnt vmcnt(0)
	v_lshlrev_b32_e32 v59, 16, v36
	v_and_b32_e32 v55, 0xffff0000, v36
	v_alignbit_b32 v33, v37, v36, 16
	v_and_b32_e32 v57, 0xffff0000, v37
	global_load_dwordx2 v[36:37], v[34:35], off offset:64
	v_and_b32_e32 v61, 0xffff0000, v33
	v_and_b32_e32 v65, 0xffff0000, v39
	v_and_b32_e32 v68, 0xffff0000, v38
	v_mov_b32_e32 v64, v70
	v_mov_b32_e32 v69, v70
	v_mul_f32_e32 v62, v70, v70
	v_mul_f32_e32 v58, v59, v59
	v_mul_f32_e32 v54, v55, v55
	v_mul_f32_e32 v60, v61, v61
	v_mul_f32_e32 v56, v57, v57
	s_waitcnt vmcnt(0)
	v_lshlrev_b32_e32 v51, 16, v36
	v_and_b32_e32 v47, 0xffff0000, v36
	v_alignbit_b32 v33, v37, v36, 16
	v_and_b32_e32 v49, 0xffff0000, v37
	global_load_dwordx2 v[36:37], v[34:35], off offset:96
	v_and_b32_e32 v53, 0xffff0000, v33
	v_mul_f32_e32 v50, v51, v51
	v_mul_f32_e32 v46, v47, v47
	v_mul_f32_e32 v52, v53, v53
	v_mul_f32_e32 v48, v49, v49
	s_waitcnt vmcnt(0)
	v_alignbit_b32 v33, v37, v36, 16
	v_and_b32_e32 v43, 0xffff0000, v33
	v_alignbit_b32 v33, v39, v38, 16
	v_and_b32_e32 v39, 0xffff0000, v33
	v_and_b32_e32 v38, 16, v38
	v_mov_b32_e32 v33, v70
	v_pk_add_f32 v[66:67], v[38:39], v[64:65]
	v_pk_add_f32 v[72:73], v[68:69], v[32:33] op_sel_hi:[0,1]
	v_mov_b32_e32 v63, v67
	v_pk_mul_f32 v[66:67], v[68:69], v[68:69]
	v_mov_b32_e32 v64, v39
	v_mov_b32_e32 v67, v73
	global_load_dwordx4 v[72:75], v89, s[0:1]
	global_load_dwordx4 v[76:79], v89, s[4:5]
	v_mul_f32_e32 v38, v65, v65
	v_mov_b32_e32 v71, v39
	v_pk_fma_f32 v[38:39], v[64:65], v[64:65], v[38:39] op_sel_hi:[1,1,0]
	v_pk_add_f32 v[62:63], v[62:63], v[66:67]
	v_mov_b32_e32 v39, v97
	v_pk_add_f32 v[38:39], v[62:63], v[38:39]
	v_pk_add_f32 v[62:63], v[58:59], v[54:55]
	v_pk_add_f32 v[66:67], v[60:61], v[56:57]
	v_lshlrev_b32_e32 v41, 16, v36
	v_pk_add_f32 v[62:63], v[62:63], v[66:67]
	v_and_b32_e32 v35, 0xffff0000, v36
	v_and_b32_e32 v37, 0xffff0000, v37
	v_pk_add_f32 v[38:39], v[38:39], v[62:63]
	v_pk_add_f32 v[62:63], v[50:51], v[46:47]
	v_pk_add_f32 v[66:67], v[52:53], v[48:49]
	v_mul_f32_e32 v40, v41, v41
	v_mul_f32_e32 v34, v35, v35
	v_mul_f32_e32 v42, v43, v43
	v_mul_f32_e32 v36, v37, v37
	v_pk_add_f32 v[62:63], v[62:63], v[66:67]
	v_pk_add_f32 v[66:67], v[42:43], v[36:37]
	v_pk_add_f32 v[38:39], v[38:39], v[62:63]
	v_pk_add_f32 v[62:63], v[40:41], v[34:35]
	v_mul_f32_e32 v36, 0xbfb8aa3b, v28
	v_pk_add_f32 v[62:63], v[62:63], v[66:67]
	v_exp_f32_e32 v66, v36
	v_pk_add_f32 v[38:39], v[38:39], v[62:63]
	s_nop 0
	ds_bpermute_b32 v63, v184, v39
	ds_bpermute_b32 v62, v184, v38
	v_mul_f32_e32 v36, 0xbfb8aa3b, v29
	v_mov_b32_e32 v69, v65
	v_mov_b32_e32 v60, v59
	v_mov_b32_e32 v56, v55
	s_waitcnt lgkmcnt(0)
	v_pk_add_f32 v[38:39], v[38:39], v[62:63]
	s_nop 0
	ds_bpermute_b32 v63, v185, v39
	ds_bpermute_b32 v62, v185, v38
	v_mov_b32_e32 v52, v51
	s_waitcnt lgkmcnt(0)
	v_pk_add_f32 v[38:39], v[38:39], v[62:63]
	s_nop 0
	v_pk_mul_f32 v[38:39], v[38:39], s[38:39] op_sel_hi:[1,0]
	v_exp_f32_e32 v62, v36
	v_fma_f32 v33, -v39, v39, v38
	v_max_f32_e32 v33, 0, v33
	v_add_f32_e32 v33, 0x3a27c5ac, v33
	v_cmp_gt_f32_e32 vcc, s12, v33
	v_mul_f32_e32 v34, 0x4b800000, v33
	v_pk_add_f32 v[70:71], v[70:71], v[38:39] op_sel:[0,1] neg_lo:[0,1] neg_hi:[0,1]
	v_cndmask_b32_e32 v33, v33, v34, vcc
	v_rsq_f32_e32 v33, v33
	v_mul_f32_e32 v36, 0xbfb8aa3b, v30
	v_exp_f32_e32 v67, v36
	v_mul_f32_e32 v36, 0xbfb8aa3b, v31
	v_mul_f32_e32 v34, 0x45800000, v33
	v_cndmask_b32_e32 v34, v33, v34, vcc
	v_pk_mul_f32 v[70:71], v[70:71], v[34:35] op_sel_hi:[1,0]
	v_pk_add_f32 v[66:67], v[66:67], 1.0 op_sel_hi:[1,0]
	v_exp_f32_e32 v63, v36
	s_nop 0
	v_pk_add_f32 v[62:63], v[62:63], 1.0 op_sel_hi:[1,0]
	v_pk_add_f32 v[64:65], v[68:69], v[38:39] op_sel:[0,1] neg_lo:[0,1] neg_hi:[0,1]
	v_mad_i64_i32 v[32:33], s[10:11], v32, s13, v[86:87]
	v_rcp_f32_e32 v36, v67
	s_nop 0
	v_mul_f32_e32 v67, v30, v36
	s_waitcnt vmcnt(1)
	v_mov_b32_e32 v92, v72
	v_mov_b32_e32 v93, v74
	s_waitcnt vmcnt(0)
	v_mov_b32_e32 v94, v76
	v_mov_b32_e32 v95, v78
	v_pk_fma_f32 v[70:71], v[92:93], v[70:71], v[94:95]
	global_load_dwordx2 v[92:93], v[44:45], off
	v_pk_mul_f32 v[64:65], v[64:65], v[34:35] op_sel_hi:[1,0]
	v_mov_b32_e32 v74, v73
	v_mov_b32_e32 v78, v77
	v_rcp_f32_e32 v30, v66
	s_nop 0
	v_mul_f32_e32 v66, v28, v30
	v_pk_fma_f32 v[64:65], v[74:75], v[64:65], v[78:79]
	v_pk_add_f32 v[58:59], v[60:61], v[38:39] op_sel:[0,1] neg_lo:[0,1] neg_hi:[0,1]
	v_pk_add_f32 v[54:55], v[56:57], v[38:39] op_sel:[0,1] neg_lo:[0,1] neg_hi:[0,1]
	v_rcp_f32_e32 v28, v63
	s_nop 0
	v_mul_f32_e32 v31, v31, v28
	v_pk_mul_f32 v[58:59], v[58:59], v[34:35] op_sel_hi:[1,0]
	v_pk_mul_f32 v[54:55], v[54:55], v[34:35] op_sel_hi:[1,0]
	v_pk_add_f32 v[50:51], v[52:53], v[38:39] op_sel:[0,1] neg_lo:[0,1] neg_hi:[0,1]
	v_rcp_f32_e32 v28, v62
	s_nop 0
	v_mul_f32_e32 v30, v29, v28
	v_pk_mul_f32 v[50:51], v[50:51], v[34:35] op_sel_hi:[1,0]
	s_waitcnt vmcnt(0)
	v_and_b32_e32 v69, 0xffff0000, v93
	v_and_b32_e32 v68, 0xffff0000, v92
	v_lshlrev_b32_e32 v95, 16, v93
	v_lshlrev_b32_e32 v94, 16, v92
	v_pk_add_f32 v[64:65], v[64:65], v[68:69]
	v_pk_add_f32 v[70:71], v[70:71], v[94:95]
	v_pk_mul_f32 v[28:29], v[30:31], v[64:65]
	v_pk_mul_f32 v[66:67], v[66:67], v[70:71]
	v_and_b32_sdwa v36, v29, v154 dst_sel:DWORD dst_unused:UNUSED_PAD src0_sel:WORD_1 src1_sel:DWORD
	v_and_b32_sdwa v40, v28, v154 dst_sel:DWORD dst_unused:UNUSED_PAD src0_sel:WORD_1 src1_sel:DWORD
	v_and_b32_sdwa v30, v67, v154 dst_sel:DWORD dst_unused:UNUSED_PAD src0_sel:WORD_1 src1_sel:DWORD
	v_and_b32_sdwa v31, v66, v154 dst_sel:DWORD dst_unused:UNUSED_PAD src0_sel:WORD_1 src1_sel:DWORD
	v_add3_u32 v29, v29, v36, s33
	v_add3_u32 v28, v28, v40, s33
	v_add3_u32 v31, v66, v31, s33
	v_add3_u32 v30, v67, v30, s33
	v_and_b32_e32 v29, 0xffff0000, v29
	v_and_b32_e32 v28, 0xffff0000, v28
	v_or_b32_sdwa v29, v29, v30 dst_sel:DWORD dst_unused:UNUSED_PAD src0_sel:DWORD src1_sel:WORD_1
	v_or_b32_sdwa v28, v28, v31 dst_sel:DWORD dst_unused:UNUSED_PAD src0_sel:DWORD src1_sel:WORD_1
	global_store_dwordx2 v[32:33], v[28:29], off
	global_load_dwordx4 v[62:65], v89, s[0:1] offset:64
	global_load_dwordx4 v[66:69], v89, s[4:5] offset:64
	v_mul_f32_e32 v28, 0xbfb8aa3b, v24
	v_mul_f32_e32 v29, 0xbfb8aa3b, v26
	v_exp_f32_e32 v30, v28
	v_exp_f32_e32 v31, v29
	v_mul_f32_e32 v28, 0xbfb8aa3b, v25
	v_mul_f32_e32 v29, 0xbfb8aa3b, v27
	v_exp_f32_e32 v28, v28
	v_pk_add_f32 v[30:31], v[30:31], 1.0 op_sel_hi:[1,0]
	v_exp_f32_e32 v29, v29
	s_nop 0
	v_pk_add_f32 v[28:29], v[28:29], 1.0 op_sel_hi:[1,0]
	v_rcp_f32_e32 v36, v31
	s_nop 0
	v_mul_f32_e32 v31, v26, v36
	v_mov_b32_e32 v48, v47
	v_rcp_f32_e32 v26, v30
	s_nop 0
	v_mul_f32_e32 v30, v24, v26
	v_pk_add_f32 v[46:47], v[48:49], v[38:39] op_sel:[0,1] neg_lo:[0,1] neg_hi:[0,1]
	v_rcp_f32_e32 v24, v29
	s_nop 0
	v_mul_f32_e32 v27, v27, v24
	v_pk_mul_f32 v[46:47], v[46:47], v[34:35] op_sel_hi:[1,0]
	v_rcp_f32_e32 v24, v28
	s_nop 0
	v_mul_f32_e32 v26, v25, v24
	s_waitcnt vmcnt(1)
	v_mov_b32_e32 v60, v62
	v_mov_b32_e32 v61, v64
	s_waitcnt vmcnt(0)
	v_mov_b32_e32 v70, v66
	v_mov_b32_e32 v71, v68
	v_pk_fma_f32 v[58:59], v[58:59], v[60:61], v[70:71]
	global_load_dwordx2 v[60:61], v[44:45], off offset:32
	v_mov_b32_e32 v64, v63
	v_mov_b32_e32 v68, v67
	v_pk_fma_f32 v[54:55], v[54:55], v[64:65], v[68:69]
	s_waitcnt vmcnt(0)
	v_and_b32_e32 v57, 0xffff0000, v61
	v_and_b32_e32 v56, 0xffff0000, v60
	v_lshlrev_b32_e32 v71, 16, v61
	v_lshlrev_b32_e32 v70, 16, v60
	v_pk_add_f32 v[54:55], v[54:55], v[56:57]
	v_pk_add_f32 v[58:59], v[58:59], v[70:71]
	v_pk_mul_f32 v[24:25], v[26:27], v[54:55]
	v_pk_mul_f32 v[30:31], v[30:31], v[58:59]
	v_and_b32_sdwa v28, v25, v154 dst_sel:DWORD dst_unused:UNUSED_PAD src0_sel:WORD_1 src1_sel:DWORD
	v_and_b32_sdwa v29, v24, v154 dst_sel:DWORD dst_unused:UNUSED_PAD src0_sel:WORD_1 src1_sel:DWORD
	v_and_b32_sdwa v26, v31, v154 dst_sel:DWORD dst_unused:UNUSED_PAD src0_sel:WORD_1 src1_sel:DWORD
	v_and_b32_sdwa v27, v30, v154 dst_sel:DWORD dst_unused:UNUSED_PAD src0_sel:WORD_1 src1_sel:DWORD
	v_add3_u32 v25, v25, v28, s33
	v_add3_u32 v24, v24, v29, s33
	v_add3_u32 v27, v30, v27, s33
	v_add3_u32 v26, v31, v26, s33
	v_and_b32_e32 v25, 0xffff0000, v25
	v_and_b32_e32 v24, 0xffff0000, v24
	v_or_b32_sdwa v25, v25, v26 dst_sel:DWORD dst_unused:UNUSED_PAD src0_sel:DWORD src1_sel:WORD_1
	v_or_b32_sdwa v24, v24, v27 dst_sel:DWORD dst_unused:UNUSED_PAD src0_sel:DWORD src1_sel:WORD_1
	global_store_dwordx2 v[32:33], v[24:25], off offset:32
	global_load_dwordx4 v[26:29], v89, s[0:1] offset:128
	global_load_dwordx4 v[54:57], v89, s[4:5] offset:128
	v_mul_f32_e32 v24, 0xbfb8aa3b, v20
	v_mul_f32_e32 v25, 0xbfb8aa3b, v22
	v_exp_f32_e32 v30, v24
	v_exp_f32_e32 v31, v25
	v_mul_f32_e32 v24, 0xbfb8aa3b, v21
	v_mul_f32_e32 v25, 0xbfb8aa3b, v23
	v_exp_f32_e32 v24, v24
	v_exp_f32_e32 v25, v25
	s_waitcnt vmcnt(1)
	v_mov_b32_e32 v52, v26
	v_mov_b32_e32 v53, v28
	s_waitcnt vmcnt(0)
	v_mov_b32_e32 v58, v54
	v_mov_b32_e32 v59, v56
	v_pk_fma_f32 v[50:51], v[50:51], v[52:53], v[58:59]
	global_load_dwordx2 v[52:53], v[44:45], off offset:64
	v_mov_b32_e32 v28, v27
	v_mov_b32_e32 v56, v55
	v_pk_fma_f32 v[26:27], v[46:47], v[28:29], v[56:57]
	v_pk_add_f32 v[24:25], v[24:25], 1.0 op_sel_hi:[1,0]
	s_waitcnt vmcnt(0)
	v_and_b32_e32 v29, 0xffff0000, v53
	v_and_b32_e32 v28, 0xffff0000, v52
	v_pk_add_f32 v[26:27], v[26:27], v[28:29]
	v_pk_add_f32 v[28:29], v[30:31], 1.0 op_sel_hi:[1,0]
	v_lshlrev_b32_e32 v59, 16, v53
	v_lshlrev_b32_e32 v58, 16, v52
	v_pk_add_f32 v[50:51], v[50:51], v[58:59]
	v_rcp_f32_e32 v30, v29
	s_nop 0
	v_mul_f32_e32 v29, v22, v30
	v_mov_b32_e32 v42, v41
	v_rcp_f32_e32 v22, v28
	s_nop 0
	v_mul_f32_e32 v28, v20, v22
	v_pk_mul_f32 v[28:29], v[28:29], v[50:51]
	v_pk_add_f32 v[40:41], v[42:43], v[38:39] op_sel:[0,1] neg_lo:[0,1] neg_hi:[0,1]
	v_rcp_f32_e32 v20, v25
	s_nop 0
	v_mul_f32_e32 v23, v23, v20
	v_pk_mul_f32 v[40:41], v[40:41], v[34:35] op_sel_hi:[1,0]
	v_mov_b32_e32 v36, v35
	v_pk_add_f32 v[36:37], v[36:37], v[38:39] op_sel:[0,1] neg_lo:[0,1] neg_hi:[0,1]
	v_rcp_f32_e32 v20, v24
	s_nop 0
	v_mul_f32_e32 v22, v21, v20
	v_pk_mul_f32 v[20:21], v[22:23], v[26:27]
	v_and_b32_sdwa v22, v29, v154 dst_sel:DWORD dst_unused:UNUSED_PAD src0_sel:WORD_1 src1_sel:DWORD
	v_and_b32_sdwa v24, v21, v154 dst_sel:DWORD dst_unused:UNUSED_PAD src0_sel:WORD_1 src1_sel:DWORD
	v_and_b32_sdwa v25, v20, v154 dst_sel:DWORD dst_unused:UNUSED_PAD src0_sel:WORD_1 src1_sel:DWORD
	v_and_b32_sdwa v23, v28, v154 dst_sel:DWORD dst_unused:UNUSED_PAD src0_sel:WORD_1 src1_sel:DWORD
	v_add3_u32 v21, v21, v24, s33
	v_add3_u32 v20, v20, v25, s33
	v_add3_u32 v23, v28, v23, s33
	v_add3_u32 v22, v29, v22, s33
	v_and_b32_e32 v21, 0xffff0000, v21
	v_and_b32_e32 v20, 0xffff0000, v20
	v_or_b32_sdwa v21, v21, v22 dst_sel:DWORD dst_unused:UNUSED_PAD src0_sel:DWORD src1_sel:WORD_1
	v_or_b32_sdwa v20, v20, v23 dst_sel:DWORD dst_unused:UNUSED_PAD src0_sel:DWORD src1_sel:WORD_1
	global_store_dwordx2 v[32:33], v[20:21], off offset:64
	global_load_dwordx4 v[22:25], v89, s[0:1] offset:192
	global_load_dwordx4 v[26:29], v89, s[4:5] offset:192
	v_mul_f32_e32 v20, 0xbfb8aa3b, v16
	v_mul_f32_e32 v21, 0xbfb8aa3b, v18
	v_exp_f32_e32 v30, v20
	v_exp_f32_e32 v31, v21
	v_pk_mul_f32 v[34:35], v[36:37], v[34:35] op_sel_hi:[1,0]
	v_mul_f32_e32 v20, 0xbfb8aa3b, v17
	v_mul_f32_e32 v21, 0xbfb8aa3b, v19
	v_exp_f32_e32 v20, v20
	v_exp_f32_e32 v21, v21
	s_waitcnt vmcnt(1)
	v_mov_b32_e32 v42, v22
	v_mov_b32_e32 v43, v24
	s_waitcnt vmcnt(0)
	v_mov_b32_e32 v46, v26
	v_mov_b32_e32 v47, v28
	v_pk_fma_f32 v[40:41], v[40:41], v[42:43], v[46:47]
	global_load_dwordx2 v[42:43], v[44:45], off offset:96
	v_mov_b32_e32 v24, v23
	v_mov_b32_e32 v28, v27
	v_pk_fma_f32 v[22:23], v[34:35], v[24:25], v[28:29]
	v_pk_add_f32 v[20:21], v[20:21], 1.0 op_sel_hi:[1,0]
	s_waitcnt vmcnt(0)
	v_and_b32_e32 v25, 0xffff0000, v43
	v_and_b32_e32 v24, 0xffff0000, v42
	v_pk_add_f32 v[22:23], v[22:23], v[24:25]
	v_pk_add_f32 v[24:25], v[30:31], 1.0 op_sel_hi:[1,0]
	v_lshlrev_b32_e32 v45, 16, v43
	v_lshlrev_b32_e32 v44, 16, v42
	v_pk_add_f32 v[40:41], v[40:41], v[44:45]
	v_rcp_f32_e32 v26, v25
	s_nop 0
	v_mul_f32_e32 v25, v18, v26
	s_nop 0
	v_rcp_f32_e32 v18, v24
	s_nop 0
	v_mul_f32_e32 v24, v16, v18
	v_pk_mul_f32 v[24:25], v[24:25], v[40:41]
	v_rcp_f32_e32 v16, v21
	s_nop 0
	v_mul_f32_e32 v19, v19, v16
	s_nop 0
	v_rcp_f32_e32 v16, v20
	s_nop 0
	v_mul_f32_e32 v18, v17, v16
	v_pk_mul_f32 v[16:17], v[18:19], v[22:23]
	v_and_b32_sdwa v18, v25, v154 dst_sel:DWORD dst_unused:UNUSED_PAD src0_sel:WORD_1 src1_sel:DWORD
	v_and_b32_sdwa v20, v17, v154 dst_sel:DWORD dst_unused:UNUSED_PAD src0_sel:WORD_1 src1_sel:DWORD
	v_and_b32_sdwa v21, v16, v154 dst_sel:DWORD dst_unused:UNUSED_PAD src0_sel:WORD_1 src1_sel:DWORD
	v_and_b32_sdwa v19, v24, v154 dst_sel:DWORD dst_unused:UNUSED_PAD src0_sel:WORD_1 src1_sel:DWORD
	v_add3_u32 v17, v17, v20, s33
	v_add3_u32 v16, v16, v21, s33
	v_add3_u32 v19, v24, v19, s33
	v_add3_u32 v18, v25, v18, s33
	v_and_b32_e32 v17, 0xffff0000, v17
	v_and_b32_e32 v16, 0xffff0000, v16
	v_or_b32_sdwa v17, v17, v18 dst_sel:DWORD dst_unused:UNUSED_PAD src0_sel:DWORD src1_sel:WORD_1
	v_or_b32_sdwa v16, v16, v19 dst_sel:DWORD dst_unused:UNUSED_PAD src0_sel:DWORD src1_sel:WORD_1
	global_store_dwordx2 v[32:33], v[16:17], off offset:96
	v_add_u32_e32 v16, 64, v88
	v_ashrrev_i32_e32 v17, 31, v16
	v_lshlrev_b64 v[28:29], 11, v[16:17]
	v_lshl_add_u64 v[18:19], v[90:91], 0, v[28:29]
	global_load_dwordx2 v[22:23], v[18:19], off
	global_load_dwordx2 v[20:21], v[18:19], off offset:32
	v_lshl_add_u64 v[28:29], s[8:9], 0, v[28:29]
	v_lshl_add_u64 v[28:29], v[28:29], 0, v[96:97]
	s_waitcnt vmcnt(1)
	v_lshlrev_b32_e32 v54, 16, v22
	s_waitcnt vmcnt(0)
	v_lshlrev_b32_e32 v43, 16, v20
	v_and_b32_e32 v39, 0xffff0000, v20
	v_alignbit_b32 v17, v21, v20, 16
	v_and_b32_e32 v41, 0xffff0000, v21
	global_load_dwordx2 v[20:21], v[18:19], off offset:64
	v_and_b32_e32 v45, 0xffff0000, v17
	v_and_b32_e32 v49, 0xffff0000, v23
	v_and_b32_e32 v52, 0xffff0000, v22
	v_mov_b32_e32 v48, v54
	v_mov_b32_e32 v53, v54
	v_mul_f32_e32 v46, v54, v54
	v_mul_f32_e32 v42, v43, v43
	v_mul_f32_e32 v38, v39, v39
	v_mul_f32_e32 v44, v45, v45
	v_mul_f32_e32 v40, v41, v41
	s_waitcnt vmcnt(0)
	v_lshlrev_b32_e32 v35, 16, v20
	v_and_b32_e32 v31, 0xffff0000, v20
	v_alignbit_b32 v17, v21, v20, 16
	v_and_b32_e32 v33, 0xffff0000, v21
	global_load_dwordx2 v[20:21], v[18:19], off offset:96
	v_and_b32_e32 v37, 0xffff0000, v17
	v_mul_f32_e32 v34, v35, v35
	v_mul_f32_e32 v30, v31, v31
	v_mul_f32_e32 v36, v37, v37
	v_mul_f32_e32 v32, v33, v33
	s_waitcnt vmcnt(0)
	v_alignbit_b32 v17, v21, v20, 16
	v_and_b32_e32 v27, 0xffff0000, v17
	v_alignbit_b32 v17, v23, v22, 16
	v_and_b32_e32 v23, 0xffff0000, v17
	v_and_b32_e32 v22, 16, v22
	v_mov_b32_e32 v17, v54
	v_pk_add_f32 v[50:51], v[22:23], v[48:49]
	v_pk_add_f32 v[56:57], v[52:53], v[16:17] op_sel_hi:[0,1]
	v_mov_b32_e32 v47, v51
	v_pk_mul_f32 v[50:51], v[52:53], v[52:53]
	v_mov_b32_e32 v48, v23
	v_mov_b32_e32 v51, v57
	global_load_dwordx4 v[56:59], v89, s[0:1]
	global_load_dwordx4 v[60:63], v89, s[4:5]
	v_mul_f32_e32 v22, v49, v49
	v_mov_b32_e32 v55, v23
	v_pk_fma_f32 v[22:23], v[48:49], v[48:49], v[22:23] op_sel_hi:[1,1,0]
	v_pk_add_f32 v[46:47], v[46:47], v[50:51]
	v_mov_b32_e32 v23, v97
	v_pk_add_f32 v[22:23], v[46:47], v[22:23]
	v_pk_add_f32 v[46:47], v[42:43], v[38:39]
	v_pk_add_f32 v[50:51], v[44:45], v[40:41]
	v_lshlrev_b32_e32 v25, 16, v20
	v_pk_add_f32 v[46:47], v[46:47], v[50:51]
	v_and_b32_e32 v19, 0xffff0000, v20
	v_and_b32_e32 v21, 0xffff0000, v21
	v_pk_add_f32 v[22:23], v[22:23], v[46:47]
	v_pk_add_f32 v[46:47], v[34:35], v[30:31]
	v_pk_add_f32 v[50:51], v[36:37], v[32:33]
	v_mul_f32_e32 v24, v25, v25
	v_mul_f32_e32 v18, v19, v19
	v_mul_f32_e32 v26, v27, v27
	v_mul_f32_e32 v20, v21, v21
	v_pk_add_f32 v[46:47], v[46:47], v[50:51]
	v_pk_add_f32 v[50:51], v[26:27], v[20:21]
	v_pk_add_f32 v[22:23], v[22:23], v[46:47]
	v_pk_add_f32 v[46:47], v[24:25], v[18:19]
	v_mul_f32_e32 v20, 0xbfb8aa3b, v12
	v_pk_add_f32 v[46:47], v[46:47], v[50:51]
	v_exp_f32_e32 v50, v20
	v_pk_add_f32 v[22:23], v[22:23], v[46:47]
	s_nop 0
	ds_bpermute_b32 v47, v184, v23
	ds_bpermute_b32 v46, v184, v22
	v_mul_f32_e32 v20, 0xbfb8aa3b, v13
	v_mov_b32_e32 v53, v49
	v_mov_b32_e32 v44, v43
	v_mov_b32_e32 v40, v39
	s_waitcnt lgkmcnt(0)
	v_pk_add_f32 v[22:23], v[22:23], v[46:47]
	s_nop 0
	ds_bpermute_b32 v47, v185, v23
	ds_bpermute_b32 v46, v185, v22
	v_mov_b32_e32 v36, v35
	s_waitcnt lgkmcnt(0)
	v_pk_add_f32 v[22:23], v[22:23], v[46:47]
	s_nop 0
	v_pk_mul_f32 v[22:23], v[22:23], s[38:39] op_sel_hi:[1,0]
	v_exp_f32_e32 v46, v20
	v_fma_f32 v17, -v23, v23, v22
	v_max_f32_e32 v17, 0, v17
	v_add_f32_e32 v17, 0x3a27c5ac, v17
	v_cmp_gt_f32_e32 vcc, s12, v17
	v_mul_f32_e32 v18, 0x4b800000, v17
	v_pk_add_f32 v[54:55], v[54:55], v[22:23] op_sel:[0,1] neg_lo:[0,1] neg_hi:[0,1]
	v_cndmask_b32_e32 v17, v17, v18, vcc
	v_rsq_f32_e32 v17, v17
	v_mul_f32_e32 v20, 0xbfb8aa3b, v14
	v_exp_f32_e32 v51, v20
	v_mul_f32_e32 v20, 0xbfb8aa3b, v15
	v_mul_f32_e32 v18, 0x45800000, v17
	v_cndmask_b32_e32 v18, v17, v18, vcc
	v_pk_mul_f32 v[54:55], v[54:55], v[18:19] op_sel_hi:[1,0]
	v_pk_add_f32 v[50:51], v[50:51], 1.0 op_sel_hi:[1,0]
	v_exp_f32_e32 v47, v20
	s_nop 0
	v_pk_add_f32 v[46:47], v[46:47], 1.0 op_sel_hi:[1,0]
	v_pk_add_f32 v[48:49], v[52:53], v[22:23] op_sel:[0,1] neg_lo:[0,1] neg_hi:[0,1]
	v_mad_i64_i32 v[16:17], s[10:11], v16, s13, v[86:87]
	v_rcp_f32_e32 v20, v51
	s_nop 0
	v_mul_f32_e32 v51, v14, v20
	s_waitcnt vmcnt(1)
	v_mov_b32_e32 v64, v56
	v_mov_b32_e32 v65, v58
	s_waitcnt vmcnt(0)
	v_mov_b32_e32 v66, v60
	v_mov_b32_e32 v67, v62
	v_pk_fma_f32 v[54:55], v[64:65], v[54:55], v[66:67]
	global_load_dwordx2 v[64:65], v[28:29], off
	v_pk_mul_f32 v[48:49], v[48:49], v[18:19] op_sel_hi:[1,0]
	v_mov_b32_e32 v58, v57
	v_mov_b32_e32 v62, v61
	v_rcp_f32_e32 v14, v50
	s_nop 0
	v_mul_f32_e32 v50, v12, v14
	v_pk_fma_f32 v[48:49], v[58:59], v[48:49], v[62:63]
	v_pk_add_f32 v[42:43], v[44:45], v[22:23] op_sel:[0,1] neg_lo:[0,1] neg_hi:[0,1]
	v_pk_add_f32 v[38:39], v[40:41], v[22:23] op_sel:[0,1] neg_lo:[0,1] neg_hi:[0,1]
	v_rcp_f32_e32 v12, v47
	s_nop 0
	v_mul_f32_e32 v15, v15, v12
	v_pk_mul_f32 v[42:43], v[42:43], v[18:19] op_sel_hi:[1,0]
	v_pk_mul_f32 v[38:39], v[38:39], v[18:19] op_sel_hi:[1,0]
	v_pk_add_f32 v[34:35], v[36:37], v[22:23] op_sel:[0,1] neg_lo:[0,1] neg_hi:[0,1]
	v_rcp_f32_e32 v12, v46
	s_nop 0
	v_mul_f32_e32 v14, v13, v12
	v_pk_mul_f32 v[34:35], v[34:35], v[18:19] op_sel_hi:[1,0]
	s_waitcnt vmcnt(0)
	v_and_b32_e32 v53, 0xffff0000, v65
	v_and_b32_e32 v52, 0xffff0000, v64
	v_lshlrev_b32_e32 v67, 16, v65
	v_lshlrev_b32_e32 v66, 16, v64
	v_pk_add_f32 v[48:49], v[48:49], v[52:53]
	v_pk_add_f32 v[54:55], v[54:55], v[66:67]
	v_pk_mul_f32 v[12:13], v[14:15], v[48:49]
	v_pk_mul_f32 v[50:51], v[50:51], v[54:55]
	v_and_b32_sdwa v20, v13, v154 dst_sel:DWORD dst_unused:UNUSED_PAD src0_sel:WORD_1 src1_sel:DWORD
	v_and_b32_sdwa v24, v12, v154 dst_sel:DWORD dst_unused:UNUSED_PAD src0_sel:WORD_1 src1_sel:DWORD
	v_and_b32_sdwa v14, v51, v154 dst_sel:DWORD dst_unused:UNUSED_PAD src0_sel:WORD_1 src1_sel:DWORD
	v_and_b32_sdwa v15, v50, v154 dst_sel:DWORD dst_unused:UNUSED_PAD src0_sel:WORD_1 src1_sel:DWORD
	v_add3_u32 v13, v13, v20, s33
	v_add3_u32 v12, v12, v24, s33
	v_add3_u32 v15, v50, v15, s33
	v_add3_u32 v14, v51, v14, s33
	v_and_b32_e32 v13, 0xffff0000, v13
	v_and_b32_e32 v12, 0xffff0000, v12
	v_or_b32_sdwa v13, v13, v14 dst_sel:DWORD dst_unused:UNUSED_PAD src0_sel:DWORD src1_sel:WORD_1
	v_or_b32_sdwa v12, v12, v15 dst_sel:DWORD dst_unused:UNUSED_PAD src0_sel:DWORD src1_sel:WORD_1
	global_store_dwordx2 v[16:17], v[12:13], off
	global_load_dwordx4 v[46:49], v89, s[0:1] offset:64
	global_load_dwordx4 v[50:53], v89, s[4:5] offset:64
	v_mul_f32_e32 v12, 0xbfb8aa3b, v8
	v_mul_f32_e32 v13, 0xbfb8aa3b, v10
	v_exp_f32_e32 v14, v12
	v_exp_f32_e32 v15, v13
	v_mul_f32_e32 v12, 0xbfb8aa3b, v9
	v_mul_f32_e32 v13, 0xbfb8aa3b, v11
	v_exp_f32_e32 v12, v12
	v_pk_add_f32 v[14:15], v[14:15], 1.0 op_sel_hi:[1,0]
	v_exp_f32_e32 v13, v13
	s_nop 0
	v_pk_add_f32 v[12:13], v[12:13], 1.0 op_sel_hi:[1,0]
	v_rcp_f32_e32 v20, v15
	s_nop 0
	v_mul_f32_e32 v15, v10, v20
	v_mov_b32_e32 v32, v31
	v_rcp_f32_e32 v10, v14
	s_nop 0
	v_mul_f32_e32 v14, v8, v10
	v_pk_add_f32 v[30:31], v[32:33], v[22:23] op_sel:[0,1] neg_lo:[0,1] neg_hi:[0,1]
	v_rcp_f32_e32 v8, v13
	s_nop 0
	v_mul_f32_e32 v11, v11, v8
	v_pk_mul_f32 v[30:31], v[30:31], v[18:19] op_sel_hi:[1,0]
	v_rcp_f32_e32 v8, v12
	s_nop 0
	v_mul_f32_e32 v10, v9, v8
	s_waitcnt vmcnt(1)
	v_mov_b32_e32 v44, v46
	v_mov_b32_e32 v45, v48
	s_waitcnt vmcnt(0)
	v_mov_b32_e32 v54, v50
	v_mov_b32_e32 v55, v52
	v_pk_fma_f32 v[42:43], v[42:43], v[44:45], v[54:55]
	global_load_dwordx2 v[44:45], v[28:29], off offset:32
	v_mov_b32_e32 v48, v47
	v_mov_b32_e32 v52, v51
	v_pk_fma_f32 v[38:39], v[38:39], v[48:49], v[52:53]
	s_waitcnt vmcnt(0)
	v_and_b32_e32 v41, 0xffff0000, v45
	v_and_b32_e32 v40, 0xffff0000, v44
	v_lshlrev_b32_e32 v55, 16, v45
	v_lshlrev_b32_e32 v54, 16, v44
	v_pk_add_f32 v[38:39], v[38:39], v[40:41]
	v_pk_add_f32 v[42:43], v[42:43], v[54:55]
	v_pk_mul_f32 v[8:9], v[10:11], v[38:39]
	v_pk_mul_f32 v[14:15], v[14:15], v[42:43]
	v_and_b32_sdwa v12, v9, v154 dst_sel:DWORD dst_unused:UNUSED_PAD src0_sel:WORD_1 src1_sel:DWORD
	v_and_b32_sdwa v13, v8, v154 dst_sel:DWORD dst_unused:UNUSED_PAD src0_sel:WORD_1 src1_sel:DWORD
	v_and_b32_sdwa v10, v15, v154 dst_sel:DWORD dst_unused:UNUSED_PAD src0_sel:WORD_1 src1_sel:DWORD
	v_and_b32_sdwa v11, v14, v154 dst_sel:DWORD dst_unused:UNUSED_PAD src0_sel:WORD_1 src1_sel:DWORD
	v_add3_u32 v9, v9, v12, s33
	v_add3_u32 v8, v8, v13, s33
	v_add3_u32 v11, v14, v11, s33
	v_add3_u32 v10, v15, v10, s33
	v_and_b32_e32 v9, 0xffff0000, v9
	v_and_b32_e32 v8, 0xffff0000, v8
	v_or_b32_sdwa v9, v9, v10 dst_sel:DWORD dst_unused:UNUSED_PAD src0_sel:DWORD src1_sel:WORD_1
	v_or_b32_sdwa v8, v8, v11 dst_sel:DWORD dst_unused:UNUSED_PAD src0_sel:DWORD src1_sel:WORD_1
	global_store_dwordx2 v[16:17], v[8:9], off offset:32
	global_load_dwordx4 v[10:13], v89, s[0:1] offset:128
	global_load_dwordx4 v[38:41], v89, s[4:5] offset:128
	v_mul_f32_e32 v8, 0xbfb8aa3b, v4
	v_mul_f32_e32 v9, 0xbfb8aa3b, v6
	v_exp_f32_e32 v14, v8
	v_exp_f32_e32 v15, v9
	v_mul_f32_e32 v8, 0xbfb8aa3b, v5
	v_mul_f32_e32 v9, 0xbfb8aa3b, v7
	v_exp_f32_e32 v8, v8
	v_exp_f32_e32 v9, v9
	s_waitcnt vmcnt(1)
	v_mov_b32_e32 v36, v10
	v_mov_b32_e32 v37, v12
	s_waitcnt vmcnt(0)
	v_mov_b32_e32 v42, v38
	v_mov_b32_e32 v43, v40
	v_pk_fma_f32 v[34:35], v[34:35], v[36:37], v[42:43]
	global_load_dwordx2 v[36:37], v[28:29], off offset:64
	v_mov_b32_e32 v12, v11
	v_mov_b32_e32 v40, v39
	v_pk_fma_f32 v[10:11], v[30:31], v[12:13], v[40:41]
	v_pk_add_f32 v[8:9], v[8:9], 1.0 op_sel_hi:[1,0]
	s_waitcnt vmcnt(0)
	v_and_b32_e32 v13, 0xffff0000, v37
	v_and_b32_e32 v12, 0xffff0000, v36
	v_pk_add_f32 v[10:11], v[10:11], v[12:13]
	v_pk_add_f32 v[12:13], v[14:15], 1.0 op_sel_hi:[1,0]
	v_lshlrev_b32_e32 v43, 16, v37
	v_lshlrev_b32_e32 v42, 16, v36
	v_pk_add_f32 v[34:35], v[34:35], v[42:43]
	v_rcp_f32_e32 v14, v13
	s_nop 0
	v_mul_f32_e32 v13, v6, v14
	v_mov_b32_e32 v26, v25
	v_rcp_f32_e32 v6, v12
	s_nop 0
	v_mul_f32_e32 v12, v4, v6
	v_pk_mul_f32 v[12:13], v[12:13], v[34:35]
	v_pk_add_f32 v[24:25], v[26:27], v[22:23] op_sel:[0,1] neg_lo:[0,1] neg_hi:[0,1]
	v_rcp_f32_e32 v4, v9
	s_nop 0
	v_mul_f32_e32 v7, v7, v4
	v_pk_mul_f32 v[24:25], v[24:25], v[18:19] op_sel_hi:[1,0]
	v_mov_b32_e32 v20, v19
	v_pk_add_f32 v[20:21], v[20:21], v[22:23] op_sel:[0,1] neg_lo:[0,1] neg_hi:[0,1]
	v_rcp_f32_e32 v4, v8
	s_nop 0
	v_mul_f32_e32 v6, v5, v4
	v_pk_mul_f32 v[4:5], v[6:7], v[10:11]
	v_and_b32_sdwa v6, v13, v154 dst_sel:DWORD dst_unused:UNUSED_PAD src0_sel:WORD_1 src1_sel:DWORD
	v_and_b32_sdwa v8, v5, v154 dst_sel:DWORD dst_unused:UNUSED_PAD src0_sel:WORD_1 src1_sel:DWORD
	v_and_b32_sdwa v9, v4, v154 dst_sel:DWORD dst_unused:UNUSED_PAD src0_sel:WORD_1 src1_sel:DWORD
	v_and_b32_sdwa v7, v12, v154 dst_sel:DWORD dst_unused:UNUSED_PAD src0_sel:WORD_1 src1_sel:DWORD
	v_add3_u32 v5, v5, v8, s33
	v_add3_u32 v4, v4, v9, s33
	v_add3_u32 v7, v12, v7, s33
	v_add3_u32 v6, v13, v6, s33
	v_and_b32_e32 v5, 0xffff0000, v5
	v_and_b32_e32 v4, 0xffff0000, v4
	v_or_b32_sdwa v5, v5, v6 dst_sel:DWORD dst_unused:UNUSED_PAD src0_sel:DWORD src1_sel:WORD_1
	v_or_b32_sdwa v4, v4, v7 dst_sel:DWORD dst_unused:UNUSED_PAD src0_sel:DWORD src1_sel:WORD_1
	global_store_dwordx2 v[16:17], v[4:5], off offset:64
	global_load_dwordx4 v[6:9], v89, s[0:1] offset:192
	global_load_dwordx4 v[10:13], v89, s[4:5] offset:192
	v_mul_f32_e32 v4, 0xbfb8aa3b, v0
	v_mul_f32_e32 v5, 0xbfb8aa3b, v2
	v_exp_f32_e32 v14, v4
	v_exp_f32_e32 v15, v5
	v_pk_mul_f32 v[18:19], v[20:21], v[18:19] op_sel_hi:[1,0]
	v_mul_f32_e32 v4, 0xbfb8aa3b, v1
	v_mul_f32_e32 v5, 0xbfb8aa3b, v3
	v_exp_f32_e32 v4, v4
	v_exp_f32_e32 v5, v5
	s_waitcnt vmcnt(1)
	v_mov_b32_e32 v26, v6
	v_mov_b32_e32 v27, v8
	s_waitcnt vmcnt(0)
	v_mov_b32_e32 v30, v10
	v_mov_b32_e32 v31, v12
	v_pk_fma_f32 v[24:25], v[24:25], v[26:27], v[30:31]
	global_load_dwordx2 v[26:27], v[28:29], off offset:96
	v_mov_b32_e32 v8, v7
	v_mov_b32_e32 v12, v11
	v_pk_fma_f32 v[6:7], v[18:19], v[8:9], v[12:13]
	v_pk_add_f32 v[4:5], v[4:5], 1.0 op_sel_hi:[1,0]
	s_waitcnt vmcnt(0)
	v_and_b32_e32 v9, 0xffff0000, v27
	v_and_b32_e32 v8, 0xffff0000, v26
	v_pk_add_f32 v[6:7], v[6:7], v[8:9]
	v_pk_add_f32 v[8:9], v[14:15], 1.0 op_sel_hi:[1,0]
	v_lshlrev_b32_e32 v29, 16, v27
	v_lshlrev_b32_e32 v28, 16, v26
	v_pk_add_f32 v[24:25], v[24:25], v[28:29]
	v_rcp_f32_e32 v10, v9
	s_nop 0
	v_mul_f32_e32 v9, v2, v10
	s_nop 0
	v_rcp_f32_e32 v2, v8
	s_nop 0
	v_mul_f32_e32 v8, v0, v2
	v_pk_mul_f32 v[8:9], v[8:9], v[24:25]
	v_rcp_f32_e32 v0, v5
	s_nop 0
	v_mul_f32_e32 v3, v3, v0
	s_nop 0
	v_rcp_f32_e32 v0, v4
	s_nop 0
	v_mul_f32_e32 v2, v1, v0
	v_pk_mul_f32 v[0:1], v[2:3], v[6:7]
	v_and_b32_sdwa v2, v9, v154 dst_sel:DWORD dst_unused:UNUSED_PAD src0_sel:WORD_1 src1_sel:DWORD
	v_and_b32_sdwa v4, v1, v154 dst_sel:DWORD dst_unused:UNUSED_PAD src0_sel:WORD_1 src1_sel:DWORD
	v_and_b32_sdwa v5, v0, v154 dst_sel:DWORD dst_unused:UNUSED_PAD src0_sel:WORD_1 src1_sel:DWORD
	v_and_b32_sdwa v3, v8, v154 dst_sel:DWORD dst_unused:UNUSED_PAD src0_sel:WORD_1 src1_sel:DWORD
	v_add3_u32 v1, v1, v4, s33
	v_add3_u32 v0, v0, v5, s33
	v_add3_u32 v3, v8, v3, s33
	v_add3_u32 v2, v9, v2, s33
	v_and_b32_e32 v1, 0xffff0000, v1
	v_and_b32_e32 v0, 0xffff0000, v0
	v_or_b32_sdwa v1, v1, v2 dst_sel:DWORD dst_unused:UNUSED_PAD src0_sel:DWORD src1_sel:WORD_1
	v_or_b32_sdwa v0, v0, v3 dst_sel:DWORD dst_unused:UNUSED_PAD src0_sel:DWORD src1_sel:WORD_1
	global_store_dwordx2 v[16:17], v[0:1], off offset:96

.LBB0_214:
	s_add_i32 s59, s58, 0x8000
	s_and_b32 s58, s58, 0x8000
	s_add_i32 s58, s58, 0
	v_add_u32_e32 v79, s58, v95
	v_add_u32_e32 v88, v79, v100
	v_add_u32_e32 v79, v79, v93
	ds_read_b128 v[80:83], v88
	ds_read_b128 v[84:87], v88 offset:2048
	ds_read_b128 v[110:113], v88 offset:4096
	ds_read_b128 v[114:117], v88 offset:6144
	ds_read_b128 v[118:121], v79 offset:16384
	ds_read_b128 v[122:125], v79 offset:18432
	ds_read_b128 v[126:129], v79 offset:20480
	ds_read_b128 v[130:133], v79 offset:22528
	v_add_u32_e32 v206, s58, v101
	v_add_u32_e32 v207, v206, v100
	v_add_u32_e32 v208, v206, v93
	ds_read_b128 v[210:213], v207
	ds_read_b128 v[214:217], v207 offset:2048
	ds_read_b128 v[218:221], v207 offset:4096
	ds_read_b128 v[222:225], v207 offset:6144
	ds_read_b128 v[226:229], v208 offset:16384
	ds_read_b128 v[230:233], v208 offset:18432
	ds_read_b128 v[234:237], v208 offset:20480
	ds_read_b128 v[238:241], v208 offset:22528
	s_setprio 1
	s_waitcnt lgkmcnt(8)
	v_mfma_f32_16x16x32_bf16 v[60:63], v[118:121], v[80:83], v[60:63]
	v_mfma_f32_16x16x32_bf16 v[56:59], v[122:125], v[80:83], v[56:59]
	v_mfma_f32_16x16x32_bf16 v[52:55], v[126:129], v[80:83], v[52:55]
	v_mfma_f32_16x16x32_bf16 v[48:51], v[130:133], v[80:83], v[48:51]
	v_mfma_f32_16x16x32_bf16 v[44:47], v[118:121], v[84:87], v[44:47]
	v_mfma_f32_16x16x32_bf16 v[40:43], v[122:125], v[84:87], v[40:43]
	v_mfma_f32_16x16x32_bf16 v[36:39], v[126:129], v[84:87], v[36:39]
	v_mfma_f32_16x16x32_bf16 v[32:35], v[130:133], v[84:87], v[32:35]
	v_mfma_f32_16x16x32_bf16 v[28:31], v[118:121], v[110:113], v[28:31]
	v_mfma_f32_16x16x32_bf16 v[24:27], v[122:125], v[110:113], v[24:27]
	v_mfma_f32_16x16x32_bf16 v[20:23], v[126:129], v[110:113], v[20:23]
	v_mfma_f32_16x16x32_bf16 v[16:19], v[130:133], v[110:113], v[16:19]
	v_mfma_f32_16x16x32_bf16 v[12:15], v[118:121], v[114:117], v[12:15]
	v_mfma_f32_16x16x32_bf16 v[8:11], v[122:125], v[114:117], v[8:11]
	v_mfma_f32_16x16x32_bf16 v[4:7], v[126:129], v[114:117], v[4:7]
	v_mfma_f32_16x16x32_bf16 v[0:3], v[130:133], v[114:117], v[0:3]
	s_waitcnt lgkmcnt(0)
	s_setprio 0
	s_barrier
	s_add_u32 s6, s6, 0x80
	s_addc_u32 s7, s7, 0
	s_mov_b32 s60, s58
	v_add_u32_e32 v79, s60, v91
	v_lshl_add_u64 v[80:81], v[74:75], 0, s[6:7]
	v_add_u32_e32 v88, 0x4000, v79
	v_readfirstlane_b32 s60, v79
	v_lshl_add_u64 v[82:83], v[80:81], 0, s[88:89]
	v_lshl_add_u64 v[84:85], v[76:77], 0, s[6:7]
	s_mov_b32 m0, s60
	v_readfirstlane_b32 s60, v88
	v_lshl_add_u64 v[86:87], v[84:85], 0, s[92:93]
	global_load_lds_dwordx4 v[82:83], off
	s_mov_b32 m0, s60
	v_lshl_add_u64 v[82:83], v[80:81], 0, s[90:91]
	global_load_lds_dwordx4 v[86:87], off
	v_add_u32_e32 v86, 0x1000, v79
	s_nop 0
	v_readfirstlane_b32 s60, v86
	v_add_u32_e32 v86, 0x5000, v79
	s_mov_b32 m0, s60
	v_readfirstlane_b32 s60, v86
	v_add_u32_e32 v86, 0x2000, v79
	global_load_lds_dwordx4 v[82:83], off
	v_lshl_add_u64 v[82:83], v[84:85], 0, s[38:39]
	s_mov_b32 m0, s60
	v_readfirstlane_b32 s60, v86
	v_add_u32_e32 v86, 0x6000, v79
	global_load_lds_dwordx4 v[82:83], off
	v_lshl_add_u64 v[82:83], v[80:81], 0, s[94:95]
	s_mov_b32 m0, s60
	v_readfirstlane_b32 s60, v86
	global_load_lds_dwordx4 v[82:83], off
	v_lshl_add_u64 v[82:83], v[84:85], 0, s[62:63]
	s_mov_b32 m0, s60
	v_lshl_add_u64 v[80:81], v[80:81], 0, vcc
	global_load_lds_dwordx4 v[82:83], off
	v_add_u32_e32 v82, 0x3000, v79
	v_add_u32_e32 v79, 0x7000, v79
	v_readfirstlane_b32 s60, v82
	s_mov_b32 m0, s60
	v_readfirstlane_b32 s60, v79
	global_load_lds_dwordx4 v[80:81], off
	v_lshl_add_u64 v[80:81], v[84:85], 0, s[68:69]
	s_mov_b32 m0, s60
	s_nop 0
	global_load_lds_dwordx4 v[80:81], off
	s_setprio 1
	v_mfma_f32_16x16x32_bf16 v[60:63], v[226:229], v[210:213], v[60:63]
	v_mfma_f32_16x16x32_bf16 v[56:59], v[230:233], v[210:213], v[56:59]
	v_mfma_f32_16x16x32_bf16 v[52:55], v[234:237], v[210:213], v[52:55]
	v_mfma_f32_16x16x32_bf16 v[48:51], v[238:241], v[210:213], v[48:51]
	v_mfma_f32_16x16x32_bf16 v[44:47], v[226:229], v[214:217], v[44:47]
	v_mfma_f32_16x16x32_bf16 v[40:43], v[230:233], v[214:217], v[40:43]
	v_mfma_f32_16x16x32_bf16 v[36:39], v[234:237], v[214:217], v[36:39]
	v_mfma_f32_16x16x32_bf16 v[32:35], v[238:241], v[214:217], v[32:35]
	v_mfma_f32_16x16x32_bf16 v[28:31], v[226:229], v[218:221], v[28:31]
	v_mfma_f32_16x16x32_bf16 v[24:27], v[230:233], v[218:221], v[24:27]
	v_mfma_f32_16x16x32_bf16 v[20:23], v[234:237], v[218:221], v[20:23]
	v_mfma_f32_16x16x32_bf16 v[16:19], v[238:241], v[218:221], v[16:19]
	v_mfma_f32_16x16x32_bf16 v[12:15], v[226:229], v[222:225], v[12:15]
	v_mfma_f32_16x16x32_bf16 v[8:11], v[230:233], v[222:225], v[8:11]
	v_mfma_f32_16x16x32_bf16 v[4:7], v[234:237], v[222:225], v[4:7]
	v_mfma_f32_16x16x32_bf16 v[0:3], v[238:241], v[222:225], v[0:3]
	s_setprio 0
	s_cmpk_lg_i32 s6, 0x700
	s_mov_b32 s58, s59
	s_waitcnt vmcnt(8)
	s_barrier
	s_cbranch_scc1 .LBB0_214
	s_add_i32 s59, s58, 0x8000
	s_and_b32 s58, s58, 0x8000
	s_add_i32 s58, s58, 0
	v_add_u32_e32 v79, s58, v95
	v_add_u32_e32 v88, v79, v100
	v_add_u32_e32 v79, v79, v93
	ds_read_b128 v[80:83], v88
	ds_read_b128 v[84:87], v88 offset:2048
	ds_read_b128 v[110:113], v88 offset:4096
	ds_read_b128 v[114:117], v88 offset:6144
	ds_read_b128 v[118:121], v79 offset:16384
	ds_read_b128 v[122:125], v79 offset:18432
	ds_read_b128 v[126:129], v79 offset:20480
	ds_read_b128 v[130:133], v79 offset:22528
	v_add_u32_e32 v206, s58, v101
	v_add_u32_e32 v207, v206, v100
	v_add_u32_e32 v208, v206, v93
	ds_read_b128 v[210:213], v207
	ds_read_b128 v[214:217], v207 offset:2048
	ds_read_b128 v[218:221], v207 offset:4096
	ds_read_b128 v[222:225], v207 offset:6144
	ds_read_b128 v[226:229], v208 offset:16384
	ds_read_b128 v[230:233], v208 offset:18432
	ds_read_b128 v[234:237], v208 offset:20480
	ds_read_b128 v[238:241], v208 offset:22528
	s_setprio 1
	s_waitcnt lgkmcnt(8)
	v_mfma_f32_16x16x32_bf16 v[60:63], v[118:121], v[80:83], v[60:63]
	v_mfma_f32_16x16x32_bf16 v[56:59], v[122:125], v[80:83], v[56:59]
	v_mfma_f32_16x16x32_bf16 v[52:55], v[126:129], v[80:83], v[52:55]
	v_mfma_f32_16x16x32_bf16 v[48:51], v[130:133], v[80:83], v[48:51]
	v_mfma_f32_16x16x32_bf16 v[44:47], v[118:121], v[84:87], v[44:47]
	v_mfma_f32_16x16x32_bf16 v[40:43], v[122:125], v[84:87], v[40:43]
	v_mfma_f32_16x16x32_bf16 v[36:39], v[126:129], v[84:87], v[36:39]
	v_mfma_f32_16x16x32_bf16 v[32:35], v[130:133], v[84:87], v[32:35]
	v_mfma_f32_16x16x32_bf16 v[28:31], v[118:121], v[110:113], v[28:31]
	v_mfma_f32_16x16x32_bf16 v[24:27], v[122:125], v[110:113], v[24:27]
	v_mfma_f32_16x16x32_bf16 v[20:23], v[126:129], v[110:113], v[20:23]
	v_mfma_f32_16x16x32_bf16 v[16:19], v[130:133], v[110:113], v[16:19]
	v_mfma_f32_16x16x32_bf16 v[12:15], v[118:121], v[114:117], v[12:15]
	v_mfma_f32_16x16x32_bf16 v[8:11], v[122:125], v[114:117], v[8:11]
	v_mfma_f32_16x16x32_bf16 v[4:7], v[126:129], v[114:117], v[4:7]
	v_mfma_f32_16x16x32_bf16 v[0:3], v[130:133], v[114:117], v[0:3]
	s_waitcnt lgkmcnt(0)
	v_mfma_f32_16x16x32_bf16 v[60:63], v[226:229], v[210:213], v[60:63]
	v_mfma_f32_16x16x32_bf16 v[56:59], v[230:233], v[210:213], v[56:59]
	v_mfma_f32_16x16x32_bf16 v[52:55], v[234:237], v[210:213], v[52:55]
	v_mfma_f32_16x16x32_bf16 v[48:51], v[238:241], v[210:213], v[48:51]
	v_mfma_f32_16x16x32_bf16 v[44:47], v[226:229], v[214:217], v[44:47]
	v_mfma_f32_16x16x32_bf16 v[40:43], v[230:233], v[214:217], v[40:43]
	v_mfma_f32_16x16x32_bf16 v[36:39], v[234:237], v[214:217], v[36:39]
	v_mfma_f32_16x16x32_bf16 v[32:35], v[238:241], v[214:217], v[32:35]
	v_mfma_f32_16x16x32_bf16 v[28:31], v[226:229], v[218:221], v[28:31]
	v_mfma_f32_16x16x32_bf16 v[24:27], v[230:233], v[218:221], v[24:27]
	v_mfma_f32_16x16x32_bf16 v[20:23], v[234:237], v[218:221], v[20:23]
	v_mfma_f32_16x16x32_bf16 v[16:19], v[238:241], v[218:221], v[16:19]
	v_mfma_f32_16x16x32_bf16 v[12:15], v[226:229], v[222:225], v[12:15]
	v_mfma_f32_16x16x32_bf16 v[8:11], v[230:233], v[222:225], v[8:11]
	v_mfma_f32_16x16x32_bf16 v[4:7], v[234:237], v[222:225], v[4:7]
	v_mfma_f32_16x16x32_bf16 v[0:3], v[238:241], v[222:225], v[0:3]
	s_setprio 0
	s_mov_b32 s58, s59
	s_waitcnt vmcnt(0)
	s_barrier
	v_add_u32_e32 v79, v104, v93
	ds_read_b128 v[74:77], v79 offset:55296
	ds_read_b128 v[80:83], v79 offset:53248
	ds_read_b128 v[84:87], v79 offset:51200
	ds_read_b128 v[110:113], v79 offset:49152
	v_add_u32_e32 v79, v104, v100
	ds_read_b128 v[114:117], v79 offset:38912
	ds_read_b128 v[118:121], v79 offset:36864
	ds_read_b128 v[122:125], v79 offset:34816
	ds_read_b128 v[126:129], v79 offset:32768
	s_setprio 1
	s_waitcnt lgkmcnt(0)
	v_mfma_f32_16x16x32_bf16 v[60:63], v[110:113], v[126:129], v[60:63]
	v_mfma_f32_16x16x32_bf16 v[56:59], v[84:87], v[126:129], v[56:59]
	v_mfma_f32_16x16x32_bf16 v[52:55], v[80:83], v[126:129], v[52:55]
	v_mfma_f32_16x16x32_bf16 v[48:51], v[74:77], v[126:129], v[48:51]
	v_mfma_f32_16x16x32_bf16 v[44:47], v[110:113], v[122:125], v[44:47]
	v_mfma_f32_16x16x32_bf16 v[40:43], v[84:87], v[122:125], v[40:43]
	v_mfma_f32_16x16x32_bf16 v[36:39], v[80:83], v[122:125], v[36:39]
	v_mfma_f32_16x16x32_bf16 v[32:35], v[74:77], v[122:125], v[32:35]
	v_mfma_f32_16x16x32_bf16 v[28:31], v[110:113], v[118:121], v[28:31]
	v_mfma_f32_16x16x32_bf16 v[24:27], v[84:87], v[118:121], v[24:27]
	v_mfma_f32_16x16x32_bf16 v[20:23], v[80:83], v[118:121], v[20:23]
	v_mfma_f32_16x16x32_bf16 v[16:19], v[74:77], v[118:121], v[16:19]
	v_mfma_f32_16x16x32_bf16 v[12:15], v[110:113], v[114:117], v[12:15]
	v_mfma_f32_16x16x32_bf16 v[8:11], v[84:87], v[114:117], v[8:11]
	v_mfma_f32_16x16x32_bf16 v[4:7], v[80:83], v[114:117], v[4:7]
	v_mfma_f32_16x16x32_bf16 v[0:3], v[74:77], v[114:117], v[0:3]
	s_setprio 0
	v_add_u32_e32 v79, v105, v100
	ds_read_b128 v[74:77], v79 offset:32768
	ds_read_b128 v[80:83], v79 offset:34816
	ds_read_b128 v[84:87], v79 offset:36864
	ds_read_b128 v[110:113], v79 offset:38912
	v_add_u32_e32 v79, v105, v93
	ds_read_b128 v[114:117], v79 offset:49152
	ds_read_b128 v[118:121], v79 offset:51200
	ds_read_b128 v[122:125], v79 offset:53248
	ds_read_b128 v[126:129], v79 offset:55296
	s_setprio 1
	s_waitcnt lgkmcnt(3)
	v_mfma_f32_16x16x32_bf16 v[60:63], v[114:117], v[74:77], v[60:63]
	s_waitcnt lgkmcnt(2)
	v_mfma_f32_16x16x32_bf16 v[56:59], v[118:121], v[74:77], v[56:59]
	s_waitcnt lgkmcnt(1)
	v_mfma_f32_16x16x32_bf16 v[52:55], v[122:125], v[74:77], v[52:55]
	s_waitcnt lgkmcnt(0)
	v_mfma_f32_16x16x32_bf16 v[48:51], v[126:129], v[74:77], v[48:51]
	v_mfma_f32_16x16x32_bf16 v[44:47], v[114:117], v[80:83], v[44:47]
	v_mfma_f32_16x16x32_bf16 v[40:43], v[118:121], v[80:83], v[40:43]
	v_mfma_f32_16x16x32_bf16 v[36:39], v[122:125], v[80:83], v[36:39]
	v_mfma_f32_16x16x32_bf16 v[32:35], v[126:129], v[80:83], v[32:35]
	v_mfma_f32_16x16x32_bf16 v[28:31], v[114:117], v[84:87], v[28:31]
	v_mfma_f32_16x16x32_bf16 v[24:27], v[118:121], v[84:87], v[24:27]
	v_mfma_f32_16x16x32_bf16 v[20:23], v[122:125], v[84:87], v[20:23]
	v_mfma_f32_16x16x32_bf16 v[16:19], v[126:129], v[84:87], v[16:19]
	v_mfma_f32_16x16x32_bf16 v[12:15], v[114:117], v[110:113], v[12:15]
	v_mfma_f32_16x16x32_bf16 v[8:11], v[118:121], v[110:113], v[8:11]
	v_mfma_f32_16x16x32_bf16 v[4:7], v[122:125], v[110:113], v[4:7]
	v_mfma_f32_16x16x32_bf16 v[0:3], v[126:129], v[110:113], v[0:3]
	s_setprio 0
	s_waitcnt vmcnt(0)
	v_and_b32_e32 v74, 0xfffff8, v78
	v_cmp_ne_u32_e32 vcc, 16, v74
	s_mov_b64 s[6:7], s[0:1]
	s_barrier
	s_and_saveexec_b64 s[58:59], vcc
	s_mov_b64 s[92:93], s[52:53]
	s_cbranch_execz .LBB0_160
	v_readlane_b32 s6, v254, 29
	v_readlane_b32 s7, v254, 30
	v_cmp_lt_u32_e32 vcc, 23, v78
	v_lshlrev_b32_e32 v80, 7, v67
	v_lshl_add_u64 v[74:75], v[96:97], 1, s[6:7]
	v_mul_f32_e32 v83, 0xbfb8aa3b, v60
	v_mul_f32_e32 v84, 0xbfb8aa3b, v61
	v_mul_f32_e32 v79, 0xbfb8aa3b, v62
	v_mul_f32_e32 v82, 0xbfb8aa3b, v63
	v_mul_f32_e32 v126, 0xbfb8aa3b, v56
	v_mul_f32_e32 v127, 0xbfb8aa3b, v57
	v_mul_f32_e32 v124, 0xbfb8aa3b, v58
	v_mul_f32_e32 v125, 0xbfb8aa3b, v59
	v_mul_f32_e32 v122, 0xbfb8aa3b, v52
	v_mul_f32_e32 v123, 0xbfb8aa3b, v53
	v_mul_f32_e32 v120, 0xbfb8aa3b, v54
	v_mul_f32_e32 v121, 0xbfb8aa3b, v55
	v_mul_f32_e32 v118, 0xbfb8aa3b, v48
	v_mul_f32_e32 v119, 0xbfb8aa3b, v49
	v_mul_f32_e32 v116, 0xbfb8aa3b, v50
	v_mul_f32_e32 v117, 0xbfb8aa3b, v51
	v_mul_f32_e32 v114, 0xbfb8aa3b, v44
	v_mul_f32_e32 v115, 0xbfb8aa3b, v45
	v_mul_f32_e32 v112, 0xbfb8aa3b, v46
	v_mul_f32_e32 v113, 0xbfb8aa3b, v47
	v_mul_f32_e32 v110, 0xbfb8aa3b, v40
	v_mul_f32_e32 v111, 0xbfb8aa3b, v41
	v_mul_f32_e32 v67, 0xbfb8aa3b, v42
	v_mul_f32_e32 v109, 0xbfb8aa3b, v43
	s_and_saveexec_b64 s[6:7], vcc
	s_xor_b64 s[60:61], exec, s[6:7]
	s_cbranch_execz .LBB0_218
	v_mov_b32_e32 v40, v97
	s_nop 0
	v_add_u32_e32 v40, v40, v176
	v_ashrrev_i32_e32 v42, 1, v40
	v_and_b32_e32 v41, 64, v40
	v_and_b32_e32 v42, 0xffffffc0, v42
	v_lshrrev_b32_e32 v43, 2, v40
	v_and_or_b32 v40, v40, 15, v80
	v_and_or_b32 v43, v43, 12, v41
	v_add_u32_e32 v42, v40, v42
	v_exp_f32_e32 v44, v83
	v_exp_f32_e32 v45, v79
	v_lshlrev_b32_e32 v96, 1, v43
	v_exp_f32_e32 v46, v84
	v_exp_f32_e32 v47, v82
	v_pk_add_f32 v[44:45], v[44:45], 1.0 op_sel_hi:[1,0]
	s_movk_i32 s67, 0x3200
	v_mad_i64_i32 v[40:41], s[6:7], v42, s67, v[74:75]
	v_lshl_add_u64 v[40:41], v[40:41], 0, v[96:97]
	v_rcp_f32_e32 v43, v44
	s_nop 0
	v_rcp_f32_e32 v48, v45
	v_pk_add_f32 v[44:45], v[46:47], 1.0 op_sel_hi:[1,0]
	s_nop 0
	s_nop 0
	v_rcp_f32_e32 v44, v44
	s_nop 0
	v_rcp_f32_e32 v45, v45
	v_and_b32_sdwa v46, v48, v154 dst_sel:DWORD dst_unused:UNUSED_PAD src0_sel:WORD_1 src1_sel:DWORD
	v_and_b32_sdwa v47, v43, v154 dst_sel:DWORD dst_unused:UNUSED_PAD src0_sel:WORD_1 src1_sel:DWORD
	v_add3_u32 v43, v43, v47, s33
	v_add3_u32 v46, v48, v46, s33
	v_and_b32_sdwa v47, v45, v154 dst_sel:DWORD dst_unused:UNUSED_PAD src0_sel:WORD_1 src1_sel:DWORD
	v_and_b32_sdwa v48, v44, v154 dst_sel:DWORD dst_unused:UNUSED_PAD src0_sel:WORD_1 src1_sel:DWORD
	v_add3_u32 v45, v45, v47, s33
	v_add3_u32 v44, v44, v48, s33
	v_and_b32_e32 v45, 0xffff0000, v45
	v_and_b32_e32 v44, 0xffff0000, v44
	v_or_b32_sdwa v45, v45, v46 dst_sel:DWORD dst_unused:UNUSED_PAD src0_sel:DWORD src1_sel:WORD_1
	v_or_b32_sdwa v44, v44, v43 dst_sel:DWORD dst_unused:UNUSED_PAD src0_sel:DWORD src1_sel:WORD_1
	global_store_dwordx2 v[40:41], v[44:45], off
	v_exp_f32_e32 v44, v126
	v_exp_f32_e32 v45, v124
	v_exp_f32_e32 v46, v127
	v_exp_f32_e32 v47, v125
	v_pk_add_f32 v[44:45], v[44:45], 1.0 op_sel_hi:[1,0]
	s_nop 0
	s_nop 0
	v_rcp_f32_e32 v43, v44
	s_nop 0
	v_rcp_f32_e32 v48, v45
	v_pk_add_f32 v[44:45], v[46:47], 1.0 op_sel_hi:[1,0]
	s_nop 0
	s_nop 0
	v_rcp_f32_e32 v44, v44
	s_nop 0
	v_rcp_f32_e32 v45, v45
	v_and_b32_sdwa v46, v48, v154 dst_sel:DWORD dst_unused:UNUSED_PAD src0_sel:WORD_1 src1_sel:DWORD
	v_and_b32_sdwa v47, v43, v154 dst_sel:DWORD dst_unused:UNUSED_PAD src0_sel:WORD_1 src1_sel:DWORD
	v_add3_u32 v43, v43, v47, s33
	v_add3_u32 v46, v48, v46, s33
	v_and_b32_sdwa v47, v45, v154 dst_sel:DWORD dst_unused:UNUSED_PAD src0_sel:WORD_1 src1_sel:DWORD
	v_and_b32_sdwa v48, v44, v154 dst_sel:DWORD dst_unused:UNUSED_PAD src0_sel:WORD_1 src1_sel:DWORD
	v_add3_u32 v45, v45, v47, s33
	v_add3_u32 v44, v44, v48, s33
	v_and_b32_e32 v45, 0xffff0000, v45
	v_and_b32_e32 v44, 0xffff0000, v44
	v_or_b32_sdwa v45, v45, v46 dst_sel:DWORD dst_unused:UNUSED_PAD src0_sel:DWORD src1_sel:WORD_1
	v_or_b32_sdwa v44, v44, v43 dst_sel:DWORD dst_unused:UNUSED_PAD src0_sel:DWORD src1_sel:WORD_1
	global_store_dwordx2 v[40:41], v[44:45], off offset:32
	v_exp_f32_e32 v44, v122
	v_exp_f32_e32 v45, v120
	v_exp_f32_e32 v46, v123
	v_exp_f32_e32 v47, v121
	v_pk_add_f32 v[44:45], v[44:45], 1.0 op_sel_hi:[1,0]
	s_nop 0
	s_nop 0
	v_rcp_f32_e32 v43, v44
	s_nop 0
	v_rcp_f32_e32 v48, v45
	v_pk_add_f32 v[44:45], v[46:47], 1.0 op_sel_hi:[1,0]
	s_nop 0
	s_nop 0
	v_rcp_f32_e32 v44, v44
	s_nop 0
	v_rcp_f32_e32 v45, v45
	v_and_b32_sdwa v46, v48, v154 dst_sel:DWORD dst_unused:UNUSED_PAD src0_sel:WORD_1 src1_sel:DWORD
	v_and_b32_sdwa v47, v43, v154 dst_sel:DWORD dst_unused:UNUSED_PAD src0_sel:WORD_1 src1_sel:DWORD
	v_add3_u32 v43, v43, v47, s33
	v_add3_u32 v46, v48, v46, s33
	v_and_b32_sdwa v47, v45, v154 dst_sel:DWORD dst_unused:UNUSED_PAD src0_sel:WORD_1 src1_sel:DWORD
	v_and_b32_sdwa v48, v44, v154 dst_sel:DWORD dst_unused:UNUSED_PAD src0_sel:WORD_1 src1_sel:DWORD
	v_add3_u32 v45, v45, v47, s33
	v_add3_u32 v44, v44, v48, s33
	v_and_b32_e32 v45, 0xffff0000, v45
	v_and_b32_e32 v44, 0xffff0000, v44
	v_or_b32_sdwa v45, v45, v46 dst_sel:DWORD dst_unused:UNUSED_PAD src0_sel:DWORD src1_sel:WORD_1
	v_or_b32_sdwa v44, v44, v43 dst_sel:DWORD dst_unused:UNUSED_PAD src0_sel:DWORD src1_sel:WORD_1
	global_store_dwordx2 v[40:41], v[44:45], off offset:64
	v_exp_f32_e32 v44, v118
	v_exp_f32_e32 v45, v116
	v_exp_f32_e32 v46, v119
	v_exp_f32_e32 v47, v117
	v_pk_add_f32 v[44:45], v[44:45], 1.0 op_sel_hi:[1,0]
	s_nop 0
	s_nop 0
	v_rcp_f32_e32 v43, v44
	s_nop 0
	v_rcp_f32_e32 v48, v45
	v_pk_add_f32 v[44:45], v[46:47], 1.0 op_sel_hi:[1,0]
	s_nop 0
	s_nop 0
	v_rcp_f32_e32 v44, v44
	s_nop 0
	v_rcp_f32_e32 v45, v45
	v_and_b32_sdwa v46, v48, v154 dst_sel:DWORD dst_unused:UNUSED_PAD src0_sel:WORD_1 src1_sel:DWORD
	v_and_b32_sdwa v47, v43, v154 dst_sel:DWORD dst_unused:UNUSED_PAD src0_sel:WORD_1 src1_sel:DWORD
	v_add3_u32 v43, v43, v47, s33
	v_add3_u32 v46, v48, v46, s33
	v_and_b32_sdwa v47, v45, v154 dst_sel:DWORD dst_unused:UNUSED_PAD src0_sel:WORD_1 src1_sel:DWORD
	v_and_b32_sdwa v48, v44, v154 dst_sel:DWORD dst_unused:UNUSED_PAD src0_sel:WORD_1 src1_sel:DWORD
	v_add3_u32 v45, v45, v47, s33
	v_add3_u32 v44, v44, v48, s33
	v_and_b32_e32 v45, 0xffff0000, v45
	v_and_b32_e32 v44, 0xffff0000, v44
	v_or_b32_sdwa v45, v45, v46 dst_sel:DWORD dst_unused:UNUSED_PAD src0_sel:DWORD src1_sel:WORD_1
	v_or_b32_sdwa v44, v44, v43 dst_sel:DWORD dst_unused:UNUSED_PAD src0_sel:DWORD src1_sel:WORD_1
	global_store_dwordx2 v[40:41], v[44:45], off offset:96
	v_exp_f32_e32 v44, v114
	v_exp_f32_e32 v45, v112
	v_exp_f32_e32 v46, v115
	v_exp_f32_e32 v47, v113
	v_or_b32_e32 v40, 16, v42
	v_pk_add_f32 v[44:45], v[44:45], 1.0 op_sel_hi:[1,0]
	v_mad_i64_i32 v[40:41], s[6:7], v40, s67, v[74:75]
	v_lshl_add_u64 v[40:41], v[40:41], 0, v[96:97]
	v_mul_f32_e32 v37, 0xbfb8aa3b, v37
	v_mul_f32_e32 v36, 0xbfb8aa3b, v36
	v_rcp_f32_e32 v43, v44
	v_exp_f32_e32 v36, v36
	v_mul_f32_e32 v33, 0xbfb8aa3b, v33
	v_mul_f32_e32 v32, 0xbfb8aa3b, v32
	v_rcp_f32_e32 v48, v45
	v_pk_add_f32 v[44:45], v[46:47], 1.0 op_sel_hi:[1,0]
	v_exp_f32_e32 v32, v32
	s_nop 0
	v_rcp_f32_e32 v44, v44
	s_nop 0
	v_rcp_f32_e32 v45, v45
	v_and_b32_sdwa v46, v48, v154 dst_sel:DWORD dst_unused:UNUSED_PAD src0_sel:WORD_1 src1_sel:DWORD
	v_and_b32_sdwa v47, v43, v154 dst_sel:DWORD dst_unused:UNUSED_PAD src0_sel:WORD_1 src1_sel:DWORD
	v_add3_u32 v43, v43, v47, s33
	v_add3_u32 v46, v48, v46, s33
	v_and_b32_sdwa v47, v45, v154 dst_sel:DWORD dst_unused:UNUSED_PAD src0_sel:WORD_1 src1_sel:DWORD
	v_and_b32_sdwa v48, v44, v154 dst_sel:DWORD dst_unused:UNUSED_PAD src0_sel:WORD_1 src1_sel:DWORD
	v_add3_u32 v45, v45, v47, s33
	v_add3_u32 v44, v44, v48, s33
	v_and_b32_e32 v45, 0xffff0000, v45
	v_and_b32_e32 v44, 0xffff0000, v44
	v_or_b32_sdwa v45, v45, v46 dst_sel:DWORD dst_unused:UNUSED_PAD src0_sel:DWORD src1_sel:WORD_1
	v_or_b32_sdwa v44, v44, v43 dst_sel:DWORD dst_unused:UNUSED_PAD src0_sel:DWORD src1_sel:WORD_1
	global_store_dwordx2 v[40:41], v[44:45], off
	v_exp_f32_e32 v44, v110
	v_exp_f32_e32 v45, v67
	v_exp_f32_e32 v46, v111
	v_exp_f32_e32 v47, v109
	v_pk_add_f32 v[44:45], v[44:45], 1.0 op_sel_hi:[1,0]
	s_nop 0
	s_nop 0
	v_rcp_f32_e32 v43, v44
	s_nop 0
	v_rcp_f32_e32 v48, v45
	v_pk_add_f32 v[44:45], v[46:47], 1.0 op_sel_hi:[1,0]
	s_nop 0
	s_nop 0
	v_rcp_f32_e32 v44, v44
	s_nop 0
	v_rcp_f32_e32 v45, v45
	v_and_b32_sdwa v46, v48, v154 dst_sel:DWORD dst_unused:UNUSED_PAD src0_sel:WORD_1 src1_sel:DWORD
	v_and_b32_sdwa v47, v43, v154 dst_sel:DWORD dst_unused:UNUSED_PAD src0_sel:WORD_1 src1_sel:DWORD
	v_add3_u32 v43, v43, v47, s33
	v_add3_u32 v46, v48, v46, s33
	v_and_b32_sdwa v47, v45, v154 dst_sel:DWORD dst_unused:UNUSED_PAD src0_sel:WORD_1 src1_sel:DWORD
	v_and_b32_sdwa v48, v44, v154 dst_sel:DWORD dst_unused:UNUSED_PAD src0_sel:WORD_1 src1_sel:DWORD
	v_add3_u32 v45, v45, v47, s33
	v_add3_u32 v44, v44, v48, s33
	v_and_b32_e32 v45, 0xffff0000, v45
	v_and_b32_e32 v44, 0xffff0000, v44
	v_or_b32_sdwa v45, v45, v46 dst_sel:DWORD dst_unused:UNUSED_PAD src0_sel:DWORD src1_sel:WORD_1
	v_or_b32_sdwa v44, v44, v43 dst_sel:DWORD dst_unused:UNUSED_PAD src0_sel:DWORD src1_sel:WORD_1
	global_store_dwordx2 v[40:41], v[44:45], off offset:32
	v_exp_f32_e32 v44, v37
	v_mul_f32_e32 v37, 0xbfb8aa3b, v38
	v_exp_f32_e32 v37, v37
	v_mul_f32_e32 v38, 0xbfb8aa3b, v39
	v_exp_f32_e32 v45, v38
	v_pk_add_f32 v[36:37], v[36:37], 1.0 op_sel_hi:[1,0]
	s_nop 0
	s_nop 0
	v_rcp_f32_e32 v38, v36
	s_nop 0
	v_rcp_f32_e32 v39, v37
	v_pk_add_f32 v[36:37], v[44:45], 1.0 op_sel_hi:[1,0]
	s_nop 0
	s_nop 0
	v_rcp_f32_e32 v36, v36
	s_nop 0
	v_rcp_f32_e32 v37, v37
	v_and_b32_sdwa v43, v39, v154 dst_sel:DWORD dst_unused:UNUSED_PAD src0_sel:WORD_1 src1_sel:DWORD
	v_and_b32_sdwa v44, v38, v154 dst_sel:DWORD dst_unused:UNUSED_PAD src0_sel:WORD_1 src1_sel:DWORD
	v_add3_u32 v38, v38, v44, s33
	v_add3_u32 v39, v39, v43, s33
	v_and_b32_sdwa v43, v37, v154 dst_sel:DWORD dst_unused:UNUSED_PAD src0_sel:WORD_1 src1_sel:DWORD
	v_and_b32_sdwa v44, v36, v154 dst_sel:DWORD dst_unused:UNUSED_PAD src0_sel:WORD_1 src1_sel:DWORD
	v_add3_u32 v37, v37, v43, s33
	v_add3_u32 v36, v36, v44, s33
	v_and_b32_e32 v37, 0xffff0000, v37
	v_and_b32_e32 v36, 0xffff0000, v36
	v_or_b32_sdwa v37, v37, v39 dst_sel:DWORD dst_unused:UNUSED_PAD src0_sel:DWORD src1_sel:WORD_1
	v_or_b32_sdwa v36, v36, v38 dst_sel:DWORD dst_unused:UNUSED_PAD src0_sel:DWORD src1_sel:WORD_1
	global_store_dwordx2 v[40:41], v[36:37], off offset:64
	v_exp_f32_e32 v36, v33
	v_mul_f32_e32 v33, 0xbfb8aa3b, v34
	v_exp_f32_e32 v33, v33
	v_mul_f32_e32 v34, 0xbfb8aa3b, v35
	v_exp_f32_e32 v37, v34
	v_pk_add_f32 v[32:33], v[32:33], 1.0 op_sel_hi:[1,0]
	s_nop 0
	s_nop 0
	v_rcp_f32_e32 v34, v32
	s_nop 0
	v_rcp_f32_e32 v35, v33
	v_pk_add_f32 v[32:33], v[36:37], 1.0 op_sel_hi:[1,0]
	s_nop 0
	s_nop 0
	v_rcp_f32_e32 v32, v32
	s_nop 0
	v_rcp_f32_e32 v33, v33
	v_and_b32_sdwa v36, v35, v154 dst_sel:DWORD dst_unused:UNUSED_PAD src0_sel:WORD_1 src1_sel:DWORD
	v_and_b32_sdwa v37, v34, v154 dst_sel:DWORD dst_unused:UNUSED_PAD src0_sel:WORD_1 src1_sel:DWORD
	v_add3_u32 v34, v34, v37, s33
	v_add3_u32 v35, v35, v36, s33
	v_and_b32_sdwa v36, v33, v154 dst_sel:DWORD dst_unused:UNUSED_PAD src0_sel:WORD_1 src1_sel:DWORD
	v_and_b32_sdwa v37, v32, v154 dst_sel:DWORD dst_unused:UNUSED_PAD src0_sel:WORD_1 src1_sel:DWORD
	v_add3_u32 v33, v33, v36, s33
	v_add3_u32 v32, v32, v37, s33
	v_and_b32_e32 v33, 0xffff0000, v33
	v_and_b32_e32 v32, 0xffff0000, v32
	v_or_b32_sdwa v33, v33, v35 dst_sel:DWORD dst_unused:UNUSED_PAD src0_sel:DWORD src1_sel:WORD_1
	v_or_b32_sdwa v32, v32, v34 dst_sel:DWORD dst_unused:UNUSED_PAD src0_sel:DWORD src1_sel:WORD_1
	global_store_dwordx2 v[40:41], v[32:33], off offset:96
	v_mul_f32_e32 v28, 0xbfb8aa3b, v28
	v_exp_f32_e32 v34, v28
	v_mul_f32_e32 v28, 0xbfb8aa3b, v29
	v_exp_f32_e32 v36, v28
	v_mul_f32_e32 v28, 0xbfb8aa3b, v30
	v_exp_f32_e32 v35, v28
	v_or_b32_e32 v32, 32, v42
	v_mad_i64_i32 v[32:33], s[6:7], v32, s67, v[74:75]
	v_mul_f32_e32 v28, 0xbfb8aa3b, v31
	v_pk_add_f32 v[30:31], v[34:35], 1.0 op_sel_hi:[1,0]
	v_exp_f32_e32 v37, v28
	v_lshl_add_u64 v[28:29], v[32:33], 0, v[96:97]
	v_mul_f32_e32 v25, 0xbfb8aa3b, v25
	v_mul_f32_e32 v24, 0xbfb8aa3b, v24
	v_exp_f32_e32 v24, v24
	v_rcp_f32_e32 v32, v30
	v_mul_f32_e32 v21, 0xbfb8aa3b, v21
	v_mul_f32_e32 v20, 0xbfb8aa3b, v20
	v_exp_f32_e32 v20, v20
	v_rcp_f32_e32 v33, v31
	v_pk_add_f32 v[30:31], v[36:37], 1.0 op_sel_hi:[1,0]
	v_mul_f32_e32 v17, 0xbfb8aa3b, v17
	v_mul_f32_e32 v16, 0xbfb8aa3b, v16
	v_exp_f32_e32 v16, v16
	v_rcp_f32_e32 v30, v30
	s_nop 0
	v_rcp_f32_e32 v31, v31
	v_and_b32_sdwa v34, v33, v154 dst_sel:DWORD dst_unused:UNUSED_PAD src0_sel:WORD_1 src1_sel:DWORD
	v_and_b32_sdwa v35, v32, v154 dst_sel:DWORD dst_unused:UNUSED_PAD src0_sel:WORD_1 src1_sel:DWORD
	v_add3_u32 v32, v32, v35, s33
	v_add3_u32 v33, v33, v34, s33
	v_and_b32_sdwa v34, v31, v154 dst_sel:DWORD dst_unused:UNUSED_PAD src0_sel:WORD_1 src1_sel:DWORD
	v_and_b32_sdwa v35, v30, v154 dst_sel:DWORD dst_unused:UNUSED_PAD src0_sel:WORD_1 src1_sel:DWORD
	v_add3_u32 v31, v31, v34, s33
	v_add3_u32 v30, v30, v35, s33
	v_and_b32_e32 v31, 0xffff0000, v31
	v_and_b32_e32 v30, 0xffff0000, v30
	v_or_b32_sdwa v31, v31, v33 dst_sel:DWORD dst_unused:UNUSED_PAD src0_sel:DWORD src1_sel:WORD_1
	v_or_b32_sdwa v30, v30, v32 dst_sel:DWORD dst_unused:UNUSED_PAD src0_sel:DWORD src1_sel:WORD_1
	global_store_dwordx2 v[28:29], v[30:31], off
	v_exp_f32_e32 v30, v25
	v_mul_f32_e32 v25, 0xbfb8aa3b, v26
	v_exp_f32_e32 v25, v25
	v_mul_f32_e32 v26, 0xbfb8aa3b, v27
	v_exp_f32_e32 v31, v26
	v_pk_add_f32 v[24:25], v[24:25], 1.0 op_sel_hi:[1,0]
	s_nop 0
	s_nop 0
	v_rcp_f32_e32 v26, v24
	s_nop 0
	v_rcp_f32_e32 v27, v25
	v_pk_add_f32 v[24:25], v[30:31], 1.0 op_sel_hi:[1,0]
	s_nop 0
	s_nop 0
	v_rcp_f32_e32 v24, v24
	s_nop 0
	v_rcp_f32_e32 v25, v25
	v_and_b32_sdwa v30, v27, v154 dst_sel:DWORD dst_unused:UNUSED_PAD src0_sel:WORD_1 src1_sel:DWORD
	v_and_b32_sdwa v31, v26, v154 dst_sel:DWORD dst_unused:UNUSED_PAD src0_sel:WORD_1 src1_sel:DWORD
	v_add3_u32 v26, v26, v31, s33
	v_add3_u32 v27, v27, v30, s33
	v_and_b32_sdwa v30, v25, v154 dst_sel:DWORD dst_unused:UNUSED_PAD src0_sel:WORD_1 src1_sel:DWORD
	v_and_b32_sdwa v31, v24, v154 dst_sel:DWORD dst_unused:UNUSED_PAD src0_sel:WORD_1 src1_sel:DWORD
	v_add3_u32 v25, v25, v30, s33
	v_add3_u32 v24, v24, v31, s33
	v_and_b32_e32 v25, 0xffff0000, v25
	v_and_b32_e32 v24, 0xffff0000, v24
	v_or_b32_sdwa v25, v25, v27 dst_sel:DWORD dst_unused:UNUSED_PAD src0_sel:DWORD src1_sel:WORD_1
	v_or_b32_sdwa v24, v24, v26 dst_sel:DWORD dst_unused:UNUSED_PAD src0_sel:DWORD src1_sel:WORD_1
	global_store_dwordx2 v[28:29], v[24:25], off offset:32
	v_exp_f32_e32 v24, v21
	v_mul_f32_e32 v21, 0xbfb8aa3b, v22
	v_exp_f32_e32 v21, v21
	v_mul_f32_e32 v22, 0xbfb8aa3b, v23
	v_exp_f32_e32 v25, v22
	v_pk_add_f32 v[20:21], v[20:21], 1.0 op_sel_hi:[1,0]
	s_nop 0
	s_nop 0
	v_rcp_f32_e32 v22, v20
	s_nop 0
	v_rcp_f32_e32 v23, v21
	v_pk_add_f32 v[20:21], v[24:25], 1.0 op_sel_hi:[1,0]
	s_nop 0
	s_nop 0
	v_rcp_f32_e32 v20, v20
	s_nop 0
	v_rcp_f32_e32 v21, v21
	v_and_b32_sdwa v24, v23, v154 dst_sel:DWORD dst_unused:UNUSED_PAD src0_sel:WORD_1 src1_sel:DWORD
	v_and_b32_sdwa v25, v22, v154 dst_sel:DWORD dst_unused:UNUSED_PAD src0_sel:WORD_1 src1_sel:DWORD
	v_add3_u32 v22, v22, v25, s33
	v_add3_u32 v23, v23, v24, s33
	v_and_b32_sdwa v24, v21, v154 dst_sel:DWORD dst_unused:UNUSED_PAD src0_sel:WORD_1 src1_sel:DWORD
	v_and_b32_sdwa v25, v20, v154 dst_sel:DWORD dst_unused:UNUSED_PAD src0_sel:WORD_1 src1_sel:DWORD
	v_add3_u32 v21, v21, v24, s33
	v_add3_u32 v20, v20, v25, s33
	v_and_b32_e32 v21, 0xffff0000, v21
	v_and_b32_e32 v20, 0xffff0000, v20
	v_or_b32_sdwa v21, v21, v23 dst_sel:DWORD dst_unused:UNUSED_PAD src0_sel:DWORD src1_sel:WORD_1
	v_or_b32_sdwa v20, v20, v22 dst_sel:DWORD dst_unused:UNUSED_PAD src0_sel:DWORD src1_sel:WORD_1
	global_store_dwordx2 v[28:29], v[20:21], off offset:64
	v_exp_f32_e32 v20, v17
	v_mul_f32_e32 v17, 0xbfb8aa3b, v18
	v_exp_f32_e32 v17, v17
	v_mul_f32_e32 v18, 0xbfb8aa3b, v19
	v_exp_f32_e32 v21, v18
	v_pk_add_f32 v[16:17], v[16:17], 1.0 op_sel_hi:[1,0]
	s_nop 0
	s_nop 0
	v_rcp_f32_e32 v18, v16
	s_nop 0
	v_rcp_f32_e32 v19, v17
	v_pk_add_f32 v[16:17], v[20:21], 1.0 op_sel_hi:[1,0]
	s_nop 0
	s_nop 0
	v_rcp_f32_e32 v16, v16
	s_nop 0
	v_rcp_f32_e32 v17, v17
	v_and_b32_sdwa v20, v19, v154 dst_sel:DWORD dst_unused:UNUSED_PAD src0_sel:WORD_1 src1_sel:DWORD
	v_and_b32_sdwa v21, v18, v154 dst_sel:DWORD dst_unused:UNUSED_PAD src0_sel:WORD_1 src1_sel:DWORD
	v_add3_u32 v18, v18, v21, s33
	v_add3_u32 v19, v19, v20, s33
	v_and_b32_sdwa v20, v17, v154 dst_sel:DWORD dst_unused:UNUSED_PAD src0_sel:WORD_1 src1_sel:DWORD
	v_and_b32_sdwa v21, v16, v154 dst_sel:DWORD dst_unused:UNUSED_PAD src0_sel:WORD_1 src1_sel:DWORD
	v_add3_u32 v17, v17, v20, s33
	v_add3_u32 v16, v16, v21, s33
	v_and_b32_e32 v17, 0xffff0000, v17
	v_and_b32_e32 v16, 0xffff0000, v16
	v_or_b32_sdwa v17, v17, v19 dst_sel:DWORD dst_unused:UNUSED_PAD src0_sel:DWORD src1_sel:WORD_1
	v_or_b32_sdwa v16, v16, v18 dst_sel:DWORD dst_unused:UNUSED_PAD src0_sel:DWORD src1_sel:WORD_1
	global_store_dwordx2 v[28:29], v[16:17], off offset:96
	v_mul_f32_e32 v12, 0xbfb8aa3b, v12
	v_exp_f32_e32 v18, v12
	v_mul_f32_e32 v12, 0xbfb8aa3b, v13
	v_exp_f32_e32 v20, v12
	v_mul_f32_e32 v12, 0xbfb8aa3b, v14
	v_exp_f32_e32 v19, v12
	v_or_b32_e32 v16, 48, v42
	v_mad_i64_i32 v[16:17], s[6:7], v16, s67, v[74:75]
	v_mul_f32_e32 v12, 0xbfb8aa3b, v15
	v_pk_add_f32 v[14:15], v[18:19], 1.0 op_sel_hi:[1,0]
	v_exp_f32_e32 v21, v12
	v_lshl_add_u64 v[12:13], v[16:17], 0, v[96:97]
	v_mul_f32_e32 v9, 0xbfb8aa3b, v9
	v_mul_f32_e32 v8, 0xbfb8aa3b, v8
	v_exp_f32_e32 v8, v8
	v_rcp_f32_e32 v16, v14
	v_mul_f32_e32 v5, 0xbfb8aa3b, v5
	v_mul_f32_e32 v4, 0xbfb8aa3b, v4
	v_exp_f32_e32 v4, v4
	v_rcp_f32_e32 v17, v15
	v_pk_add_f32 v[14:15], v[20:21], 1.0 op_sel_hi:[1,0]
	v_mul_f32_e32 v0, 0xbfb8aa3b, v0
	v_exp_f32_e32 v0, v0
	v_rcp_f32_e32 v14, v14
	v_add_f32_e32 v0, 1.0, v0
	v_rcp_f32_e32 v15, v15
	v_and_b32_sdwa v18, v17, v154 dst_sel:DWORD dst_unused:UNUSED_PAD src0_sel:WORD_1 src1_sel:DWORD
	v_and_b32_sdwa v19, v16, v154 dst_sel:DWORD dst_unused:UNUSED_PAD src0_sel:WORD_1 src1_sel:DWORD
	v_add3_u32 v16, v16, v19, s33
	v_add3_u32 v17, v17, v18, s33
	v_and_b32_sdwa v18, v15, v154 dst_sel:DWORD dst_unused:UNUSED_PAD src0_sel:WORD_1 src1_sel:DWORD
	v_and_b32_sdwa v19, v14, v154 dst_sel:DWORD dst_unused:UNUSED_PAD src0_sel:WORD_1 src1_sel:DWORD
	v_add3_u32 v15, v15, v18, s33
	v_add3_u32 v14, v14, v19, s33
	v_and_b32_e32 v15, 0xffff0000, v15
	v_and_b32_e32 v14, 0xffff0000, v14
	v_or_b32_sdwa v15, v15, v17 dst_sel:DWORD dst_unused:UNUSED_PAD src0_sel:DWORD src1_sel:WORD_1
	v_or_b32_sdwa v14, v14, v16 dst_sel:DWORD dst_unused:UNUSED_PAD src0_sel:DWORD src1_sel:WORD_1
	global_store_dwordx2 v[12:13], v[14:15], off
	v_exp_f32_e32 v14, v9
	v_mul_f32_e32 v9, 0xbfb8aa3b, v10
	v_exp_f32_e32 v9, v9
	v_mul_f32_e32 v10, 0xbfb8aa3b, v11
	v_exp_f32_e32 v15, v10
	v_pk_add_f32 v[8:9], v[8:9], 1.0 op_sel_hi:[1,0]
	s_nop 0
	s_nop 0
	v_rcp_f32_e32 v10, v8
	s_nop 0
	v_rcp_f32_e32 v11, v9
	v_pk_add_f32 v[8:9], v[14:15], 1.0 op_sel_hi:[1,0]
	s_nop 0
	s_nop 0
	v_rcp_f32_e32 v8, v8
	s_nop 0
	v_rcp_f32_e32 v9, v9
	v_and_b32_sdwa v14, v11, v154 dst_sel:DWORD dst_unused:UNUSED_PAD src0_sel:WORD_1 src1_sel:DWORD
	v_and_b32_sdwa v15, v10, v154 dst_sel:DWORD dst_unused:UNUSED_PAD src0_sel:WORD_1 src1_sel:DWORD
	v_add3_u32 v10, v10, v15, s33
	v_add3_u32 v11, v11, v14, s33
	v_and_b32_sdwa v14, v9, v154 dst_sel:DWORD dst_unused:UNUSED_PAD src0_sel:WORD_1 src1_sel:DWORD
	v_and_b32_sdwa v15, v8, v154 dst_sel:DWORD dst_unused:UNUSED_PAD src0_sel:WORD_1 src1_sel:DWORD
	v_add3_u32 v9, v9, v14, s33
	v_add3_u32 v8, v8, v15, s33
	v_and_b32_e32 v9, 0xffff0000, v9
	v_and_b32_e32 v8, 0xffff0000, v8
	v_or_b32_sdwa v9, v9, v11 dst_sel:DWORD dst_unused:UNUSED_PAD src0_sel:DWORD src1_sel:WORD_1
	v_or_b32_sdwa v8, v8, v10 dst_sel:DWORD dst_unused:UNUSED_PAD src0_sel:DWORD src1_sel:WORD_1
	global_store_dwordx2 v[12:13], v[8:9], off offset:32
	v_exp_f32_e32 v8, v5
	v_mul_f32_e32 v5, 0xbfb8aa3b, v6
	v_exp_f32_e32 v5, v5
	v_mul_f32_e32 v6, 0xbfb8aa3b, v7
	v_exp_f32_e32 v9, v6
	v_pk_add_f32 v[4:5], v[4:5], 1.0 op_sel_hi:[1,0]
	s_nop 0
	s_nop 0
	v_rcp_f32_e32 v6, v4
	s_nop 0
	v_rcp_f32_e32 v7, v5
	v_pk_add_f32 v[4:5], v[8:9], 1.0 op_sel_hi:[1,0]
	s_nop 0
	s_nop 0
	v_rcp_f32_e32 v4, v4
	s_nop 0
	v_rcp_f32_e32 v5, v5
	v_and_b32_sdwa v8, v7, v154 dst_sel:DWORD dst_unused:UNUSED_PAD src0_sel:WORD_1 src1_sel:DWORD
	v_and_b32_sdwa v9, v6, v154 dst_sel:DWORD dst_unused:UNUSED_PAD src0_sel:WORD_1 src1_sel:DWORD
	v_add3_u32 v6, v6, v9, s33
	v_add3_u32 v7, v7, v8, s33
	v_and_b32_sdwa v8, v5, v154 dst_sel:DWORD dst_unused:UNUSED_PAD src0_sel:WORD_1 src1_sel:DWORD
	v_and_b32_sdwa v9, v4, v154 dst_sel:DWORD dst_unused:UNUSED_PAD src0_sel:WORD_1 src1_sel:DWORD
	v_add3_u32 v5, v5, v8, s33
	v_add3_u32 v4, v4, v9, s33
	v_and_b32_e32 v5, 0xffff0000, v5
	v_and_b32_e32 v4, 0xffff0000, v4
	v_or_b32_sdwa v5, v5, v7 dst_sel:DWORD dst_unused:UNUSED_PAD src0_sel:DWORD src1_sel:WORD_1
	v_or_b32_sdwa v4, v4, v6 dst_sel:DWORD dst_unused:UNUSED_PAD src0_sel:DWORD src1_sel:WORD_1
	global_store_dwordx2 v[12:13], v[4:5], off offset:64
	s_nop 0
	v_rcp_f32_e32 v4, v0
	v_mul_f32_e32 v0, 0xbfb8aa3b, v1
	v_exp_f32_e32 v0, v0
	s_nop 0
	v_add_f32_e32 v0, 1.0, v0
	s_nop 0
	v_rcp_f32_e32 v5, v0
	v_mul_f32_e32 v0, 0xbfb8aa3b, v2
	v_exp_f32_e32 v1, v0
	v_mul_f32_e32 v0, 0xbfb8aa3b, v3
	v_exp_f32_e32 v0, v0
	v_bfe_u32 v2, v4, 16, 1
	v_add3_u32 v2, v4, v2, s33
	v_bfe_u32 v3, v5, 16, 1
	v_pk_add_f32 v[0:1], v[0:1], 1.0 op_sel_hi:[1,0]
	v_add3_u32 v3, v5, v3, s33
	v_lshrrev_b32_e32 v2, 16, v2
	v_rcp_f32_e32 v0, v0
	s_mov_b32 s6, 0xffff0000
	v_and_or_b32 v2, v3, s6, v2
	global_store_dword v[12:13], v2, off offset:96
	v_rcp_f32_e32 v1, v1
	s_nop 0
	v_and_b32_sdwa v4, v1, v154 dst_sel:DWORD dst_unused:UNUSED_PAD src0_sel:WORD_1 src1_sel:DWORD
	v_and_b32_sdwa v5, v0, v154 dst_sel:DWORD dst_unused:UNUSED_PAD src0_sel:WORD_1 src1_sel:DWORD
	v_add3_u32 v1, v1, v4, s33
	v_add3_u32 v0, v0, v5, s33
	v_lshrrev_b32_e32 v1, 16, v1
	v_and_or_b32 v81, v0, s6, v1
	s_mov_b64 s[6:7], 0x60
	v_lshl_add_u64 v[76:77], v[12:13], 0, s[6:7]

.LBB0_280:
	v_cndmask_b32_e64 v95, 0, 1, s[0:1]
	s_lshl_b32 s0, s2, 6
	v_cmp_ne_u32_e32 vcc, 1, v95
	v_add3_u32 v95, v78, s0, v124
	ds_read_b128 v[104:107], v95 offset:40960
	ds_read_b128 v[108:111], v95 offset:43264
	ds_read_b128 v[156:159], v95 offset:45568
	ds_read_b128 v[166:169], v95 offset:47872
	v_lshl_or_b32 v95, s2, 5, v123
	v_or_b32_e32 v188, 3, v95
	v_or_b32_e32 v189, 5, v95
	v_min_i32_e32 v188, s93, v188
	v_min_i32_e32 v189, s93, v189
	v_add_u32_e32 v188, s7, v188
	v_add_u32_e32 v189, s7, v189
	v_min_i32_e32 v101, s93, v95
	v_or_b32_e32 v186, 1, v95
	v_or_b32_e32 v187, 2, v95
	v_mad_i64_i32 v[196:197], s[0:1], v188, s8, v[102:103]
	v_or_b32_e32 v188, 4, v95
	v_mad_i64_i32 v[200:201], s[0:1], v189, s8, v[102:103]
	v_or_b32_e32 v189, 6, v95
	v_or_b32_e32 v95, 7, v95
	v_min_i32_e32 v186, s93, v186
	v_min_i32_e32 v187, s93, v187
	v_min_i32_e32 v188, s93, v188
	v_min_i32_e32 v189, s93, v189
	v_min_i32_e32 v95, s93, v95
	v_add_u32_e32 v101, s7, v101
	v_add_u32_e32 v186, s7, v186
	v_add_u32_e32 v187, s7, v187
	v_add_u32_e32 v188, s7, v188
	v_add_u32_e32 v189, s7, v189
	v_add_u32_e32 v95, s7, v95
	v_mad_i64_i32 v[190:191], s[0:1], v101, s8, v[102:103]
	v_mad_i64_i32 v[192:193], s[0:1], v186, s8, v[102:103]
	v_mad_i64_i32 v[194:195], s[0:1], v187, s8, v[102:103]
	v_mad_i64_i32 v[198:199], s[0:1], v188, s8, v[102:103]
	v_mad_i64_i32 v[202:203], s[0:1], v189, s8, v[102:103]
	v_mad_i64_i32 v[206:207], s[0:1], v95, s8, v[102:103]
	global_load_ushort v101, v[190:191], off offset:2048
	global_load_ushort v186, v[192:193], off offset:2048
	global_load_ushort v187, v[194:195], off offset:2048
	global_load_ushort v204, v[196:197], off offset:2048
	global_load_ushort v188, v[198:199], off offset:2048
	global_load_ushort v208, v[200:201], off offset:2048
	global_load_ushort v189, v[202:203], off offset:2048
	global_load_ushort v95, v[206:207], off offset:2048
	global_load_ushort v210, v[190:191], off offset:2080
	global_load_ushort v211, v[192:193], off offset:2080
	global_load_ushort v212, v[194:195], off offset:2080
	global_load_ushort v213, v[196:197], off offset:2080
	global_load_ushort v214, v[198:199], off offset:2080
	global_load_ushort v215, v[200:201], off offset:2080
	global_load_ushort v216, v[202:203], off offset:2080
	global_load_ushort v217, v[206:207], off offset:2080
	global_load_ushort v218, v[190:191], off offset:2112
	global_load_ushort v219, v[192:193], off offset:2112
	global_load_ushort v220, v[194:195], off offset:2112
	global_load_ushort v221, v[196:197], off offset:2112
	global_load_ushort v222, v[198:199], off offset:2112
	global_load_ushort v223, v[200:201], off offset:2112
	global_load_ushort v224, v[202:203], off offset:2112
	global_load_ushort v225, v[206:207], off offset:2112
	global_load_ushort v226, v[190:191], off offset:2144
	global_load_ushort v227, v[192:193], off offset:2144
	global_load_ushort v228, v[194:195], off offset:2144
	global_load_ushort v229, v[196:197], off offset:2144
	global_load_ushort v230, v[198:199], off offset:2144
	global_load_ushort v231, v[200:201], off offset:2144
	global_load_ushort v232, v[202:203], off offset:2144
	global_load_ushort v233, v[206:207], off offset:2144
	s_setprio 1
	s_waitcnt vmcnt(24)
	v_perm_b32 v189, v95, v189, s9
	v_perm_b32 v188, v208, v188, s9
	v_perm_b32 v187, v204, v187, s9
	v_perm_b32 v186, v186, v101, s9
	s_waitcnt lgkmcnt(3)
	s_nop 0
	v_mfma_f32_16x16x32_bf16 v[60:63], v[104:107], v[186:189], v[60:63]
	s_waitcnt lgkmcnt(2)
	v_mfma_f32_16x16x32_bf16 v[44:47], v[108:111], v[186:189], v[44:47]
	s_waitcnt lgkmcnt(1)
	v_mfma_f32_16x16x32_bf16 v[28:31], v[156:159], v[186:189], v[28:31]
	s_waitcnt lgkmcnt(0)
	v_mfma_f32_16x16x32_bf16 v[12:15], v[166:169], v[186:189], v[12:15]
	s_waitcnt vmcnt(16)
	v_perm_b32 v189, v217, v216, s9
	v_perm_b32 v188, v215, v214, s9
	v_perm_b32 v187, v213, v212, s9
	v_perm_b32 v186, v211, v210, s9
	s_nop 1
	v_mfma_f32_16x16x32_bf16 v[56:59], v[104:107], v[186:189], v[56:59]
	v_mfma_f32_16x16x32_bf16 v[40:43], v[108:111], v[186:189], v[40:43]
	v_mfma_f32_16x16x32_bf16 v[24:27], v[156:159], v[186:189], v[24:27]
	v_mfma_f32_16x16x32_bf16 v[8:11], v[166:169], v[186:189], v[8:11]
	s_waitcnt vmcnt(8)
	v_perm_b32 v189, v225, v224, s9
	v_perm_b32 v188, v223, v222, s9
	v_perm_b32 v187, v221, v220, s9
	v_perm_b32 v186, v219, v218, s9
	s_nop 1
	v_mfma_f32_16x16x32_bf16 v[52:55], v[104:107], v[186:189], v[52:55]
	v_mfma_f32_16x16x32_bf16 v[36:39], v[108:111], v[186:189], v[36:39]
	v_mfma_f32_16x16x32_bf16 v[20:23], v[156:159], v[186:189], v[20:23]
	v_mfma_f32_16x16x32_bf16 v[4:7], v[166:169], v[186:189], v[4:7]
	s_setprio 0
	s_nop 0
	s_setprio 1
	s_waitcnt vmcnt(0)
	v_perm_b32 v189, v233, v232, s9
	v_perm_b32 v188, v231, v230, s9
	v_perm_b32 v187, v229, v228, s9
	v_perm_b32 v186, v227, v226, s9
	s_nop 1
	v_mfma_f32_16x16x32_bf16 v[48:51], v[104:107], v[186:189], v[48:51]
	v_mfma_f32_16x16x32_bf16 v[32:35], v[108:111], v[186:189], v[32:35]
	v_mfma_f32_16x16x32_bf16 v[16:19], v[156:159], v[186:189], v[16:19]
	v_mfma_f32_16x16x32_bf16 v[0:3], v[166:169], v[186:189], v[0:3]
	s_setprio 0
	s_mov_b64 s[0:1], 0
	s_mov_b32 s2, 1
	s_cbranch_vccz .LBB0_280
	v_mul_f32_e32 v95, v56, v56
	v_fmac_f32_e32 v95, v60, v60
	v_fmac_f32_e32 v95, v52, v52
	v_fmac_f32_e32 v95, v48, v48
	s_nop 1
	v_add_f32_dpp v95, v95, v95 quad_perm:[1,0,3,2] row_mask:0xf bank_mask:0xf bound_ctrl:1
	s_nop 1
	v_add_f32_dpp v95, v95, v95 quad_perm:[2,3,0,1] row_mask:0xf bank_mask:0xf bound_ctrl:1
	s_nop 1
	v_add_f32_dpp v95, v95, v95 row_half_mirror row_mask:0xf bank_mask:0xf bound_ctrl:1
	s_nop 1
	v_mov_b32_dpp v101, v95 row_mirror row_mask:0xf bank_mask:0xf bound_ctrl:1
	s_and_saveexec_b64 s[0:1], s[40:41]
	v_add_f32_e32 v95, v95, v101
	ds_write_b32 v184, v95 offset:5120
	s_or_b64 exec, exec, s[0:1]
	v_mul_f32_e32 v95, v57, v57
	v_fmac_f32_e32 v95, v61, v61
	v_fmac_f32_e32 v95, v53, v53
	v_fmac_f32_e32 v95, v49, v49
	s_nop 1
	v_add_f32_dpp v95, v95, v95 quad_perm:[1,0,3,2] row_mask:0xf bank_mask:0xf bound_ctrl:1
	s_nop 1
	v_add_f32_dpp v95, v95, v95 quad_perm:[2,3,0,1] row_mask:0xf bank_mask:0xf bound_ctrl:1
	s_nop 1
	v_add_f32_dpp v95, v95, v95 row_half_mirror row_mask:0xf bank_mask:0xf bound_ctrl:1
	s_nop 1
	v_mov_b32_dpp v101, v95 row_mirror row_mask:0xf bank_mask:0xf bound_ctrl:1
	s_and_saveexec_b64 s[0:1], s[40:41]
	v_add_f32_e32 v95, v95, v101
	ds_write_b32 v184, v95 offset:5124
	s_or_b64 exec, exec, s[0:1]
	v_mul_f32_e32 v95, v58, v58
	v_fmac_f32_e32 v95, v62, v62
	v_fmac_f32_e32 v95, v54, v54
	v_fmac_f32_e32 v95, v50, v50
	s_nop 1
	v_add_f32_dpp v95, v95, v95 quad_perm:[1,0,3,2] row_mask:0xf bank_mask:0xf bound_ctrl:1
	s_nop 1
	v_add_f32_dpp v95, v95, v95 quad_perm:[2,3,0,1] row_mask:0xf bank_mask:0xf bound_ctrl:1
	s_nop 1
	v_add_f32_dpp v95, v95, v95 row_half_mirror row_mask:0xf bank_mask:0xf bound_ctrl:1
	s_nop 1
	v_mov_b32_dpp v101, v95 row_mirror row_mask:0xf bank_mask:0xf bound_ctrl:1
	s_and_saveexec_b64 s[0:1], s[40:41]
	v_add_f32_e32 v95, v95, v101
	ds_write_b32 v184, v95 offset:5128
	s_or_b64 exec, exec, s[0:1]
	v_mul_f32_e32 v95, v59, v59
	v_fmac_f32_e32 v95, v63, v63
	v_fmac_f32_e32 v95, v55, v55
	v_fmac_f32_e32 v95, v51, v51
	s_nop 1
	v_add_f32_dpp v95, v95, v95 quad_perm:[1,0,3,2] row_mask:0xf bank_mask:0xf bound_ctrl:1
	s_nop 1
	v_add_f32_dpp v95, v95, v95 quad_perm:[2,3,0,1] row_mask:0xf bank_mask:0xf bound_ctrl:1
	s_nop 1
	v_add_f32_dpp v95, v95, v95 row_half_mirror row_mask:0xf bank_mask:0xf bound_ctrl:1
	s_nop 1
	v_mov_b32_dpp v101, v95 row_mirror row_mask:0xf bank_mask:0xf bound_ctrl:1
	s_and_saveexec_b64 s[0:1], s[40:41]
	v_add_f32_e32 v95, v95, v101
	ds_write_b32 v184, v95 offset:5132
	s_or_b64 exec, exec, s[0:1]
	v_mul_f32_e32 v95, v40, v40
	v_fmac_f32_e32 v95, v44, v44
	v_fmac_f32_e32 v95, v36, v36
	v_fmac_f32_e32 v95, v32, v32
	s_nop 1
	v_add_f32_dpp v95, v95, v95 quad_perm:[1,0,3,2] row_mask:0xf bank_mask:0xf bound_ctrl:1
	s_nop 1
	v_add_f32_dpp v95, v95, v95 quad_perm:[2,3,0,1] row_mask:0xf bank_mask:0xf bound_ctrl:1
	s_nop 1
	v_add_f32_dpp v95, v95, v95 row_half_mirror row_mask:0xf bank_mask:0xf bound_ctrl:1
	s_nop 1
	v_mov_b32_dpp v101, v95 row_mirror row_mask:0xf bank_mask:0xf bound_ctrl:1
	s_and_saveexec_b64 s[0:1], s[40:41]
	v_add_f32_e32 v95, v95, v101
	ds_write_b32 v184, v95 offset:5184
	s_or_b64 exec, exec, s[0:1]
	v_mul_f32_e32 v95, v41, v41
	v_fmac_f32_e32 v95, v45, v45
	v_fmac_f32_e32 v95, v37, v37
	v_fmac_f32_e32 v95, v33, v33
	s_nop 1
	v_add_f32_dpp v95, v95, v95 quad_perm:[1,0,3,2] row_mask:0xf bank_mask:0xf bound_ctrl:1
	s_nop 1
	v_add_f32_dpp v95, v95, v95 quad_perm:[2,3,0,1] row_mask:0xf bank_mask:0xf bound_ctrl:1
	s_nop 1
	v_add_f32_dpp v95, v95, v95 row_half_mirror row_mask:0xf bank_mask:0xf bound_ctrl:1
	s_nop 1
	v_mov_b32_dpp v101, v95 row_mirror row_mask:0xf bank_mask:0xf bound_ctrl:1
	s_and_saveexec_b64 s[0:1], s[40:41]
	v_add_f32_e32 v95, v95, v101
	ds_write_b32 v184, v95 offset:5188
	s_or_b64 exec, exec, s[0:1]
	v_mul_f32_e32 v95, v42, v42
	v_fmac_f32_e32 v95, v46, v46
	v_fmac_f32_e32 v95, v38, v38
	v_fmac_f32_e32 v95, v34, v34
	s_nop 1
	v_add_f32_dpp v95, v95, v95 quad_perm:[1,0,3,2] row_mask:0xf bank_mask:0xf bound_ctrl:1
	s_nop 1
	v_add_f32_dpp v95, v95, v95 quad_perm:[2,3,0,1] row_mask:0xf bank_mask:0xf bound_ctrl:1
	s_nop 1
	v_add_f32_dpp v95, v95, v95 row_half_mirror row_mask:0xf bank_mask:0xf bound_ctrl:1
	s_nop 1
	v_mov_b32_dpp v101, v95 row_mirror row_mask:0xf bank_mask:0xf bound_ctrl:1
	s_and_saveexec_b64 s[0:1], s[40:41]
	v_add_f32_e32 v95, v95, v101
	ds_write_b32 v184, v95 offset:5192
	s_or_b64 exec, exec, s[0:1]
	v_mul_f32_e32 v95, v43, v43
	v_fmac_f32_e32 v95, v47, v47
	v_fmac_f32_e32 v95, v39, v39
	v_fmac_f32_e32 v95, v35, v35
	s_nop 1
	v_add_f32_dpp v95, v95, v95 quad_perm:[1,0,3,2] row_mask:0xf bank_mask:0xf bound_ctrl:1
	s_nop 1
	v_add_f32_dpp v95, v95, v95 quad_perm:[2,3,0,1] row_mask:0xf bank_mask:0xf bound_ctrl:1
	s_nop 1
	v_add_f32_dpp v95, v95, v95 row_half_mirror row_mask:0xf bank_mask:0xf bound_ctrl:1
	s_nop 1
	v_mov_b32_dpp v101, v95 row_mirror row_mask:0xf bank_mask:0xf bound_ctrl:1
	s_and_saveexec_b64 s[0:1], s[40:41]
	v_add_f32_e32 v95, v95, v101
	ds_write_b32 v184, v95 offset:5196
	s_or_b64 exec, exec, s[0:1]
	v_mul_f32_e32 v95, v24, v24
	v_fmac_f32_e32 v95, v28, v28
	v_fmac_f32_e32 v95, v20, v20
	v_fmac_f32_e32 v95, v16, v16
	s_nop 1
	v_add_f32_dpp v95, v95, v95 quad_perm:[1,0,3,2] row_mask:0xf bank_mask:0xf bound_ctrl:1
	s_nop 1
	v_add_f32_dpp v95, v95, v95 quad_perm:[2,3,0,1] row_mask:0xf bank_mask:0xf bound_ctrl:1
	s_nop 1
	v_add_f32_dpp v95, v95, v95 row_half_mirror row_mask:0xf bank_mask:0xf bound_ctrl:1
	s_nop 1
	v_mov_b32_dpp v101, v95 row_mirror row_mask:0xf bank_mask:0xf bound_ctrl:1
	s_and_saveexec_b64 s[0:1], s[40:41]
	v_add_f32_e32 v95, v95, v101
	ds_write_b32 v184, v95 offset:5248
	s_or_b64 exec, exec, s[0:1]
	v_mul_f32_e32 v95, v25, v25
	v_fmac_f32_e32 v95, v29, v29
	v_fmac_f32_e32 v95, v21, v21
	v_fmac_f32_e32 v95, v17, v17
	s_nop 1
	v_add_f32_dpp v95, v95, v95 quad_perm:[1,0,3,2] row_mask:0xf bank_mask:0xf bound_ctrl:1
	s_nop 1
	v_add_f32_dpp v95, v95, v95 quad_perm:[2,3,0,1] row_mask:0xf bank_mask:0xf bound_ctrl:1
	s_nop 1
	v_add_f32_dpp v95, v95, v95 row_half_mirror row_mask:0xf bank_mask:0xf bound_ctrl:1
	s_nop 1
	v_mov_b32_dpp v101, v95 row_mirror row_mask:0xf bank_mask:0xf bound_ctrl:1
	s_and_saveexec_b64 s[0:1], s[40:41]
	v_add_f32_e32 v95, v95, v101
	ds_write_b32 v184, v95 offset:5252
	s_or_b64 exec, exec, s[0:1]
	v_mul_f32_e32 v95, v26, v26
	v_fmac_f32_e32 v95, v30, v30
	v_fmac_f32_e32 v95, v22, v22
	v_fmac_f32_e32 v95, v18, v18
	s_nop 1
	v_add_f32_dpp v95, v95, v95 quad_perm:[1,0,3,2] row_mask:0xf bank_mask:0xf bound_ctrl:1
	s_nop 1
	v_add_f32_dpp v95, v95, v95 quad_perm:[2,3,0,1] row_mask:0xf bank_mask:0xf bound_ctrl:1
	s_nop 1
	v_add_f32_dpp v95, v95, v95 row_half_mirror row_mask:0xf bank_mask:0xf bound_ctrl:1
	s_nop 1
	v_mov_b32_dpp v101, v95 row_mirror row_mask:0xf bank_mask:0xf bound_ctrl:1
	s_and_saveexec_b64 s[0:1], s[40:41]
	v_add_f32_e32 v95, v95, v101
	ds_write_b32 v184, v95 offset:5256
	s_or_b64 exec, exec, s[0:1]
	v_mul_f32_e32 v95, v27, v27
	v_fmac_f32_e32 v95, v31, v31
	v_fmac_f32_e32 v95, v23, v23
	v_fmac_f32_e32 v95, v19, v19
	s_nop 1
	v_add_f32_dpp v95, v95, v95 quad_perm:[1,0,3,2] row_mask:0xf bank_mask:0xf bound_ctrl:1
	s_nop 1
	v_add_f32_dpp v95, v95, v95 quad_perm:[2,3,0,1] row_mask:0xf bank_mask:0xf bound_ctrl:1
	s_nop 1
	v_add_f32_dpp v95, v95, v95 row_half_mirror row_mask:0xf bank_mask:0xf bound_ctrl:1
	s_nop 1
	v_mov_b32_dpp v101, v95 row_mirror row_mask:0xf bank_mask:0xf bound_ctrl:1
	s_and_saveexec_b64 s[0:1], s[40:41]
	v_add_f32_e32 v95, v95, v101
	ds_write_b32 v184, v95 offset:5260
	s_or_b64 exec, exec, s[0:1]
	v_mul_f32_e32 v95, v8, v8
	v_fmac_f32_e32 v95, v12, v12
	v_fmac_f32_e32 v95, v4, v4
	v_fmac_f32_e32 v95, v0, v0
	s_nop 1
	v_add_f32_dpp v95, v95, v95 quad_perm:[1,0,3,2] row_mask:0xf bank_mask:0xf bound_ctrl:1
	s_nop 1
	v_add_f32_dpp v95, v95, v95 quad_perm:[2,3,0,1] row_mask:0xf bank_mask:0xf bound_ctrl:1
	s_nop 1
	v_add_f32_dpp v95, v95, v95 row_half_mirror row_mask:0xf bank_mask:0xf bound_ctrl:1
	s_nop 1
	v_mov_b32_dpp v101, v95 row_mirror row_mask:0xf bank_mask:0xf bound_ctrl:1
	s_and_saveexec_b64 s[0:1], s[40:41]
	v_add_f32_e32 v95, v95, v101
	ds_write_b32 v184, v95 offset:5312
	s_or_b64 exec, exec, s[0:1]
	v_mul_f32_e32 v95, v9, v9
	v_fmac_f32_e32 v95, v13, v13
	v_fmac_f32_e32 v95, v5, v5
	v_fmac_f32_e32 v95, v1, v1
	s_nop 1
	v_add_f32_dpp v95, v95, v95 quad_perm:[1,0,3,2] row_mask:0xf bank_mask:0xf bound_ctrl:1
	s_nop 1
	v_add_f32_dpp v95, v95, v95 quad_perm:[2,3,0,1] row_mask:0xf bank_mask:0xf bound_ctrl:1
	s_nop 1
	v_add_f32_dpp v95, v95, v95 row_half_mirror row_mask:0xf bank_mask:0xf bound_ctrl:1
	s_nop 1
	v_mov_b32_dpp v101, v95 row_mirror row_mask:0xf bank_mask:0xf bound_ctrl:1
	s_and_saveexec_b64 s[0:1], s[40:41]
	v_add_f32_e32 v95, v95, v101
	ds_write_b32 v184, v95 offset:5316
	s_or_b64 exec, exec, s[0:1]
	v_mul_f32_e32 v95, v10, v10
	v_fmac_f32_e32 v95, v14, v14
	v_fmac_f32_e32 v95, v6, v6
	v_fmac_f32_e32 v95, v2, v2
	s_nop 1
	v_add_f32_dpp v95, v95, v95 quad_perm:[1,0,3,2] row_mask:0xf bank_mask:0xf bound_ctrl:1
	s_nop 1
	v_add_f32_dpp v95, v95, v95 quad_perm:[2,3,0,1] row_mask:0xf bank_mask:0xf bound_ctrl:1
	s_nop 1
	v_add_f32_dpp v95, v95, v95 row_half_mirror row_mask:0xf bank_mask:0xf bound_ctrl:1
	s_nop 1
	v_mov_b32_dpp v101, v95 row_mirror row_mask:0xf bank_mask:0xf bound_ctrl:1
	s_and_saveexec_b64 s[0:1], s[40:41]
	v_add_f32_e32 v95, v95, v101
	ds_write_b32 v184, v95 offset:5320
	s_or_b64 exec, exec, s[0:1]
	v_mul_f32_e32 v95, v11, v11
	v_fmac_f32_e32 v95, v15, v15
	v_fmac_f32_e32 v95, v7, v7
	v_fmac_f32_e32 v95, v3, v3
	s_nop 1
	v_add_f32_dpp v95, v95, v95 quad_perm:[1,0,3,2] row_mask:0xf bank_mask:0xf bound_ctrl:1
	s_nop 1
	v_add_f32_dpp v95, v95, v95 quad_perm:[2,3,0,1] row_mask:0xf bank_mask:0xf bound_ctrl:1
	s_nop 1
	v_add_f32_dpp v95, v95, v95 row_half_mirror row_mask:0xf bank_mask:0xf bound_ctrl:1
	s_nop 1
	v_mov_b32_dpp v101, v95 row_mirror row_mask:0xf bank_mask:0xf bound_ctrl:1
	s_and_saveexec_b64 s[0:1], s[40:41]
	v_add_f32_e32 v95, v95, v101
	ds_write_b32 v184, v95 offset:5324
	s_or_b64 exec, exec, s[0:1]
	s_lshl_b32 s0, s44, 2
	v_readlane_b32 s1, v254, 59
	s_add_u32 s0, s1, s0
	v_readlane_b32 s1, v254, 53
	s_addc_u32 s1, s1, 0
	s_waitcnt lgkmcnt(0)
	v_lshl_add_u64 v[104:105], v[82:83], 2, s[0:1]
	s_barrier
	global_load_dword v186, v[104:105], off
	global_load_dword v101, v[104:105], off offset:64
	global_load_dword v95, v[104:105], off offset:128
	v_lshl_add_u64 v[104:105], v[84:85], 2, s[0:1]
	global_load_dword v187, v[104:105], off
	s_lshl_b32 s2, s44, 1
	v_add_u32_e32 v102, s7, v81
	s_add_u32 s44, s66, s2
	v_readlane_b32 s2, v254, 57
	v_ashrrev_i32_e32 v103, 31, v102
	s_addc_u32 s45, s2, 0
	v_lshlrev_b64 v[102:103], 11, v[102:103]
	v_lshl_add_u64 v[106:107], s[44:45], 0, v[102:103]
	v_lshlrev_b64 v[102:103], 1, v[82:83]
	v_lshlrev_b64 v[104:105], 1, v[84:85]
	v_lshl_add_u64 v[110:111], v[106:107], 0, v[102:103]
	v_lshl_add_u64 v[192:193], v[106:107], 0, v[104:105]
	ds_read_b128 v[106:109], v78 offset:5120
	ds_read_b128 v[156:159], v78 offset:5376
	ds_read_b128 v[166:169], v78 offset:5632
	ds_read_b128 v[188:191], v78 offset:5888
	s_mov_b32 s0, 0x358637bd
	s_mov_b32 s8, 0x3b800000
	s_waitcnt lgkmcnt(2)
	v_pk_add_f32 v[106:107], v[106:107], v[156:157]
	s_mov_b32 s2, 0x800000
	s_waitcnt lgkmcnt(1)
	v_pk_add_f32 v[106:107], v[106:107], v[166:167]
	s_waitcnt lgkmcnt(0)
	v_pk_add_f32 v[156:157], v[106:107], v[188:189]
	v_mov_b64_e32 v[106:107], s[0:1]
	v_pk_fma_f32 v[156:157], v[156:157], s[8:9], v[106:107] op_sel_hi:[1,0,0]
	s_nop 0
	v_mul_f32_e32 v166, 0x4b800000, v156
	v_cmp_gt_f32_e64 s[0:1], s2, v156
	v_cmp_gt_f32_e32 vcc, s2, v157
	s_nop 0
	v_cndmask_b32_e64 v156, v156, v166, s[0:1]
	v_rsq_f32_e32 v156, v156
	s_nop 0
	v_mul_f32_e32 v166, 0x45800000, v156
	v_cndmask_b32_e64 v156, v156, v166, s[0:1]
	v_mul_f32_e32 v60, v60, v156
	v_mul_f32_e32 v56, v56, v156
	v_mul_f32_e32 v52, v52, v156
	v_mul_f32_e32 v48, v48, v156
	s_waitcnt vmcnt(2)
	v_mul_f32_e32 v56, v101, v56
	v_mul_f32_e32 v60, v186, v60
	v_bfe_u32 v166, v60, 16, 1
	v_add3_u32 v60, v60, v166, s33
	global_store_short_d16_hi v[110:111], v60, off
	v_bfe_u32 v60, v56, 16, 1
	v_add3_u32 v56, v56, v60, s33
	s_waitcnt vmcnt(2)
	v_mul_f32_e32 v52, v95, v52
	global_store_short_d16_hi v[110:111], v56, off offset:32
	v_bfe_u32 v56, v52, 16, 1
	v_add3_u32 v52, v52, v56, s33
	s_waitcnt vmcnt(2)
	v_mul_f32_e32 v48, v187, v48
	global_store_short_d16_hi v[110:111], v52, off offset:64
	v_bfe_u32 v52, v48, 16, 1
	v_add3_u32 v48, v48, v52, s33
	global_store_short_d16_hi v[192:193], v48, off
	v_mul_f32_e32 v48, 0x4b800000, v157
	v_cndmask_b32_e32 v48, v157, v48, vcc
	v_rsq_f32_e32 v48, v48
	v_add_u32_e32 v110, s7, v125
	v_ashrrev_i32_e32 v111, 31, v110
	v_lshlrev_b64 v[110:111], 11, v[110:111]
	v_mul_f32_e32 v52, 0x45800000, v48
	v_cndmask_b32_e32 v48, v48, v52, vcc
	v_mul_f32_e32 v52, v61, v48
	v_mul_f32_e32 v52, v186, v52
	v_lshl_add_u64 v[110:111], s[44:45], 0, v[110:111]
	v_bfe_u32 v56, v52, 16, 1
	v_add3_u32 v52, v52, v56, s33
	v_lshl_add_u64 v[60:61], v[110:111], 0, v[102:103]
	global_store_short_d16_hi v[60:61], v52, off
	v_mul_f32_e32 v52, v57, v48
	v_mul_f32_e32 v52, v101, v52
	v_bfe_u32 v56, v52, 16, 1
	v_add3_u32 v52, v52, v56, s33
	global_store_short_d16_hi v[60:61], v52, off offset:32
	v_mul_f32_e32 v52, v53, v48
	v_pk_add_f32 v[56:57], v[108:109], v[158:159]
	v_mul_f32_e32 v52, v95, v52
	v_pk_add_f32 v[56:57], v[56:57], v[168:169]
	v_bfe_u32 v53, v52, 16, 1
	v_pk_add_f32 v[56:57], v[56:57], v[190:191]
	v_add3_u32 v52, v52, v53, s33
	v_pk_fma_f32 v[56:57], v[56:57], s[8:9], v[106:107] op_sel_hi:[1,0,0]
	global_store_short_d16_hi v[60:61], v52, off offset:64
	v_mul_f32_e32 v60, 0x4b800000, v56
	v_cmp_gt_f32_e64 s[0:1], s2, v56
	v_mul_f32_e32 v48, v49, v48
	v_mul_f32_e32 v48, v187, v48
	v_cndmask_b32_e64 v56, v56, v60, s[0:1]
	v_rsq_f32_e32 v56, v56
	v_bfe_u32 v49, v48, 16, 1
	v_add3_u32 v52, v48, v49, s33
	v_lshl_add_u64 v[48:49], v[110:111], 0, v[104:105]
	v_mul_f32_e32 v60, 0x45800000, v56
	global_store_short_d16_hi v[48:49], v52, off
	v_add_u32_e32 v48, s7, v126
	v_cndmask_b32_e64 v56, v56, v60, s[0:1]
	v_ashrrev_i32_e32 v49, 31, v48
	v_mul_f32_e32 v60, v62, v56
	v_lshlrev_b64 v[48:49], 11, v[48:49]
	v_mul_f32_e32 v60, v186, v60
	v_lshl_add_u64 v[48:49], s[44:45], 0, v[48:49]
	v_bfe_u32 v61, v60, 16, 1
	v_mul_f32_e32 v58, v58, v56
	v_lshl_add_u64 v[52:53], v[48:49], 0, v[102:103]
	v_add3_u32 v60, v60, v61, s33
	v_mul_f32_e32 v58, v101, v58
	global_store_short_d16_hi v[52:53], v60, off
	v_bfe_u32 v60, v58, 16, 1
	v_mul_f32_e32 v54, v54, v56
	v_add3_u32 v58, v58, v60, s33
	v_mul_f32_e32 v54, v95, v54
	global_store_short_d16_hi v[52:53], v58, off offset:32
	v_bfe_u32 v58, v54, 16, 1
	v_mul_f32_e32 v50, v50, v56
	v_add3_u32 v54, v54, v58, s33
	v_mul_f32_e32 v50, v187, v50
	global_store_short_d16_hi v[52:53], v54, off offset:64
	v_bfe_u32 v52, v50, 16, 1
	v_lshl_add_u64 v[48:49], v[48:49], 0, v[104:105]
	v_add3_u32 v50, v50, v52, s33
	v_cmp_gt_f32_e32 vcc, s2, v57
	global_store_short_d16_hi v[48:49], v50, off
	v_mul_f32_e32 v48, 0x4b800000, v57
	v_cndmask_b32_e32 v48, v57, v48, vcc
	v_rsq_f32_e32 v48, v48
	s_nop 0
	v_mul_f32_e32 v49, 0x45800000, v48
	v_cndmask_b32_e32 v50, v48, v49, vcc
	v_add_u32_e32 v48, s7, v127
	v_ashrrev_i32_e32 v49, 31, v48
	v_mul_f32_e32 v52, v63, v50
	v_lshlrev_b64 v[48:49], 11, v[48:49]
	v_mul_f32_e32 v52, v186, v52
	v_lshl_add_u64 v[48:49], s[44:45], 0, v[48:49]
	v_bfe_u32 v53, v52, 16, 1
	v_add3_u32 v54, v52, v53, s33
	v_lshl_add_u64 v[52:53], v[48:49], 0, v[102:103]
	global_store_short_d16_hi v[52:53], v54, off
	v_mul_f32_e32 v54, v59, v50
	v_mul_f32_e32 v54, v101, v54
	v_bfe_u32 v56, v54, 16, 1
	v_add3_u32 v54, v54, v56, s33
	global_store_short_d16_hi v[52:53], v54, off offset:32
	v_mul_f32_e32 v54, v55, v50
	v_mul_f32_e32 v50, v51, v50
	v_mul_f32_e32 v54, v95, v54
	v_mul_f32_e32 v50, v187, v50
	v_bfe_u32 v55, v54, 16, 1
	v_bfe_u32 v51, v50, 16, 1
	v_add3_u32 v54, v54, v55, s33
	v_add3_u32 v50, v50, v51, s33
	v_lshl_add_u64 v[48:49], v[48:49], 0, v[104:105]
	global_store_short_d16_hi v[52:53], v54, off offset:64
	global_store_short_d16_hi v[48:49], v50, off
	v_add_u32_e32 v48, s7, v128
	v_ashrrev_i32_e32 v49, 31, v48
	v_lshlrev_b64 v[48:49], 11, v[48:49]
	v_lshl_add_u64 v[48:49], s[44:45], 0, v[48:49]
	v_lshl_add_u64 v[110:111], v[48:49], 0, v[102:103]
	v_lshl_add_u64 v[108:109], v[48:49], 0, v[104:105]
	ds_read_b128 v[48:51], v78 offset:5184
	ds_read_b128 v[52:55], v78 offset:5440
	ds_read_b128 v[56:59], v78 offset:5696
	ds_read_b128 v[60:63], v78 offset:5952
	s_waitcnt lgkmcnt(2)
	v_pk_add_f32 v[48:49], v[48:49], v[52:53]
	s_waitcnt lgkmcnt(1)
	v_pk_add_f32 v[48:49], v[48:49], v[56:57]
	s_waitcnt lgkmcnt(0)
	v_pk_add_f32 v[48:49], v[48:49], v[60:61]
	s_nop 0
	v_pk_fma_f32 v[48:49], v[48:49], s[8:9], v[106:107] op_sel_hi:[1,0,0]
	s_nop 0
	v_mul_f32_e32 v52, 0x4b800000, v48
	v_cmp_gt_f32_e64 s[0:1], s2, v48
	v_cmp_gt_f32_e32 vcc, s2, v49
	s_nop 0
	v_cndmask_b32_e64 v48, v48, v52, s[0:1]
	v_rsq_f32_e32 v48, v48
	s_nop 0
	v_mul_f32_e32 v52, 0x45800000, v48
	v_cndmask_b32_e64 v48, v48, v52, s[0:1]
	v_mul_f32_e32 v44, v44, v48
	v_mul_f32_e32 v44, v186, v44
	v_bfe_u32 v52, v44, 16, 1
	v_mul_f32_e32 v40, v40, v48
	v_add3_u32 v44, v44, v52, s33
	v_mul_f32_e32 v40, v101, v40
	global_store_short_d16_hi v[110:111], v44, off
	v_bfe_u32 v44, v40, 16, 1
	v_mul_f32_e32 v36, v36, v48
	v_add3_u32 v40, v40, v44, s33
	v_mul_f32_e32 v36, v95, v36
	global_store_short_d16_hi v[110:111], v40, off offset:32
	v_bfe_u32 v40, v36, 16, 1
	v_mul_f32_e32 v32, v32, v48
	v_add3_u32 v36, v36, v40, s33
	v_mul_f32_e32 v32, v187, v32
	global_store_short_d16_hi v[110:111], v36, off offset:64
	v_bfe_u32 v36, v32, 16, 1
	v_add3_u32 v32, v32, v36, s33
	global_store_short_d16_hi v[108:109], v32, off
	v_mul_f32_e32 v32, 0x4b800000, v49
	v_cndmask_b32_e32 v32, v49, v32, vcc
	v_rsq_f32_e32 v32, v32
	v_add_u32_e32 v48, s7, v129
	v_ashrrev_i32_e32 v49, 31, v48
	v_lshlrev_b64 v[48:49], 11, v[48:49]
	v_mul_f32_e32 v36, 0x45800000, v32
	v_cndmask_b32_e32 v32, v32, v36, vcc
	v_mul_f32_e32 v36, v45, v32
	v_mul_f32_e32 v36, v186, v36
	v_lshl_add_u64 v[48:49], s[44:45], 0, v[48:49]
	v_bfe_u32 v40, v36, 16, 1
	v_add3_u32 v36, v36, v40, s33
	v_lshl_add_u64 v[44:45], v[48:49], 0, v[102:103]
	global_store_short_d16_hi v[44:45], v36, off
	v_mul_f32_e32 v36, v41, v32
	v_mul_f32_e32 v36, v101, v36
	v_bfe_u32 v40, v36, 16, 1
	v_add3_u32 v36, v36, v40, s33
	global_store_short_d16_hi v[44:45], v36, off offset:32
	v_mul_f32_e32 v36, v37, v32
	v_pk_add_f32 v[40:41], v[50:51], v[54:55]
	v_mul_f32_e32 v36, v95, v36
	v_pk_add_f32 v[40:41], v[40:41], v[58:59]
	v_bfe_u32 v37, v36, 16, 1
	v_pk_add_f32 v[40:41], v[40:41], v[62:63]
	v_add3_u32 v36, v36, v37, s33
	v_pk_fma_f32 v[40:41], v[40:41], s[8:9], v[106:107] op_sel_hi:[1,0,0]
	global_store_short_d16_hi v[44:45], v36, off offset:64
	v_mul_f32_e32 v44, 0x4b800000, v40
	v_cmp_gt_f32_e64 s[0:1], s2, v40
	v_mul_f32_e32 v32, v33, v32
	v_mul_f32_e32 v32, v187, v32
	v_cndmask_b32_e64 v40, v40, v44, s[0:1]
	v_rsq_f32_e32 v40, v40
	v_bfe_u32 v33, v32, 16, 1
	v_add3_u32 v36, v32, v33, s33
	v_lshl_add_u64 v[32:33], v[48:49], 0, v[104:105]
	v_mul_f32_e32 v44, 0x45800000, v40
	global_store_short_d16_hi v[32:33], v36, off
	v_add_u32_e32 v32, s7, v130
	v_cndmask_b32_e64 v40, v40, v44, s[0:1]
	v_ashrrev_i32_e32 v33, 31, v32
	v_mul_f32_e32 v44, v46, v40
	v_lshlrev_b64 v[32:33], 11, v[32:33]
	v_mul_f32_e32 v44, v186, v44
	v_lshl_add_u64 v[32:33], s[44:45], 0, v[32:33]
	v_bfe_u32 v45, v44, 16, 1
	v_mul_f32_e32 v42, v42, v40
	v_lshl_add_u64 v[36:37], v[32:33], 0, v[102:103]
	v_add3_u32 v44, v44, v45, s33
	v_mul_f32_e32 v42, v101, v42
	global_store_short_d16_hi v[36:37], v44, off
	v_bfe_u32 v44, v42, 16, 1
	v_mul_f32_e32 v38, v38, v40
	v_add3_u32 v42, v42, v44, s33
	v_mul_f32_e32 v38, v95, v38
	global_store_short_d16_hi v[36:37], v42, off offset:32
	v_bfe_u32 v42, v38, 16, 1
	v_mul_f32_e32 v34, v34, v40
	v_add3_u32 v38, v38, v42, s33
	v_mul_f32_e32 v34, v187, v34
	global_store_short_d16_hi v[36:37], v38, off offset:64
	v_bfe_u32 v36, v34, 16, 1
	v_lshl_add_u64 v[32:33], v[32:33], 0, v[104:105]
	v_add3_u32 v34, v34, v36, s33
	v_cmp_gt_f32_e32 vcc, s2, v41
	global_store_short_d16_hi v[32:33], v34, off
	v_mul_f32_e32 v32, 0x4b800000, v41
	v_cndmask_b32_e32 v32, v41, v32, vcc
	v_rsq_f32_e32 v32, v32
	s_nop 0
	v_mul_f32_e32 v33, 0x45800000, v32
	v_cndmask_b32_e32 v34, v32, v33, vcc
	v_add_u32_e32 v32, s7, v131
	v_ashrrev_i32_e32 v33, 31, v32
	v_mul_f32_e32 v36, v47, v34
	v_lshlrev_b64 v[32:33], 11, v[32:33]
	v_mul_f32_e32 v36, v186, v36
	v_lshl_add_u64 v[32:33], s[44:45], 0, v[32:33]
	v_bfe_u32 v37, v36, 16, 1
	v_add3_u32 v38, v36, v37, s33
	v_lshl_add_u64 v[36:37], v[32:33], 0, v[102:103]
	global_store_short_d16_hi v[36:37], v38, off
	v_mul_f32_e32 v38, v43, v34
	v_mul_f32_e32 v38, v101, v38
	v_bfe_u32 v40, v38, 16, 1
	v_add3_u32 v38, v38, v40, s33
	global_store_short_d16_hi v[36:37], v38, off offset:32
	v_mul_f32_e32 v38, v39, v34
	v_mul_f32_e32 v34, v35, v34
	v_mul_f32_e32 v38, v95, v38
	v_mul_f32_e32 v34, v187, v34
	v_bfe_u32 v39, v38, 16, 1
	v_bfe_u32 v35, v34, 16, 1
	v_add3_u32 v38, v38, v39, s33
	v_add3_u32 v34, v34, v35, s33
	v_lshl_add_u64 v[32:33], v[32:33], 0, v[104:105]
	v_cmp_gt_u32_e32 vcc, s92, v132
	global_store_short_d16_hi v[36:37], v38, off offset:64
	global_store_short_d16_hi v[32:33], v34, off
	s_and_saveexec_b64 s[0:1], vcc
	s_cbranch_execnz .LBB0_321
	s_or_b64 exec, exec, s[0:1]
	v_cmp_gt_u32_e32 vcc, s92, v133
	s_and_saveexec_b64 s[0:1], vcc
	s_cbranch_execnz .LBB0_322

.LBB0_582:
	s_add_i32 s7, s5, 1
	s_bitcmp1_b32 s5, 0
	s_cselect_b32 s5, 0x9000, 0
	s_add_i32 s5, s5, 0
	v_add_u32_e32 v118, s5, v93
	v_add_u32_e32 v119, v118, v94
	v_add_u32_e32 v156, v118, v95
	ds_read_b128 v[102:105], v119
	ds_read_b128 v[106:109], v119 offset:2048
	ds_read_b128 v[110:113], v119 offset:4096
	ds_read_b128 v[114:117], v119 offset:6144
	ds_read_b128 v[118:121], v119 offset:8192
	ds_read_b128 v[122:125], v156 offset:20480
	ds_read_b128 v[126:129], v156 offset:22528
	ds_read_b128 v[130:133], v156 offset:24576
	ds_read_b128 v[156:159], v156 offset:26624
	v_add_u32_e32 v206, s5, v96
	v_add_u32_e32 v207, v206, v94
	v_add_u32_e32 v208, v206, v95
	ds_read_b128 v[210:213], v207
	ds_read_b128 v[214:217], v207 offset:2048
	ds_read_b128 v[218:221], v207 offset:4096
	ds_read_b128 v[222:225], v207 offset:6144
	ds_read_b128 v[226:229], v207 offset:8192
	ds_read_b128 v[230:233], v208 offset:20480
	ds_read_b128 v[234:237], v208 offset:22528
	ds_read_b128 v[238:241], v208 offset:24576
	ds_read_b128 v[242:245], v208 offset:26624
	s_setprio 1
	s_waitcnt lgkmcnt(9)
	v_mfma_f32_16x16x32_bf16 v[76:79], v[122:125], v[102:105], v[76:79]
	v_mfma_f32_16x16x32_bf16 v[72:75], v[126:129], v[102:105], v[72:75]
	v_mfma_f32_16x16x32_bf16 v[68:71], v[130:133], v[102:105], v[68:71]
	v_mfma_f32_16x16x32_bf16 v[64:67], v[156:159], v[102:105], v[64:67]
	v_mfma_f32_16x16x32_bf16 v[60:63], v[122:125], v[106:109], v[60:63]
	v_mfma_f32_16x16x32_bf16 v[56:59], v[126:129], v[106:109], v[56:59]
	v_mfma_f32_16x16x32_bf16 v[52:55], v[130:133], v[106:109], v[52:55]
	v_mfma_f32_16x16x32_bf16 v[48:51], v[156:159], v[106:109], v[48:51]
	v_mfma_f32_16x16x32_bf16 v[44:47], v[122:125], v[110:113], v[44:47]
	v_mfma_f32_16x16x32_bf16 v[40:43], v[126:129], v[110:113], v[40:43]
	v_mfma_f32_16x16x32_bf16 v[36:39], v[130:133], v[110:113], v[36:39]
	v_mfma_f32_16x16x32_bf16 v[32:35], v[156:159], v[110:113], v[32:35]
	v_mfma_f32_16x16x32_bf16 v[28:31], v[122:125], v[114:117], v[28:31]
	v_mfma_f32_16x16x32_bf16 v[24:27], v[126:129], v[114:117], v[24:27]
	v_mfma_f32_16x16x32_bf16 v[20:23], v[130:133], v[114:117], v[20:23]
	v_mfma_f32_16x16x32_bf16 v[16:19], v[156:159], v[114:117], v[16:19]
	v_mfma_f32_16x16x32_bf16 v[12:15], v[122:125], v[118:121], v[12:15]
	v_mfma_f32_16x16x32_bf16 v[8:11], v[126:129], v[118:121], v[8:11]
	v_mfma_f32_16x16x32_bf16 v[4:7], v[130:133], v[118:121], v[4:7]
	v_mfma_f32_16x16x32_bf16 v[0:3], v[156:159], v[118:121], v[0:3]
	s_waitcnt lgkmcnt(0)
	s_setprio 0
	s_barrier
	s_add_u32 s8, s8, 0x80
	s_addc_u32 s9, s9, 0
	s_mov_b32 s13, s5
	v_add_u32_e32 v190, s13, v92
	v_lshl_add_u64 v[186:187], v[88:89], 0, s[8:9]
	s_mov_b64 s[14:15], 0x1c9b1080
	v_readfirstlane_b32 s13, v190
	v_add_u32_e32 v191, 0x1000, v190
	v_lshl_add_u64 v[188:189], v[186:187], 0, s[14:15]
	s_mov_b32 m0, s13
	s_mov_b64 s[14:15], 0x1c9c1080
	v_readfirstlane_b32 s13, v191
	v_add_u32_e32 v191, 0x2000, v190
	global_load_lds_dwordx4 v[188:189], off
	v_lshl_add_u64 v[188:189], v[186:187], 0, s[14:15]
	s_mov_b32 m0, s13
	s_mov_b64 s[14:15], 0x1c9d1080
	v_readfirstlane_b32 s13, v191
	v_add_u32_e32 v191, 0x3000, v190
	global_load_lds_dwordx4 v[188:189], off
	v_lshl_add_u64 v[188:189], v[186:187], 0, s[14:15]
	s_mov_b32 m0, s13
	s_mov_b64 s[14:15], 0x1c9e1080
	v_readfirstlane_b32 s13, v191
	global_load_lds_dwordx4 v[188:189], off
	v_lshl_add_u64 v[188:189], v[186:187], 0, s[14:15]
	s_mov_b32 m0, s13
	s_mov_b64 s[14:15], 0x1c9f1080
	global_load_lds_dwordx4 v[188:189], off
	v_add_u32_e32 v188, 0x4000, v190
	v_lshl_add_u64 v[186:187], v[186:187], 0, s[14:15]
	v_readfirstlane_b32 s13, v188
	s_mov_b32 m0, s13
	v_add_u32_e32 v191, 0x5000, v190
	global_load_lds_dwordx4 v[186:187], off
	v_lshl_add_u64 v[186:187], v[90:91], 0, s[8:9]
	s_mov_b64 s[14:15], 0x14b31080
	v_readfirstlane_b32 s13, v191
	v_add_u32_e32 v191, 0x6000, v190
	v_lshl_add_u64 v[188:189], v[186:187], 0, s[14:15]
	s_mov_b32 m0, s13
	s_mov_b64 s[14:15], 0x14b41080
	v_readfirstlane_b32 s13, v191
	v_add_u32_e32 v191, 0x7000, v190
	global_load_lds_dwordx4 v[188:189], off
	v_lshl_add_u64 v[188:189], v[186:187], 0, s[14:15]
	s_mov_b32 m0, s13
	s_mov_b64 s[14:15], 0x14b51080
	v_readfirstlane_b32 s13, v191
	global_load_lds_dwordx4 v[188:189], off
	v_lshl_add_u64 v[188:189], v[186:187], 0, s[14:15]
	s_mov_b32 m0, s13
	s_mov_b64 s[14:15], 0x14b61080
	global_load_lds_dwordx4 v[188:189], off
	v_add_u32_e32 v188, 0x8000, v190
	v_lshl_add_u64 v[186:187], v[186:187], 0, s[14:15]
	v_readfirstlane_b32 s13, v188
	s_mov_b32 m0, s13
	s_nop 0
	global_load_lds_dwordx4 v[186:187], off
	s_setprio 1
	v_mfma_f32_16x16x32_bf16 v[76:79], v[230:233], v[210:213], v[76:79]
	v_mfma_f32_16x16x32_bf16 v[72:75], v[234:237], v[210:213], v[72:75]
	v_mfma_f32_16x16x32_bf16 v[68:71], v[238:241], v[210:213], v[68:71]
	v_mfma_f32_16x16x32_bf16 v[64:67], v[242:245], v[210:213], v[64:67]
	v_mfma_f32_16x16x32_bf16 v[60:63], v[230:233], v[214:217], v[60:63]
	v_mfma_f32_16x16x32_bf16 v[56:59], v[234:237], v[214:217], v[56:59]
	v_mfma_f32_16x16x32_bf16 v[52:55], v[238:241], v[214:217], v[52:55]
	v_mfma_f32_16x16x32_bf16 v[48:51], v[242:245], v[214:217], v[48:51]
	v_mfma_f32_16x16x32_bf16 v[44:47], v[230:233], v[218:221], v[44:47]
	v_mfma_f32_16x16x32_bf16 v[40:43], v[234:237], v[218:221], v[40:43]
	v_mfma_f32_16x16x32_bf16 v[36:39], v[238:241], v[218:221], v[36:39]
	v_mfma_f32_16x16x32_bf16 v[32:35], v[242:245], v[218:221], v[32:35]
	v_mfma_f32_16x16x32_bf16 v[28:31], v[230:233], v[222:225], v[28:31]
	v_mfma_f32_16x16x32_bf16 v[24:27], v[234:237], v[222:225], v[24:27]
	v_mfma_f32_16x16x32_bf16 v[20:23], v[238:241], v[222:225], v[20:23]
	v_mfma_f32_16x16x32_bf16 v[16:19], v[242:245], v[222:225], v[16:19]
	v_mfma_f32_16x16x32_bf16 v[12:15], v[230:233], v[226:229], v[12:15]
	v_mfma_f32_16x16x32_bf16 v[8:11], v[234:237], v[226:229], v[8:11]
	v_mfma_f32_16x16x32_bf16 v[4:7], v[238:241], v[226:229], v[4:7]
	v_mfma_f32_16x16x32_bf16 v[0:3], v[242:245], v[226:229], v[0:3]
	s_setprio 0
	s_cmpk_lg_i32 s8, 0x700
	s_mov_b32 s5, s7
	s_waitcnt vmcnt(9)
	s_barrier
	s_cbranch_scc1 .LBB0_582
	s_add_i32 s7, s5, 1
	s_bitcmp1_b32 s5, 0
	s_cselect_b32 s5, 0x9000, 0
	s_add_i32 s5, s5, 0
	v_add_u32_e32 v118, s5, v93
	v_add_u32_e32 v119, v118, v94
	v_add_u32_e32 v156, v118, v95
	ds_read_b128 v[102:105], v119
	ds_read_b128 v[106:109], v119 offset:2048
	ds_read_b128 v[110:113], v119 offset:4096
	ds_read_b128 v[114:117], v119 offset:6144
	ds_read_b128 v[118:121], v119 offset:8192
	ds_read_b128 v[122:125], v156 offset:20480
	ds_read_b128 v[126:129], v156 offset:22528
	ds_read_b128 v[130:133], v156 offset:24576
	ds_read_b128 v[156:159], v156 offset:26624
	v_add_u32_e32 v206, s5, v96
	v_add_u32_e32 v207, v206, v94
	v_add_u32_e32 v208, v206, v95
	ds_read_b128 v[210:213], v207
	ds_read_b128 v[214:217], v207 offset:2048
	ds_read_b128 v[218:221], v207 offset:4096
	ds_read_b128 v[222:225], v207 offset:6144
	ds_read_b128 v[226:229], v207 offset:8192
	ds_read_b128 v[230:233], v208 offset:20480
	ds_read_b128 v[234:237], v208 offset:22528
	ds_read_b128 v[238:241], v208 offset:24576
	ds_read_b128 v[242:245], v208 offset:26624
	s_setprio 1
	s_waitcnt lgkmcnt(9)
	v_mfma_f32_16x16x32_bf16 v[76:79], v[122:125], v[102:105], v[76:79]
	v_mfma_f32_16x16x32_bf16 v[72:75], v[126:129], v[102:105], v[72:75]
	v_mfma_f32_16x16x32_bf16 v[68:71], v[130:133], v[102:105], v[68:71]
	v_mfma_f32_16x16x32_bf16 v[64:67], v[156:159], v[102:105], v[64:67]
	v_mfma_f32_16x16x32_bf16 v[60:63], v[122:125], v[106:109], v[60:63]
	v_mfma_f32_16x16x32_bf16 v[56:59], v[126:129], v[106:109], v[56:59]
	v_mfma_f32_16x16x32_bf16 v[52:55], v[130:133], v[106:109], v[52:55]
	v_mfma_f32_16x16x32_bf16 v[48:51], v[156:159], v[106:109], v[48:51]
	v_mfma_f32_16x16x32_bf16 v[44:47], v[122:125], v[110:113], v[44:47]
	v_mfma_f32_16x16x32_bf16 v[40:43], v[126:129], v[110:113], v[40:43]
	v_mfma_f32_16x16x32_bf16 v[36:39], v[130:133], v[110:113], v[36:39]
	v_mfma_f32_16x16x32_bf16 v[32:35], v[156:159], v[110:113], v[32:35]
	v_mfma_f32_16x16x32_bf16 v[28:31], v[122:125], v[114:117], v[28:31]
	v_mfma_f32_16x16x32_bf16 v[24:27], v[126:129], v[114:117], v[24:27]
	v_mfma_f32_16x16x32_bf16 v[20:23], v[130:133], v[114:117], v[20:23]
	v_mfma_f32_16x16x32_bf16 v[16:19], v[156:159], v[114:117], v[16:19]
	v_mfma_f32_16x16x32_bf16 v[12:15], v[122:125], v[118:121], v[12:15]
	v_mfma_f32_16x16x32_bf16 v[8:11], v[126:129], v[118:121], v[8:11]
	v_mfma_f32_16x16x32_bf16 v[4:7], v[130:133], v[118:121], v[4:7]
	v_mfma_f32_16x16x32_bf16 v[0:3], v[156:159], v[118:121], v[0:3]
	s_waitcnt lgkmcnt(0)
	v_mfma_f32_16x16x32_bf16 v[76:79], v[230:233], v[210:213], v[76:79]
	v_mfma_f32_16x16x32_bf16 v[72:75], v[234:237], v[210:213], v[72:75]
	v_mfma_f32_16x16x32_bf16 v[68:71], v[238:241], v[210:213], v[68:71]
	v_mfma_f32_16x16x32_bf16 v[64:67], v[242:245], v[210:213], v[64:67]
	v_mfma_f32_16x16x32_bf16 v[60:63], v[230:233], v[214:217], v[60:63]
	v_mfma_f32_16x16x32_bf16 v[56:59], v[234:237], v[214:217], v[56:59]
	v_mfma_f32_16x16x32_bf16 v[52:55], v[238:241], v[214:217], v[52:55]
	v_mfma_f32_16x16x32_bf16 v[48:51], v[242:245], v[214:217], v[48:51]
	v_mfma_f32_16x16x32_bf16 v[44:47], v[230:233], v[218:221], v[44:47]
	v_mfma_f32_16x16x32_bf16 v[40:43], v[234:237], v[218:221], v[40:43]
	v_mfma_f32_16x16x32_bf16 v[36:39], v[238:241], v[218:221], v[36:39]
	v_mfma_f32_16x16x32_bf16 v[32:35], v[242:245], v[218:221], v[32:35]
	v_mfma_f32_16x16x32_bf16 v[28:31], v[230:233], v[222:225], v[28:31]
	v_mfma_f32_16x16x32_bf16 v[24:27], v[234:237], v[222:225], v[24:27]
	v_mfma_f32_16x16x32_bf16 v[20:23], v[238:241], v[222:225], v[20:23]
	v_mfma_f32_16x16x32_bf16 v[16:19], v[242:245], v[222:225], v[16:19]
	v_mfma_f32_16x16x32_bf16 v[12:15], v[230:233], v[226:229], v[12:15]
	v_mfma_f32_16x16x32_bf16 v[8:11], v[234:237], v[226:229], v[8:11]
	v_mfma_f32_16x16x32_bf16 v[4:7], v[238:241], v[226:229], v[4:7]
	v_mfma_f32_16x16x32_bf16 v[0:3], v[242:245], v[226:229], v[0:3]
	s_setprio 0
	s_add_u32 s8, s8, 0x80
	s_addc_u32 s9, s9, 0
	s_mov_b32 s5, s7
	s_waitcnt vmcnt(0)
	s_barrier
	v_add_u32_e32 v232, v97, v176
	v_lshrrev_b32_e32 v233, 2, v232
	v_ashrrev_i32_e32 v234, 7, v232
	v_and_b32_e32 v236, 64, v232
	v_and_b32_e32 v233, 12, v233
	v_and_or_b32 v248, v232, 15, s6
	s_movk_i32 s5, 0x50
	s_lshl_b32 s4, s4, 7
	v_mad_u32_u24 v248, v234, s5, v248
	v_or3_b32 v236, v236, v233, s4
	v_ashrrev_i32_e32 v249, 31, v248
	v_lshlrev_b64 v[248:249], 12, v[248:249]
	v_lshl_add_u64 v[248:249], s[0:1], 0, v[248:249]
	v_ashrrev_i32_e32 v237, 31, v236
	v_lshl_add_u64 v[248:249], v[236:237], 2, v[248:249]
	s_mov_b64 s[4:5], 0x10000
	v_lshl_add_u64 v[246:247], v[248:249], 0, s[4:5]
	s_mov_b64 s[4:5], 0x20000
	v_lshl_add_u64 v[244:245], v[248:249], 0, s[4:5]
	s_mov_b64 s[4:5], 0x30000
	v_lshl_add_u64 v[242:243], v[248:249], 0, s[4:5]
	s_mov_b64 s[4:5], 0x40000
	v_lshl_add_u64 v[240:241], v[248:249], 0, s[4:5]
	global_load_dwordx4 v[178:181], v[248:249], off
	global_load_dwordx4 v[182:185], v[248:249], off offset:64
	global_load_dwordx4 v[186:189], v[248:249], off offset:128
	global_load_dwordx4 v[190:193], v[248:249], off offset:192
	global_load_dwordx4 v[194:197], v[246:247], off
	global_load_dwordx4 v[198:201], v[246:247], off offset:64
	global_load_dwordx4 v[206:209], v[246:247], off offset:128
	global_load_dwordx4 v[210:213], v[246:247], off offset:192
	global_load_dwordx4 v[214:217], v[244:245], off
	global_load_dwordx4 v[218:221], v[244:245], off offset:64
	global_load_dwordx4 v[222:225], v[244:245], off offset:128
	global_load_dwordx4 v[226:229], v[244:245], off offset:192
	v_add_u32_e32 v110, v100, v95
	v_add_u32_e32 v130, v100, v94
	ds_read_b128 v[88:91], v110 offset:63488
	ds_read_b128 v[102:105], v110 offset:61440
	ds_read_b128 v[106:109], v110 offset:59392
	ds_read_b128 v[110:113], v110 offset:57344
	ds_read_b128 v[114:117], v130 offset:45056
	ds_read_b128 v[118:121], v130 offset:43008
	ds_read_b128 v[122:125], v130 offset:40960
	ds_read_b128 v[126:129], v130 offset:38912
	ds_read_b128 v[130:133], v130 offset:36864
	s_setprio 1
	s_waitcnt lgkmcnt(0)
	v_mfma_f32_16x16x32_bf16 v[76:79], v[110:113], v[130:133], v[76:79]
	v_mfma_f32_16x16x32_bf16 v[72:75], v[106:109], v[130:133], v[72:75]
	v_mfma_f32_16x16x32_bf16 v[68:71], v[102:105], v[130:133], v[68:71]
	v_mfma_f32_16x16x32_bf16 v[64:67], v[88:91], v[130:133], v[64:67]
	v_mfma_f32_16x16x32_bf16 v[60:63], v[110:113], v[126:129], v[60:63]
	v_mfma_f32_16x16x32_bf16 v[56:59], v[106:109], v[126:129], v[56:59]
	v_mfma_f32_16x16x32_bf16 v[52:55], v[102:105], v[126:129], v[52:55]
	v_mfma_f32_16x16x32_bf16 v[48:51], v[88:91], v[126:129], v[48:51]
	v_mfma_f32_16x16x32_bf16 v[44:47], v[110:113], v[122:125], v[44:47]
	v_mfma_f32_16x16x32_bf16 v[40:43], v[106:109], v[122:125], v[40:43]
	v_mfma_f32_16x16x32_bf16 v[36:39], v[102:105], v[122:125], v[36:39]
	v_mfma_f32_16x16x32_bf16 v[32:35], v[88:91], v[122:125], v[32:35]
	v_mfma_f32_16x16x32_bf16 v[28:31], v[110:113], v[118:121], v[28:31]
	v_mfma_f32_16x16x32_bf16 v[24:27], v[106:109], v[118:121], v[24:27]
	v_mfma_f32_16x16x32_bf16 v[20:23], v[102:105], v[118:121], v[20:23]
	v_mfma_f32_16x16x32_bf16 v[16:19], v[88:91], v[118:121], v[16:19]
	v_mfma_f32_16x16x32_bf16 v[12:15], v[110:113], v[114:117], v[12:15]
	v_mfma_f32_16x16x32_bf16 v[8:11], v[106:109], v[114:117], v[8:11]
	v_mfma_f32_16x16x32_bf16 v[4:7], v[102:105], v[114:117], v[4:7]
	v_mfma_f32_16x16x32_bf16 v[0:3], v[88:91], v[114:117], v[0:3]
	s_setprio 0
	v_add_u32_e32 v114, v101, v94
	v_add_u32_e32 v130, v101, v95
	ds_read_b128 v[88:91], v114 offset:36864
	ds_read_b128 v[102:105], v114 offset:38912
	ds_read_b128 v[106:109], v114 offset:40960
	ds_read_b128 v[110:113], v114 offset:43008
	ds_read_b128 v[114:117], v114 offset:45056
	ds_read_b128 v[118:121], v130 offset:57344
	ds_read_b128 v[122:125], v130 offset:59392
	ds_read_b128 v[126:129], v130 offset:61440
	ds_read_b128 v[130:133], v130 offset:63488
	s_setprio 1
	s_waitcnt lgkmcnt(3)
	v_mfma_f32_16x16x32_bf16 v[76:79], v[118:121], v[88:91], v[76:79]
	s_waitcnt lgkmcnt(2)
	v_mfma_f32_16x16x32_bf16 v[72:75], v[122:125], v[88:91], v[72:75]
	s_waitcnt lgkmcnt(1)
	v_mfma_f32_16x16x32_bf16 v[68:71], v[126:129], v[88:91], v[68:71]
	s_waitcnt lgkmcnt(0)
	v_mfma_f32_16x16x32_bf16 v[64:67], v[130:133], v[88:91], v[64:67]
	v_mfma_f32_16x16x32_bf16 v[60:63], v[118:121], v[102:105], v[60:63]
	v_mfma_f32_16x16x32_bf16 v[56:59], v[122:125], v[102:105], v[56:59]
	v_mfma_f32_16x16x32_bf16 v[88:91], v[126:129], v[102:105], v[52:55]
	v_mfma_f32_16x16x32_bf16 v[48:51], v[130:133], v[102:105], v[48:51]
	v_mfma_f32_16x16x32_bf16 v[44:47], v[118:121], v[106:109], v[44:47]
	v_mfma_f32_16x16x32_bf16 v[40:43], v[122:125], v[106:109], v[40:43]
	v_mfma_f32_16x16x32_bf16 v[36:39], v[126:129], v[106:109], v[36:39]
	v_mfma_f32_16x16x32_bf16 v[32:35], v[130:133], v[106:109], v[32:35]
	v_mfma_f32_16x16x32_bf16 v[28:31], v[118:121], v[110:113], v[28:31]
	v_mfma_f32_16x16x32_bf16 v[24:27], v[122:125], v[110:113], v[24:27]
	v_mfma_f32_16x16x32_bf16 v[20:23], v[126:129], v[110:113], v[20:23]
	v_mfma_f32_16x16x32_bf16 v[16:19], v[130:133], v[110:113], v[16:19]
	v_mfma_f32_16x16x32_bf16 v[12:15], v[118:121], v[114:117], v[12:15]
	v_mfma_f32_16x16x32_bf16 v[8:11], v[122:125], v[114:117], v[8:11]
	v_mfma_f32_16x16x32_bf16 v[4:7], v[126:129], v[114:117], v[4:7]
	v_mfma_f32_16x16x32_bf16 v[0:3], v[130:133], v[114:117], v[0:3]
	s_setprio 0
	global_load_dwordx4 v[102:105], v[242:243], off
	global_load_dwordx4 v[106:109], v[242:243], off offset:64
	global_load_dwordx4 v[110:113], v[242:243], off offset:128
	global_load_dwordx4 v[114:117], v[242:243], off offset:192
	global_load_dwordx4 v[118:121], v[240:241], off
	global_load_dwordx4 v[122:125], v[240:241], off offset:64
	global_load_dwordx4 v[126:129], v[240:241], off offset:128
	global_load_dwordx4 v[130:133], v[240:241], off offset:192
	s_barrier
	s_mov_b32 s8, 0
	s_waitcnt vmcnt(19)
	v_pk_add_f32 v[76:77], v[76:77], v[178:179]
	v_pk_add_f32 v[78:79], v[78:79], v[180:181]
	global_store_dwordx4 v[248:249], v[76:79], off
	s_waitcnt vmcnt(19)
	v_pk_add_f32 v[72:73], v[72:73], v[182:183]
	v_pk_add_f32 v[74:75], v[74:75], v[184:185]
	global_store_dwordx4 v[248:249], v[72:75], off offset:64
	s_waitcnt vmcnt(19)
	v_pk_add_f32 v[68:69], v[68:69], v[186:187]
	v_pk_add_f32 v[70:71], v[70:71], v[188:189]
	global_store_dwordx4 v[248:249], v[68:71], off offset:128
	s_waitcnt vmcnt(19)
	v_pk_add_f32 v[64:65], v[64:65], v[190:191]
	v_pk_add_f32 v[66:67], v[66:67], v[192:193]
	global_store_dwordx4 v[248:249], v[64:67], off offset:192
	s_waitcnt vmcnt(19)
	v_pk_add_f32 v[60:61], v[60:61], v[194:195]
	v_pk_add_f32 v[62:63], v[62:63], v[196:197]
	global_store_dwordx4 v[246:247], v[60:63], off
	s_waitcnt vmcnt(19)
	v_pk_add_f32 v[56:57], v[56:57], v[198:199]
	v_pk_add_f32 v[58:59], v[58:59], v[200:201]
	global_store_dwordx4 v[246:247], v[56:59], off offset:64
	s_waitcnt vmcnt(19)
	v_pk_add_f32 v[88:89], v[88:89], v[206:207]
	v_pk_add_f32 v[90:91], v[90:91], v[208:209]
	global_store_dwordx4 v[246:247], v[88:91], off offset:128
	s_waitcnt vmcnt(19)
	v_pk_add_f32 v[48:49], v[48:49], v[210:211]
	v_pk_add_f32 v[50:51], v[50:51], v[212:213]
	global_store_dwordx4 v[246:247], v[48:51], off offset:192
	s_waitcnt vmcnt(19)
	v_pk_add_f32 v[44:45], v[44:45], v[214:215]
	v_pk_add_f32 v[46:47], v[46:47], v[216:217]
	global_store_dwordx4 v[244:245], v[44:47], off
	s_waitcnt vmcnt(19)
	v_pk_add_f32 v[40:41], v[40:41], v[218:219]
	v_pk_add_f32 v[42:43], v[42:43], v[220:221]
	global_store_dwordx4 v[244:245], v[40:43], off offset:64
	s_waitcnt vmcnt(19)
	v_pk_add_f32 v[36:37], v[36:37], v[222:223]
	v_pk_add_f32 v[38:39], v[38:39], v[224:225]
	global_store_dwordx4 v[244:245], v[36:39], off offset:128
	s_waitcnt vmcnt(19)
	v_pk_add_f32 v[32:33], v[32:33], v[226:227]
	v_pk_add_f32 v[34:35], v[34:35], v[228:229]
	global_store_dwordx4 v[244:245], v[32:35], off offset:192
	s_waitcnt vmcnt(19)
	v_pk_add_f32 v[28:29], v[28:29], v[102:103]
	v_pk_add_f32 v[30:31], v[30:31], v[104:105]
	global_store_dwordx4 v[242:243], v[28:31], off
	s_waitcnt vmcnt(19)
	v_pk_add_f32 v[24:25], v[24:25], v[106:107]
	v_pk_add_f32 v[26:27], v[26:27], v[108:109]
	global_store_dwordx4 v[242:243], v[24:27], off offset:64
	s_waitcnt vmcnt(19)
	v_pk_add_f32 v[20:21], v[20:21], v[110:111]
	v_pk_add_f32 v[22:23], v[22:23], v[112:113]
	global_store_dwordx4 v[242:243], v[20:23], off offset:128
	s_waitcnt vmcnt(19)
	v_pk_add_f32 v[16:17], v[16:17], v[114:115]
	v_pk_add_f32 v[18:19], v[18:19], v[116:117]
	global_store_dwordx4 v[242:243], v[16:19], off offset:192
	s_waitcnt vmcnt(19)
	v_pk_add_f32 v[12:13], v[12:13], v[118:119]
	v_pk_add_f32 v[14:15], v[14:15], v[120:121]
	global_store_dwordx4 v[240:241], v[12:15], off
	s_waitcnt vmcnt(19)
	v_pk_add_f32 v[8:9], v[8:9], v[122:123]
	v_pk_add_f32 v[10:11], v[10:11], v[124:125]
	global_store_dwordx4 v[240:241], v[8:11], off offset:64
	s_waitcnt vmcnt(19)
	v_pk_add_f32 v[4:5], v[4:5], v[126:127]
	v_pk_add_f32 v[6:7], v[6:7], v[128:129]
	global_store_dwordx4 v[240:241], v[4:7], off offset:128
	s_waitcnt vmcnt(19)
	v_pk_add_f32 v[0:1], v[0:1], v[130:131]
	v_pk_add_f32 v[2:3], v[2:3], v[132:133]
	global_store_dwordx4 v[240:241], v[0:3], off offset:192
